# v45_bcum_log_deadcode_trim
# speedup vs baseline: 1.0384x; 1.0034x over previous
; #define LAS __attribute__((address_space(3)))
; __device__ __forceinline__ void gla_bcum(KArgs a, int tid, int t0, int h, LAS float* segtot, LAS float* glrs, float (&bc)[32], float& tot) {
;     const int d = tid & 127, seg = __builtin_amdgcn_readfirstlane(tid >> 7), col = h * 128 + d;
;     const float* glr = (const float*)(a->ws + WS_GLR);
;     float w2r[16];
; #pragma unroll
;     for (int j = 0; j < 16; ++j) w2r[j] = a->gate_w2[j * 512 + col];
;     const float bias = a->gate_b[col];
;     *(LAS f32x4*)(glrs + tid * 4) = *(const f32x4*)(glr + (size_t)t0 * 16 + tid * 4);
;     __syncthreads();
;     float run = 0.f;
; #pragma unroll
;     for (int r = 0; r < 32; ++r) { const LAS f32x4* gp = (const LAS f32x4*)(glrs + (seg * 32 + r) * 16);
;         float z = bias;
; #pragma unroll
;         for (int q = 0; q < 4; ++q) { const f32x4 g = gp[q]; z += g[0] * w2r[4 * q] + g[1] * w2r[4 * q + 1] + g[2] * w2r[4 * q + 2] + g[3] * w2r[4 * q + 3]; }
;         const float la = (fminf(z, 0.f) - __logf(1.0f + __expf(-fabsf(z)))) * (1.0f / 16.0f);
;         run += la; bc[r] = run; }
.LBB0_341:
	s_bfe_u32 s5, s10, 0x20005
	v_lshlrev_b32_e32 v2, 2, v8
	v_lshl_or_b32 v2, s5, 9, v2
	v_lshl_add_u64 v[20:21], s[12:13], 0, v[2:3]
	s_and_b32 s0, s2, 0xfffff000
	s_and_b32 s1, s3, 0xf80
	v_add_co_u32_e64 v28, s[6:7], s29, v20
	s_or_b32 s20, s0, s1
	s_nop 0
	v_addc_co_u32_e64 v29, s[6:7], 0, v21, s[6:7]
	s_movk_i32 s0, 0x2000
	v_add_co_u32_e64 v14, s[6:7], s0, v20
	s_movk_i32 s0, 0x3000
	s_nop 0
	v_addc_co_u32_e64 v15, s[6:7], 0, v21, s[6:7]
	s_ashr_i32 s21, s20, 31
	v_add_co_u32_e64 v42, s[6:7], s0, v20
	s_lshl_b64 s[0:1], s[20:21], 6
	s_nop 0
	v_addc_co_u32_e64 v43, s[6:7], 0, v21, s[6:7]
	v_lshl_add_u64 v[16:17], v[10:11], 0, s[0:1]
	s_movk_i32 s0, 0x4000
	s_barrier
	global_load_dwordx4 v[44:47], v[16:17], off
	v_add_co_u32_e64 v16, s[6:7], s0, v20
	s_movk_i32 s0, 0x5000
	s_nop 0
	v_addc_co_u32_e64 v17, s[6:7], 0, v21, s[6:7]
	v_add_co_u32_e64 v48, s[6:7], s0, v20
	s_movk_i32 s0, 0x6000
	s_nop 0
	v_addc_co_u32_e64 v49, s[6:7], 0, v21, s[6:7]
	v_add_co_u32_e64 v50, s[6:7], s0, v20
	s_movk_i32 s0, 0x7000
	s_nop 0
	v_addc_co_u32_e64 v51, s[6:7], 0, v21, s[6:7]
	global_load_dword v24, v2, s[12:13]
	global_load_dword v26, v2, s[12:13] offset:2048
	global_load_dword v22, v[14:15], off offset:-4096
	global_load_dword v25, v[14:15], off
	global_load_dword v27, v[14:15], off offset:2048
	global_load_dword v23, v[16:17], off offset:-4096
	s_nop 0
	global_load_dword v14, v[16:17], off
	global_load_dword v18, v[16:17], off offset:2048
	s_nop 0
	global_load_dword v16, v[50:51], off offset:-4096
	global_load_dword v15, v[50:51], off
	global_load_dword v19, v[50:51], off offset:2048
	v_add_co_u32_e64 v20, s[6:7], s0, v20
	v_readfirstlane_b32 s1, v32
	s_nop 0
	v_addc_co_u32_e64 v21, s[6:7], 0, v21, s[6:7]
	global_load_dword v28, v[28:29], off offset:2048
	s_nop 0
	global_load_dword v29, v[42:43], off offset:2048
	global_load_dword v17, v[20:21], off
	s_nop 0
	global_load_dword v21, v[20:21], off offset:2048
	s_nop 0
	global_load_dword v20, v[48:49], off offset:2048
	s_nop 0
	global_load_dword v2, v2, s[14:15]
	s_ashr_i32 s0, s1, 7
	s_lshl_b32 s6, s0, 11
	s_add_i32 s6, s6, 0
	v_mov_b32_e32 v42, s6
	s_and_b32 s1, s1, 0x3fffff80
	s_cmp_gt_i32 s0, 0
	s_waitcnt vmcnt(17)
	ds_write_b128 v33, v[44:47] offset:34816
	s_waitcnt lgkmcnt(0)
	s_barrier
	ds_read_b128 v[44:47], v42 offset:34816
	ds_read_b128 v[48:51], v42 offset:34832
	ds_read_b128 v[52:55], v42 offset:34848
	ds_read_b128 v[56:59], v42 offset:34864
	ds_read_b128 v[60:63], v42 offset:34880
	ds_read_b128 v[64:67], v42 offset:34896
	s_waitcnt lgkmcnt(4)
	v_mov_b32_e32 v69, v48
	v_mov_b32_e32 v48, v45
	v_mov_b32_e32 v68, v44
	v_mov_b32_e32 v44, v46
	v_mov_b32_e32 v45, v50
	v_mov_b32_e32 v50, v47
	s_waitcnt lgkmcnt(2)
	v_mov_b32_e32 v47, v56
	v_mov_b32_e32 v56, v53
	v_mov_b32_e32 v46, v52
	s_waitcnt vmcnt(12)
	v_pk_mul_f32 v[48:49], v[26:27], v[48:49]
	v_mov_b32_e32 v52, v54
	v_pk_fma_f32 v[48:49], v[24:25], v[68:69], v[48:49]
	v_mov_b32_e32 v53, v58
	v_mov_b32_e32 v58, v55
	s_waitcnt vmcnt(6)
	v_pk_mul_f32 v[54:55], v[18:19], v[56:57]
	v_pk_fma_f32 v[44:45], v[22:23], v[44:45], v[48:49]
	v_pk_fma_f32 v[46:47], v[14:15], v[46:47], v[54:55]
	s_waitcnt vmcnt(4)
	v_pk_fma_f32 v[44:45], v[28:29], v[50:51], v[44:45]
	s_waitcnt vmcnt(3)
	v_pk_fma_f32 v[46:47], v[16:17], v[52:53], v[46:47]
	s_waitcnt vmcnt(0)
	v_add_f32_e32 v13, v2, v44
	v_pk_fma_f32 v[46:47], v[20:21], v[58:59], v[46:47]
	v_add_f32_e32 v13, v13, v45
	v_add_f32_e32 v13, v13, v46
	v_add_f32_e32 v13, v13, v47
	v_mul_f32_e64 v43, |v13|, s4
	v_exp_f32_e32 v43, v43
	s_waitcnt lgkmcnt(0)
	v_mov_b32_e32 v45, v64
	v_mov_b32_e32 v64, v61
	v_mov_b32_e32 v44, v60
	v_add_f32_e32 v43, 1.0, v43
	v_min_f32_e32 v13, 0, v13
	s_nop 0
	v_log_f32_e32 v43, v43
	v_pk_mul_f32 v[46:47], v[26:27], v[64:65]
	v_pk_fma_f32 v[44:45], v[24:25], v[44:45], v[46:47]
	v_mul_f32_e32 v46, 0x3f317217, v43
	v_fma_f32 v54, v43, s36, -v46
	v_mov_b32_e32 v46, v62
	v_mov_b32_e32 v47, v66
	v_pk_fma_f32 v[52:53], v[22:23], v[46:47], v[44:45]
	ds_read_b128 v[44:47], v42 offset:34912
	ds_read_b128 v[48:51], v42 offset:34928
	v_mov_b32_e32 v66, v63
	v_pk_fma_f32 v[52:53], v[28:29], v[66:67], v[52:53]
	v_fmac_f32_e32 v54, 0x3377d1cf, v43
	v_add_f32_e32 v52, v2, v52
	v_add_f32_e32 v55, v52, v53
	s_waitcnt lgkmcnt(0)
	v_mov_b32_e32 v53, v48
	v_mov_b32_e32 v48, v45
	v_mov_b32_e32 v52, v44
	v_pk_mul_f32 v[44:45], v[18:19], v[48:49]
	v_mov_b32_e32 v48, v46
	v_pk_fma_f32 v[44:45], v[14:15], v[52:53], v[44:45]
	v_mov_b32_e32 v49, v50
	v_pk_fma_f32 v[44:45], v[16:17], v[48:49], v[44:45]
	v_mov_b32_e32 v50, v47
	v_pk_fma_f32 v[44:45], v[20:21], v[50:51], v[44:45]
	v_fmac_f32_e32 v54, 0x3f317217, v43
	v_add_f32_e32 v44, v55, v44
	v_add_f32_e32 v45, v44, v45
	v_mul_f32_e64 v44, |v45|, s4
	v_exp_f32_e32 v44, v44
	v_mov_b32_e32 v43, v54
	v_add_f32_e32 v44, 1.0, v44
	v_sub_f32_e32 v13, v13, v43
	s_mov_b32 s8, 0x3d800000
	ds_read_b128 v[46:49], v42 offset:34944
	ds_read_b128 v[50:53], v42 offset:34960
	v_log_f32_e32 v58, v44
	v_fma_f32 v44, v13, s8, 0
	v_min_f32_e32 v13, 0, v45
	s_waitcnt lgkmcnt(1)
	v_mov_b32_e32 v54, v46
	s_waitcnt lgkmcnt(0)
	v_mov_b32_e32 v55, v50
	v_mov_b32_e32 v50, v47
	v_pk_mul_f32 v[46:47], v[26:27], v[50:51]
	v_mov_b32_e32 v50, v48
	v_pk_fma_f32 v[46:47], v[24:25], v[54:55], v[46:47]
	v_mov_b32_e32 v51, v52
	v_pk_fma_f32 v[50:51], v[22:23], v[50:51], v[46:47]
	v_mov_b32_e32 v52, v49
	ds_read_b128 v[46:49], v42 offset:34976
	ds_read_b128 v[54:57], v42 offset:34992
	v_pk_fma_f32 v[50:51], v[28:29], v[52:53], v[50:51]
	v_mul_f32_e32 v43, 0x3f317217, v58
	v_add_f32_e32 v45, v2, v50
	v_add_f32_e32 v45, v45, v51
	s_waitcnt lgkmcnt(0)
; #define LAS __attribute__((address_space(3)))
; __device__ __forceinline__ void gla_bcum(KArgs a, int tid, int t0, int h, LAS float* segtot, LAS float* glrs, float (&bc)[32], float& tot) {
;     ...
;     for (int r = 0; r < 32; ++r) { const LAS f32x4* gp = (const LAS f32x4*)(glrs + (seg * 32 + r) * 16);
;         float z = bias;
; #pragma unroll
;         for (int q = 0; q < 4; ++q) { const f32x4 g = gp[q]; z += g[0] * w2r[4 * q] + g[1] * w2r[4 * q + 1] + g[2] * w2r[4 * q + 2] + g[3] * w2r[4 * q + 3]; }
;         const float la = (fminf(z, 0.f) - __logf(1.0f + __expf(-fabsf(z)))) * (1.0f / 16.0f);
;         run += la; bc[r] = run; }
	v_mov_b32_e32 v51, v54
	v_mov_b32_e32 v54, v47
	v_mov_b32_e32 v50, v46
	v_pk_mul_f32 v[46:47], v[18:19], v[54:55]
	v_fma_f32 v43, v58, s36, -v43
	v_pk_fma_f32 v[46:47], v[14:15], v[50:51], v[46:47]
	v_mov_b32_e32 v50, v48
	v_mov_b32_e32 v51, v56
	v_pk_fma_f32 v[46:47], v[16:17], v[50:51], v[46:47]
	v_mov_b32_e32 v56, v49
	v_pk_fma_f32 v[46:47], v[20:21], v[56:57], v[46:47]
	ds_read_b128 v[48:51], v42 offset:35008
	ds_read_b128 v[52:55], v42 offset:35024
	v_add_f32_e32 v45, v45, v46
	v_add_f32_e32 v45, v45, v47
	v_mul_f32_e64 v46, |v45|, s4
	v_exp_f32_e32 v46, v46
	s_waitcnt lgkmcnt(0)
	v_mov_b32_e32 v57, v52
	v_mov_b32_e32 v52, v49
	v_fmac_f32_e32 v43, 0x3377d1cf, v58
	v_mov_b32_e32 v56, v48
	v_pk_mul_f32 v[48:49], v[26:27], v[52:53]
	v_fmac_f32_e32 v43, 0x3f317217, v58
	v_pk_fma_f32 v[48:49], v[24:25], v[56:57], v[48:49]
	v_mov_b32_e32 v52, v50
	v_mov_b32_e32 v53, v54
	v_mov_b32_e32 v43, v43
	v_add_f32_e32 v46, 1.0, v46
	v_pk_fma_f32 v[52:53], v[22:23], v[52:53], v[48:49]
	v_mov_b32_e32 v54, v51
	ds_read_b128 v[48:51], v42 offset:35040
	ds_read_b128 v[56:59], v42 offset:35056
	v_sub_f32_e32 v13, v13, v43
	v_pk_fma_f32 v[52:53], v[28:29], v[54:55], v[52:53]
	v_log_f32_e32 v47, v46
	v_fmamk_f32 v46, v13, 0x3d800000, v44
	v_min_f32_e32 v13, 0, v45
	v_add_f32_e32 v45, v2, v52
	v_add_f32_e32 v45, v45, v53
	s_waitcnt lgkmcnt(0)
	v_mov_b32_e32 v53, v56
	v_mov_b32_e32 v56, v49
	v_mov_b32_e32 v52, v48
	v_pk_mul_f32 v[48:49], v[18:19], v[56:57]
	v_mul_f32_e32 v43, 0x3f317217, v47
	v_pk_fma_f32 v[48:49], v[14:15], v[52:53], v[48:49]
	v_mov_b32_e32 v52, v50
	v_mov_b32_e32 v53, v58
	v_pk_fma_f32 v[48:49], v[16:17], v[52:53], v[48:49]
	v_mov_b32_e32 v58, v51
	v_pk_fma_f32 v[48:49], v[20:21], v[58:59], v[48:49]
	v_fma_f32 v43, v47, s36, -v43
	v_add_f32_e32 v45, v45, v48
	v_add_f32_e32 v45, v45, v49
	v_mul_f32_e64 v48, |v45|, s4
	v_exp_f32_e32 v48, v48
	v_fmac_f32_e32 v43, 0x3377d1cf, v47
	v_fmac_f32_e32 v43, 0x3f317217, v47
	s_nop 1
	v_mov_b32_e32 v43, v43
	v_add_f32_e32 v47, 1.0, v48
	v_sub_f32_e32 v13, v13, v43
	v_min_f32_e32 v43, 0, v45
	ds_read_b128 v[48:51], v42 offset:35072
	ds_read_b128 v[52:55], v42 offset:35088
	v_log_f32_e32 v47, v47
	v_fmamk_f32 v13, v13, 0x3d800000, v46
	s_waitcnt lgkmcnt(1)
	v_mov_b32_e32 v56, v48
	s_waitcnt lgkmcnt(0)
	v_mov_b32_e32 v57, v52
	v_mov_b32_e32 v52, v49
	v_pk_mul_f32 v[48:49], v[26:27], v[52:53]
	v_mov_b32_e32 v52, v50
	v_pk_fma_f32 v[48:49], v[24:25], v[56:57], v[48:49]
	v_mov_b32_e32 v53, v54
	v_pk_fma_f32 v[52:53], v[22:23], v[52:53], v[48:49]
	v_mov_b32_e32 v54, v51
	ds_read_b128 v[48:51], v42 offset:35104
	ds_read_b128 v[56:59], v42 offset:35120
	v_pk_fma_f32 v[52:53], v[28:29], v[54:55], v[52:53]
	v_mul_f32_e32 v45, 0x3f317217, v47
	v_add_f32_e32 v52, v2, v52
	v_add_f32_e32 v54, v52, v53
	s_waitcnt lgkmcnt(0)
	v_mov_b32_e32 v53, v56
	v_mov_b32_e32 v56, v49
	v_mov_b32_e32 v52, v48
	v_pk_mul_f32 v[48:49], v[18:19], v[56:57]
	v_fma_f32 v45, v47, s36, -v45
	v_pk_fma_f32 v[48:49], v[14:15], v[52:53], v[48:49]
	v_mov_b32_e32 v52, v50
	v_mov_b32_e32 v53, v58
	v_pk_fma_f32 v[48:49], v[16:17], v[52:53], v[48:49]
	v_mov_b32_e32 v58, v51
	v_pk_fma_f32 v[48:49], v[20:21], v[58:59], v[48:49]
	v_fmac_f32_e32 v45, 0x3377d1cf, v47
	v_add_f32_e32 v48, v54, v48
	v_add_f32_e32 v48, v48, v49
	v_mul_f32_e64 v49, |v48|, s4
	v_exp_f32_e32 v49, v49
	v_fmac_f32_e32 v45, 0x3f317217, v47
	s_nop 1
	v_mov_b32_e32 v45, v45
	v_add_f32_e32 v47, 1.0, v49
	v_sub_f32_e32 v43, v43, v45
	v_min_f32_e32 v45, 0, v48
	ds_read_b128 v[48:51], v42 offset:35136
	ds_read_b128 v[52:55], v42 offset:35152
	v_log_f32_e32 v47, v47
	v_fmamk_f32 v43, v43, 0x3d800000, v13
	v_mul_f32_e32 v56, 0x3f317217, v47
	s_waitcnt lgkmcnt(0)
	v_mov_b32_e32 v57, v52
	v_mov_b32_e32 v52, v49
	v_fma_f32 v60, v47, s36, -v56
	v_mov_b32_e32 v56, v48
	v_pk_mul_f32 v[48:49], v[26:27], v[52:53]
	v_mov_b32_e32 v52, v50
	v_pk_fma_f32 v[48:49], v[24:25], v[56:57], v[48:49]
	v_mov_b32_e32 v53, v54
	v_pk_fma_f32 v[52:53], v[22:23], v[52:53], v[48:49]
	v_mov_b32_e32 v54, v51
	ds_read_b128 v[48:51], v42 offset:35168
	ds_read_b128 v[56:59], v42 offset:35184
	v_pk_fma_f32 v[52:53], v[28:29], v[54:55], v[52:53]
	v_fmac_f32_e32 v60, 0x3377d1cf, v47
	v_add_f32_e32 v52, v2, v52
	v_add_f32_e32 v54, v52, v53
	s_waitcnt lgkmcnt(0)
	v_mov_b32_e32 v53, v56
	v_mov_b32_e32 v56, v49
	v_mov_b32_e32 v52, v48
	v_pk_mul_f32 v[48:49], v[18:19], v[56:57]
	v_fmac_f32_e32 v60, 0x3f317217, v47
	v_pk_fma_f32 v[48:49], v[14:15], v[52:53], v[48:49]
	v_mov_b32_e32 v52, v50
	v_mov_b32_e32 v53, v58
	v_pk_fma_f32 v[48:49], v[16:17], v[52:53], v[48:49]
	v_mov_b32_e32 v58, v51
	v_pk_fma_f32 v[48:49], v[20:21], v[58:59], v[48:49]
	v_add_f32_e32 v48, v54, v48
	v_add_f32_e32 v48, v48, v49
	v_mul_f32_e64 v49, |v48|, s4
	v_exp_f32_e32 v49, v49
	v_mov_b32_e32 v47, v60
	v_add_f32_e32 v49, 1.0, v49
	v_sub_f32_e32 v45, v45, v47
	v_min_f32_e32 v47, 0, v48
	v_log_f32_e32 v60, v49
	ds_read_b128 v[48:51], v42 offset:35200
	ds_read_b128 v[52:55], v42 offset:35216
	v_fmamk_f32 v45, v45, 0x3d800000, v43
	v_mul_f32_e32 v56, 0x3f317217, v60
	v_fma_f32 v61, v60, s36, -v56
	s_waitcnt lgkmcnt(0)
	v_mov_b32_e32 v57, v52
	v_mov_b32_e32 v52, v49
	v_mov_b32_e32 v56, v48
	v_pk_mul_f32 v[48:49], v[26:27], v[52:53]
	v_mov_b32_e32 v52, v50
	v_pk_fma_f32 v[48:49], v[24:25], v[56:57], v[48:49]
	v_mov_b32_e32 v53, v54
	v_pk_fma_f32 v[52:53], v[22:23], v[52:53], v[48:49]
	v_mov_b32_e32 v54, v51
	ds_read_b128 v[48:51], v42 offset:35232
	ds_read_b128 v[56:59], v42 offset:35248
	v_pk_fma_f32 v[52:53], v[28:29], v[54:55], v[52:53]
	v_fmac_f32_e32 v61, 0x3377d1cf, v60
	v_add_f32_e32 v52, v2, v52
	v_add_f32_e32 v54, v52, v53
	s_waitcnt lgkmcnt(0)
; #define LAS __attribute__((address_space(3)))
; __device__ __forceinline__ void gla_bcum(KArgs a, int tid, int t0, int h, LAS float* segtot, LAS float* glrs, float (&bc)[32], float& tot) {
;     ...
;     for (int r = 0; r < 32; ++r) { const LAS f32x4* gp = (const LAS f32x4*)(glrs + (seg * 32 + r) * 16);
;         float z = bias;
; #pragma unroll
;         for (int q = 0; q < 4; ++q) { const f32x4 g = gp[q]; z += g[0] * w2r[4 * q] + g[1] * w2r[4 * q + 1] + g[2] * w2r[4 * q + 2] + g[3] * w2r[4 * q + 3]; }
;         const float la = (fminf(z, 0.f) - __logf(1.0f + __expf(-fabsf(z)))) * (1.0f / 16.0f);
;         run += la; bc[r] = run; }
	v_mov_b32_e32 v53, v56
	v_mov_b32_e32 v56, v49
	v_mov_b32_e32 v52, v48
	v_pk_mul_f32 v[48:49], v[18:19], v[56:57]
	v_fmac_f32_e32 v61, 0x3f317217, v60
	v_pk_fma_f32 v[48:49], v[14:15], v[52:53], v[48:49]
	v_mov_b32_e32 v52, v50
	v_mov_b32_e32 v53, v58
	v_pk_fma_f32 v[48:49], v[16:17], v[52:53], v[48:49]
	v_mov_b32_e32 v58, v51
	v_pk_fma_f32 v[48:49], v[20:21], v[58:59], v[48:49]
	v_add_f32_e32 v48, v54, v48
	v_add_f32_e32 v48, v48, v49
	v_mul_f32_e64 v49, |v48|, s4
	v_exp_f32_e32 v49, v49
	v_mov_b32_e32 v50, v61
	v_add_f32_e32 v49, 1.0, v49
	v_sub_f32_e32 v47, v47, v50
	v_min_f32_e32 v61, 0, v48
	v_log_f32_e32 v60, v49
	ds_read_b128 v[48:51], v42 offset:35264
	ds_read_b128 v[52:55], v42 offset:35280
	v_fmamk_f32 v47, v47, 0x3d800000, v45
	v_mul_f32_e32 v56, 0x3f317217, v60
	v_fma_f32 v62, v60, s36, -v56
	s_waitcnt lgkmcnt(0)
	v_mov_b32_e32 v57, v52
	v_mov_b32_e32 v52, v49
	v_mov_b32_e32 v56, v48
	v_pk_mul_f32 v[48:49], v[26:27], v[52:53]
	v_mov_b32_e32 v52, v50
	v_pk_fma_f32 v[48:49], v[24:25], v[56:57], v[48:49]
	v_mov_b32_e32 v53, v54
	v_pk_fma_f32 v[52:53], v[22:23], v[52:53], v[48:49]
	v_mov_b32_e32 v54, v51
	ds_read_b128 v[48:51], v42 offset:35296
	ds_read_b128 v[56:59], v42 offset:35312
	v_pk_fma_f32 v[52:53], v[28:29], v[54:55], v[52:53]
	v_fmac_f32_e32 v62, 0x3377d1cf, v60
	v_add_f32_e32 v52, v2, v52
	v_add_f32_e32 v54, v52, v53
	s_waitcnt lgkmcnt(0)
	v_mov_b32_e32 v53, v56
	v_mov_b32_e32 v56, v49
	v_mov_b32_e32 v52, v48
	v_pk_mul_f32 v[48:49], v[18:19], v[56:57]
	v_fmac_f32_e32 v62, 0x3f317217, v60
	v_pk_fma_f32 v[48:49], v[14:15], v[52:53], v[48:49]
	v_mov_b32_e32 v52, v50
	v_mov_b32_e32 v53, v58
	v_pk_fma_f32 v[48:49], v[16:17], v[52:53], v[48:49]
	v_mov_b32_e32 v58, v51
	v_pk_fma_f32 v[48:49], v[20:21], v[58:59], v[48:49]
	v_add_f32_e32 v48, v54, v48
	v_add_f32_e32 v49, v48, v49
	v_mul_f32_e64 v48, |v49|, s4
	v_exp_f32_e32 v48, v48
	v_mov_b32_e32 v50, v62
	v_add_f32_e32 v48, 1.0, v48
	v_min_f32_e32 v49, 0, v49
	s_nop 0
	v_log_f32_e32 v62, v48
	v_sub_f32_e32 v48, v61, v50
	ds_read_b128 v[50:53], v42 offset:35328
	ds_read_b128 v[54:57], v42 offset:35344
	v_fmamk_f32 v48, v48, 0x3d800000, v47
	v_mul_f32_e32 v58, 0x3f317217, v62
	v_fma_f32 v63, v62, s36, -v58
	s_waitcnt lgkmcnt(1)
	v_mov_b32_e32 v58, v50
	s_waitcnt lgkmcnt(0)
	v_mov_b32_e32 v59, v54
	v_mov_b32_e32 v54, v51
	v_pk_mul_f32 v[50:51], v[26:27], v[54:55]
	v_mov_b32_e32 v54, v52
	v_pk_fma_f32 v[50:51], v[24:25], v[58:59], v[50:51]
	v_mov_b32_e32 v55, v56
	v_pk_fma_f32 v[54:55], v[22:23], v[54:55], v[50:51]
	v_mov_b32_e32 v56, v53
	ds_read_b128 v[50:53], v42 offset:35360
	ds_read_b128 v[58:61], v42 offset:35376
	v_pk_fma_f32 v[54:55], v[28:29], v[56:57], v[54:55]
	v_fmac_f32_e32 v63, 0x3377d1cf, v62
	v_add_f32_e32 v54, v2, v54
	v_add_f32_e32 v56, v54, v55
	s_waitcnt lgkmcnt(0)
	v_mov_b32_e32 v55, v58
	v_mov_b32_e32 v58, v51
	v_mov_b32_e32 v54, v50
	v_pk_mul_f32 v[50:51], v[18:19], v[58:59]
	v_fmac_f32_e32 v63, 0x3f317217, v62
	v_pk_fma_f32 v[50:51], v[14:15], v[54:55], v[50:51]
	v_mov_b32_e32 v54, v52
	v_mov_b32_e32 v55, v60
	v_pk_fma_f32 v[50:51], v[16:17], v[54:55], v[50:51]
	v_mov_b32_e32 v60, v53
	v_pk_fma_f32 v[50:51], v[20:21], v[60:61], v[50:51]
	v_add_f32_e32 v50, v56, v50
	v_add_f32_e32 v50, v50, v51
	v_mul_f32_e64 v51, |v50|, s4
	v_exp_f32_e32 v51, v51
	s_nop 0
	v_add_f32_e32 v51, 1.0, v51
	v_mov_b32_e32 v52, v63
	v_min_f32_e32 v63, 0, v50
	v_log_f32_e32 v62, v51
	v_mov_b32_e32 v51, v52
	v_sub_f32_e32 v49, v49, v51
	ds_read_b128 v[50:53], v42 offset:35392
	ds_read_b128 v[54:57], v42 offset:35408
	v_mul_f32_e32 v58, 0x3f317217, v62
	v_fma_f32 v64, v62, s36, -v58
	v_fmac_f32_e32 v64, 0x3377d1cf, v62
	s_waitcnt lgkmcnt(1)
	v_mov_b32_e32 v58, v50
	s_waitcnt lgkmcnt(0)
	v_mov_b32_e32 v59, v54
	v_mov_b32_e32 v54, v51
	v_pk_mul_f32 v[50:51], v[26:27], v[54:55]
	v_mov_b32_e32 v54, v52
	v_pk_fma_f32 v[50:51], v[24:25], v[58:59], v[50:51]
	v_mov_b32_e32 v55, v56
	v_pk_fma_f32 v[54:55], v[22:23], v[54:55], v[50:51]
	v_mov_b32_e32 v56, v53
	ds_read_b128 v[50:53], v42 offset:35424
	ds_read_b128 v[58:61], v42 offset:35440
	v_pk_fma_f32 v[54:55], v[28:29], v[56:57], v[54:55]
	v_fmac_f32_e32 v64, 0x3f317217, v62
	v_add_f32_e32 v54, v2, v54
	v_add_f32_e32 v56, v54, v55
	s_waitcnt lgkmcnt(0)
	v_mov_b32_e32 v55, v58
	v_mov_b32_e32 v58, v51
	v_mov_b32_e32 v54, v50
	v_pk_mul_f32 v[50:51], v[18:19], v[58:59]
	v_pk_fma_f32 v[50:51], v[14:15], v[54:55], v[50:51]
	v_mov_b32_e32 v54, v52
	v_mov_b32_e32 v55, v60
	v_pk_fma_f32 v[50:51], v[16:17], v[54:55], v[50:51]
	v_mov_b32_e32 v60, v53
	v_pk_fma_f32 v[50:51], v[20:21], v[60:61], v[50:51]
	v_add_f32_e32 v50, v56, v50
	v_add_f32_e32 v51, v50, v51
	v_mul_f32_e64 v50, |v51|, s4
	v_exp_f32_e32 v50, v50
	v_mov_b32_e32 v52, v64
	v_min_f32_e32 v51, 0, v51
	v_add_f32_e32 v50, 1.0, v50
	s_nop 1
	v_log_f32_e32 v64, v50
	v_mov_b32_e32 v50, v52
	ds_read_b128 v[52:55], v42 offset:35456
	ds_read_b128 v[56:59], v42 offset:35472
	v_sub_f32_e32 v50, v63, v50
	v_mul_f32_e32 v60, 0x3f317217, v64
	v_fma_f32 v65, v64, s36, -v60
	s_waitcnt lgkmcnt(1)
	v_mov_b32_e32 v60, v52
	s_waitcnt lgkmcnt(0)
	v_mov_b32_e32 v61, v56
	v_mov_b32_e32 v56, v53
	v_pk_mul_f32 v[52:53], v[26:27], v[56:57]
	v_mov_b32_e32 v56, v54
	v_pk_fma_f32 v[52:53], v[24:25], v[60:61], v[52:53]
	v_mov_b32_e32 v57, v58
	v_pk_fma_f32 v[56:57], v[22:23], v[56:57], v[52:53]
	v_mov_b32_e32 v58, v55
	ds_read_b128 v[52:55], v42 offset:35488
	ds_read_b128 v[60:63], v42 offset:35504
	v_pk_fma_f32 v[56:57], v[28:29], v[58:59], v[56:57]
	v_fmac_f32_e32 v65, 0x3377d1cf, v64
	v_add_f32_e32 v56, v2, v56
	v_add_f32_e32 v58, v56, v57
	s_waitcnt lgkmcnt(0)
; #define LAS __attribute__((address_space(3)))
; __device__ __forceinline__ void gla_bcum(KArgs a, int tid, int t0, int h, LAS float* segtot, LAS float* glrs, float (&bc)[32], float& tot) {
;     ...
;     for (int r = 0; r < 32; ++r) { const LAS f32x4* gp = (const LAS f32x4*)(glrs + (seg * 32 + r) * 16);
;         float z = bias;
; #pragma unroll
;         for (int q = 0; q < 4; ++q) { const f32x4 g = gp[q]; z += g[0] * w2r[4 * q] + g[1] * w2r[4 * q + 1] + g[2] * w2r[4 * q + 2] + g[3] * w2r[4 * q + 3]; }
;         const float la = (fminf(z, 0.f) - __logf(1.0f + __expf(-fabsf(z)))) * (1.0f / 16.0f);
;         run += la; bc[r] = run; }
	v_mov_b32_e32 v57, v60
	v_mov_b32_e32 v60, v53
	v_mov_b32_e32 v56, v52
	v_pk_mul_f32 v[52:53], v[18:19], v[60:61]
	v_fmac_f32_e32 v65, 0x3f317217, v64
	v_pk_fma_f32 v[52:53], v[14:15], v[56:57], v[52:53]
	v_mov_b32_e32 v56, v54
	v_mov_b32_e32 v57, v62
	v_pk_fma_f32 v[52:53], v[16:17], v[56:57], v[52:53]
	v_mov_b32_e32 v62, v55
	v_pk_fma_f32 v[52:53], v[20:21], v[62:63], v[52:53]
	v_add_f32_e32 v52, v58, v52
	v_add_f32_e32 v52, v52, v53
	v_mul_f32_e64 v53, |v52|, s4
	v_exp_f32_e32 v53, v53
	s_nop 0
	v_add_f32_e32 v53, 1.0, v53
	v_mov_b32_e32 v54, v65
	v_min_f32_e32 v65, 0, v52
	v_log_f32_e32 v64, v53
	v_mov_b32_e32 v53, v54
	v_sub_f32_e32 v51, v51, v53
	ds_read_b128 v[52:55], v42 offset:35520
	ds_read_b128 v[56:59], v42 offset:35536
	v_mul_f32_e32 v60, 0x3f317217, v64
	v_fma_f32 v66, v64, s36, -v60
	v_fmac_f32_e32 v66, 0x3377d1cf, v64
	s_waitcnt lgkmcnt(1)
	v_mov_b32_e32 v60, v52
	s_waitcnt lgkmcnt(0)
	v_mov_b32_e32 v61, v56
	v_mov_b32_e32 v56, v53
	v_pk_mul_f32 v[52:53], v[26:27], v[56:57]
	v_mov_b32_e32 v56, v54
	v_pk_fma_f32 v[52:53], v[24:25], v[60:61], v[52:53]
	v_mov_b32_e32 v57, v58
	v_pk_fma_f32 v[56:57], v[22:23], v[56:57], v[52:53]
	v_mov_b32_e32 v58, v55
	ds_read_b128 v[52:55], v42 offset:35552
	ds_read_b128 v[60:63], v42 offset:35568
	v_pk_fma_f32 v[56:57], v[28:29], v[58:59], v[56:57]
	v_fmac_f32_e32 v66, 0x3f317217, v64
	v_add_f32_e32 v56, v2, v56
	v_add_f32_e32 v58, v56, v57
	s_waitcnt lgkmcnt(0)
	v_mov_b32_e32 v57, v60
	v_mov_b32_e32 v60, v53
	v_mov_b32_e32 v56, v52
	v_pk_mul_f32 v[52:53], v[18:19], v[60:61]
	v_pk_fma_f32 v[52:53], v[14:15], v[56:57], v[52:53]
	v_mov_b32_e32 v56, v54
	v_mov_b32_e32 v57, v62
	v_pk_fma_f32 v[52:53], v[16:17], v[56:57], v[52:53]
	v_mov_b32_e32 v62, v55
	v_pk_fma_f32 v[52:53], v[20:21], v[62:63], v[52:53]
	v_add_f32_e32 v52, v58, v52
	v_add_f32_e32 v53, v52, v53
	v_mul_f32_e64 v52, |v53|, s4
	v_exp_f32_e32 v52, v52
	v_mov_b32_e32 v54, v66
	v_min_f32_e32 v53, 0, v53
	v_add_f32_e32 v52, 1.0, v52
	s_nop 1
	v_log_f32_e32 v66, v52
	v_mov_b32_e32 v52, v54
	ds_read_b128 v[54:57], v42 offset:35584
	ds_read_b128 v[58:61], v42 offset:35600
	v_sub_f32_e32 v52, v65, v52
	v_mul_f32_e32 v62, 0x3f317217, v66
	v_fma_f32 v67, v66, s36, -v62
	s_waitcnt lgkmcnt(1)
	v_mov_b32_e32 v62, v54
	s_waitcnt lgkmcnt(0)
	v_mov_b32_e32 v63, v58
	v_mov_b32_e32 v58, v55
	v_pk_mul_f32 v[54:55], v[26:27], v[58:59]
	v_mov_b32_e32 v58, v56
	v_pk_fma_f32 v[54:55], v[24:25], v[62:63], v[54:55]
	v_mov_b32_e32 v59, v60
	v_pk_fma_f32 v[58:59], v[22:23], v[58:59], v[54:55]
	v_mov_b32_e32 v60, v57
	ds_read_b128 v[54:57], v42 offset:35616
	ds_read_b128 v[62:65], v42 offset:35632
	v_pk_fma_f32 v[58:59], v[28:29], v[60:61], v[58:59]
	v_fmac_f32_e32 v67, 0x3377d1cf, v66
	v_add_f32_e32 v58, v2, v58
	v_add_f32_e32 v60, v58, v59
	s_waitcnt lgkmcnt(0)
	v_mov_b32_e32 v59, v62
	v_mov_b32_e32 v62, v55
	v_mov_b32_e32 v58, v54
	v_pk_mul_f32 v[54:55], v[18:19], v[62:63]
	v_fmac_f32_e32 v67, 0x3f317217, v66
	v_pk_fma_f32 v[54:55], v[14:15], v[58:59], v[54:55]
	v_mov_b32_e32 v58, v56
	v_mov_b32_e32 v59, v64
	v_pk_fma_f32 v[54:55], v[16:17], v[58:59], v[54:55]
	v_mov_b32_e32 v64, v57
	v_pk_fma_f32 v[54:55], v[20:21], v[64:65], v[54:55]
	v_add_f32_e32 v54, v60, v54
	v_add_f32_e32 v54, v54, v55
	v_mul_f32_e64 v55, |v54|, s4
	v_exp_f32_e32 v55, v55
	s_nop 0
	v_add_f32_e32 v55, 1.0, v55
	v_mov_b32_e32 v56, v67
	v_min_f32_e32 v67, 0, v54
	v_log_f32_e32 v66, v55
	v_mov_b32_e32 v55, v56
	v_sub_f32_e32 v53, v53, v55
	ds_read_b128 v[54:57], v42 offset:35648
	ds_read_b128 v[58:61], v42 offset:35664
	v_mul_f32_e32 v62, 0x3f317217, v66
	v_fma_f32 v68, v66, s36, -v62
	v_fmac_f32_e32 v68, 0x3377d1cf, v66
	s_waitcnt lgkmcnt(1)
	v_mov_b32_e32 v62, v54
	s_waitcnt lgkmcnt(0)
	v_mov_b32_e32 v63, v58
	v_mov_b32_e32 v58, v55
	v_pk_mul_f32 v[54:55], v[26:27], v[58:59]
	v_mov_b32_e32 v58, v56
	v_pk_fma_f32 v[54:55], v[24:25], v[62:63], v[54:55]
	v_mov_b32_e32 v59, v60
	v_pk_fma_f32 v[58:59], v[22:23], v[58:59], v[54:55]
	v_mov_b32_e32 v60, v57
	ds_read_b128 v[54:57], v42 offset:35680
	ds_read_b128 v[62:65], v42 offset:35696
	v_pk_fma_f32 v[58:59], v[28:29], v[60:61], v[58:59]
	v_fmac_f32_e32 v68, 0x3f317217, v66
	v_add_f32_e32 v58, v2, v58
	v_add_f32_e32 v60, v58, v59
	s_waitcnt lgkmcnt(0)
	v_mov_b32_e32 v59, v62
	v_mov_b32_e32 v62, v55
	v_mov_b32_e32 v58, v54
	v_pk_mul_f32 v[54:55], v[18:19], v[62:63]
	v_pk_fma_f32 v[54:55], v[14:15], v[58:59], v[54:55]
	v_mov_b32_e32 v58, v56
	v_mov_b32_e32 v59, v64
	v_pk_fma_f32 v[54:55], v[16:17], v[58:59], v[54:55]
	v_mov_b32_e32 v64, v57
	v_pk_fma_f32 v[54:55], v[20:21], v[64:65], v[54:55]
	v_add_f32_e32 v54, v60, v54
	v_add_f32_e32 v55, v54, v55
	v_mul_f32_e64 v54, |v55|, s4
	v_exp_f32_e32 v54, v54
	v_mov_b32_e32 v56, v68
	v_min_f32_e32 v55, 0, v55
	v_add_f32_e32 v54, 1.0, v54
	s_nop 1
	v_log_f32_e32 v68, v54
	v_mov_b32_e32 v54, v56
	ds_read_b128 v[56:59], v42 offset:35712
	ds_read_b128 v[60:63], v42 offset:35728
	v_sub_f32_e32 v54, v67, v54
	v_mul_f32_e32 v64, 0x3f317217, v68
	v_fma_f32 v69, v68, s36, -v64
	s_waitcnt lgkmcnt(1)
	v_mov_b32_e32 v64, v56
	s_waitcnt lgkmcnt(0)
	v_mov_b32_e32 v65, v60
	v_mov_b32_e32 v60, v57
	v_pk_mul_f32 v[56:57], v[26:27], v[60:61]
	v_mov_b32_e32 v60, v58
	v_pk_fma_f32 v[56:57], v[24:25], v[64:65], v[56:57]
	v_mov_b32_e32 v61, v62
	v_pk_fma_f32 v[60:61], v[22:23], v[60:61], v[56:57]
	v_mov_b32_e32 v62, v59
	ds_read_b128 v[56:59], v42 offset:35744
	ds_read_b128 v[64:67], v42 offset:35760
	v_pk_fma_f32 v[60:61], v[28:29], v[62:63], v[60:61]
	v_fmac_f32_e32 v69, 0x3377d1cf, v68
	v_add_f32_e32 v60, v2, v60
	v_add_f32_e32 v62, v60, v61
	s_waitcnt lgkmcnt(0)
; #define LAS __attribute__((address_space(3)))
; __device__ __forceinline__ void gla_bcum(KArgs a, int tid, int t0, int h, LAS float* segtot, LAS float* glrs, float (&bc)[32], float& tot) {
;     ...
;     for (int r = 0; r < 32; ++r) { const LAS f32x4* gp = (const LAS f32x4*)(glrs + (seg * 32 + r) * 16);
;         float z = bias;
; #pragma unroll
;         for (int q = 0; q < 4; ++q) { const f32x4 g = gp[q]; z += g[0] * w2r[4 * q] + g[1] * w2r[4 * q + 1] + g[2] * w2r[4 * q + 2] + g[3] * w2r[4 * q + 3]; }
;         const float la = (fminf(z, 0.f) - __logf(1.0f + __expf(-fabsf(z)))) * (1.0f / 16.0f);
;         run += la; bc[r] = run; }
	v_mov_b32_e32 v61, v64
	v_mov_b32_e32 v64, v57
	v_mov_b32_e32 v60, v56
	v_pk_mul_f32 v[56:57], v[18:19], v[64:65]
	v_fmac_f32_e32 v69, 0x3f317217, v68
	v_pk_fma_f32 v[56:57], v[14:15], v[60:61], v[56:57]
	v_mov_b32_e32 v60, v58
	v_mov_b32_e32 v61, v66
	v_pk_fma_f32 v[56:57], v[16:17], v[60:61], v[56:57]
	v_mov_b32_e32 v66, v59
	v_pk_fma_f32 v[56:57], v[20:21], v[66:67], v[56:57]
	v_add_f32_e32 v56, v62, v56
	v_add_f32_e32 v56, v56, v57
	v_mul_f32_e64 v57, |v56|, s4
	v_exp_f32_e32 v57, v57
	s_nop 0
	v_add_f32_e32 v57, 1.0, v57
	v_mov_b32_e32 v58, v69
	v_min_f32_e32 v69, 0, v56
	v_log_f32_e32 v68, v57
	v_mov_b32_e32 v57, v58
	v_sub_f32_e32 v55, v55, v57
	ds_read_b128 v[56:59], v42 offset:35776
	ds_read_b128 v[60:63], v42 offset:35792
	v_mul_f32_e32 v64, 0x3f317217, v68
	v_fma_f32 v70, v68, s36, -v64
	v_fmac_f32_e32 v70, 0x3377d1cf, v68
	s_waitcnt lgkmcnt(1)
	v_mov_b32_e32 v64, v56
	s_waitcnt lgkmcnt(0)
	v_mov_b32_e32 v65, v60
	v_mov_b32_e32 v60, v57
	v_pk_mul_f32 v[56:57], v[26:27], v[60:61]
	v_mov_b32_e32 v60, v58
	v_pk_fma_f32 v[56:57], v[24:25], v[64:65], v[56:57]
	v_mov_b32_e32 v61, v62
	v_pk_fma_f32 v[60:61], v[22:23], v[60:61], v[56:57]
	v_mov_b32_e32 v62, v59
	ds_read_b128 v[56:59], v42 offset:35808
	ds_read_b128 v[64:67], v42 offset:35824
	v_pk_fma_f32 v[60:61], v[28:29], v[62:63], v[60:61]
	v_fmac_f32_e32 v70, 0x3f317217, v68
	v_add_f32_e32 v60, v2, v60
	v_add_f32_e32 v62, v60, v61
	s_waitcnt lgkmcnt(0)
	v_mov_b32_e32 v61, v64
	v_mov_b32_e32 v64, v57
	v_mov_b32_e32 v60, v56
	v_pk_mul_f32 v[56:57], v[18:19], v[64:65]
	v_pk_fma_f32 v[56:57], v[14:15], v[60:61], v[56:57]
	v_mov_b32_e32 v60, v58
	v_mov_b32_e32 v61, v66
	v_pk_fma_f32 v[56:57], v[16:17], v[60:61], v[56:57]
	v_mov_b32_e32 v66, v59
	v_pk_fma_f32 v[56:57], v[20:21], v[66:67], v[56:57]
	v_add_f32_e32 v56, v62, v56
	v_add_f32_e32 v57, v56, v57
	v_mul_f32_e64 v56, |v57|, s4
	v_exp_f32_e32 v56, v56
	v_mov_b32_e32 v58, v70
	v_min_f32_e32 v57, 0, v57
	v_add_f32_e32 v56, 1.0, v56
	s_nop 1
	v_log_f32_e32 v70, v56
	v_mov_b32_e32 v56, v58
	ds_read_b128 v[58:61], v42 offset:35840
	ds_read_b128 v[62:65], v42 offset:35856
	v_sub_f32_e32 v56, v69, v56
	v_mul_f32_e32 v66, 0x3f317217, v70
	v_fma_f32 v71, v70, s36, -v66
	s_waitcnt lgkmcnt(1)
	v_mov_b32_e32 v66, v58
	s_waitcnt lgkmcnt(0)
	v_mov_b32_e32 v67, v62
	v_mov_b32_e32 v62, v59
	v_pk_mul_f32 v[58:59], v[26:27], v[62:63]
	v_mov_b32_e32 v62, v60
	v_pk_fma_f32 v[58:59], v[24:25], v[66:67], v[58:59]
	v_mov_b32_e32 v63, v64
	v_pk_fma_f32 v[62:63], v[22:23], v[62:63], v[58:59]
	v_mov_b32_e32 v64, v61
	ds_read_b128 v[58:61], v42 offset:35872
	ds_read_b128 v[66:69], v42 offset:35888
	v_pk_fma_f32 v[62:63], v[28:29], v[64:65], v[62:63]
	v_fmac_f32_e32 v71, 0x3377d1cf, v70
	v_add_f32_e32 v62, v2, v62
	v_add_f32_e32 v64, v62, v63
	s_waitcnt lgkmcnt(0)
	v_mov_b32_e32 v63, v66
	v_mov_b32_e32 v66, v59
	v_mov_b32_e32 v62, v58
	v_pk_mul_f32 v[58:59], v[18:19], v[66:67]
	v_fmac_f32_e32 v71, 0x3f317217, v70
	v_pk_fma_f32 v[58:59], v[14:15], v[62:63], v[58:59]
	v_mov_b32_e32 v62, v60
	v_mov_b32_e32 v63, v68
	v_pk_fma_f32 v[58:59], v[16:17], v[62:63], v[58:59]
	v_mov_b32_e32 v68, v61
	v_pk_fma_f32 v[58:59], v[20:21], v[68:69], v[58:59]
	v_add_f32_e32 v58, v64, v58
	v_add_f32_e32 v58, v58, v59
	v_mul_f32_e64 v59, |v58|, s4
	v_exp_f32_e32 v59, v59
	s_nop 0
	v_add_f32_e32 v59, 1.0, v59
	v_mov_b32_e32 v60, v71
	v_min_f32_e32 v71, 0, v58
	v_log_f32_e32 v70, v59
	v_mov_b32_e32 v59, v60
	v_sub_f32_e32 v57, v57, v59
	ds_read_b128 v[58:61], v42 offset:35904
	ds_read_b128 v[62:65], v42 offset:35920
	v_mul_f32_e32 v66, 0x3f317217, v70
	v_fma_f32 v72, v70, s36, -v66
	v_fmac_f32_e32 v72, 0x3377d1cf, v70
	s_waitcnt lgkmcnt(1)
	v_mov_b32_e32 v66, v58
	s_waitcnt lgkmcnt(0)
	v_mov_b32_e32 v67, v62
	v_mov_b32_e32 v62, v59
	v_pk_mul_f32 v[58:59], v[26:27], v[62:63]
	v_mov_b32_e32 v62, v60
	v_pk_fma_f32 v[58:59], v[24:25], v[66:67], v[58:59]
	v_mov_b32_e32 v63, v64
	v_pk_fma_f32 v[62:63], v[22:23], v[62:63], v[58:59]
	v_mov_b32_e32 v64, v61
	ds_read_b128 v[58:61], v42 offset:35936
	ds_read_b128 v[66:69], v42 offset:35952
	v_pk_fma_f32 v[62:63], v[28:29], v[64:65], v[62:63]
	v_fmac_f32_e32 v72, 0x3f317217, v70
	v_add_f32_e32 v62, v2, v62
	v_add_f32_e32 v64, v62, v63
	s_waitcnt lgkmcnt(0)
	v_mov_b32_e32 v63, v66
	v_mov_b32_e32 v66, v59
	v_mov_b32_e32 v62, v58
	v_pk_mul_f32 v[58:59], v[18:19], v[66:67]
	v_pk_fma_f32 v[58:59], v[14:15], v[62:63], v[58:59]
	v_mov_b32_e32 v62, v60
	v_mov_b32_e32 v63, v68
	v_pk_fma_f32 v[58:59], v[16:17], v[62:63], v[58:59]
	v_mov_b32_e32 v68, v61
	v_pk_fma_f32 v[58:59], v[20:21], v[68:69], v[58:59]
	v_add_f32_e32 v58, v64, v58
	v_add_f32_e32 v59, v58, v59
	v_mul_f32_e64 v58, |v59|, s4
	v_exp_f32_e32 v58, v58
	v_mov_b32_e32 v60, v72
	v_min_f32_e32 v59, 0, v59
	v_add_f32_e32 v58, 1.0, v58
	s_nop 1
	v_log_f32_e32 v72, v58
	v_mov_b32_e32 v58, v60
	ds_read_b128 v[60:63], v42 offset:35968
	ds_read_b128 v[64:67], v42 offset:35984
	v_sub_f32_e32 v58, v71, v58
	v_mul_f32_e32 v68, 0x3f317217, v72
	v_fma_f32 v73, v72, s36, -v68
	s_waitcnt lgkmcnt(1)
	v_mov_b32_e32 v68, v60
	s_waitcnt lgkmcnt(0)
	v_mov_b32_e32 v69, v64
	v_mov_b32_e32 v64, v61
	v_pk_mul_f32 v[60:61], v[26:27], v[64:65]
	v_mov_b32_e32 v64, v62
	v_pk_fma_f32 v[60:61], v[24:25], v[68:69], v[60:61]
	v_mov_b32_e32 v65, v66
	v_pk_fma_f32 v[64:65], v[22:23], v[64:65], v[60:61]
	v_mov_b32_e32 v66, v63
	ds_read_b128 v[60:63], v42 offset:36000
	ds_read_b128 v[68:71], v42 offset:36016
	v_pk_fma_f32 v[64:65], v[28:29], v[66:67], v[64:65]
	v_fmac_f32_e32 v73, 0x3377d1cf, v72
	v_add_f32_e32 v64, v2, v64
	v_add_f32_e32 v66, v64, v65
	s_waitcnt lgkmcnt(0)
; #define LAS __attribute__((address_space(3)))
; __device__ __forceinline__ void gla_bcum(KArgs a, int tid, int t0, int h, LAS float* segtot, LAS float* glrs, float (&bc)[32], float& tot) {
;     ...
;     for (int r = 0; r < 32; ++r) { const LAS f32x4* gp = (const LAS f32x4*)(glrs + (seg * 32 + r) * 16);
;         float z = bias;
; #pragma unroll
;         for (int q = 0; q < 4; ++q) { const f32x4 g = gp[q]; z += g[0] * w2r[4 * q] + g[1] * w2r[4 * q + 1] + g[2] * w2r[4 * q + 2] + g[3] * w2r[4 * q + 3]; }
;         const float la = (fminf(z, 0.f) - __logf(1.0f + __expf(-fabsf(z)))) * (1.0f / 16.0f);
;         run += la; bc[r] = run; }
	v_mov_b32_e32 v65, v68
	v_mov_b32_e32 v68, v61
	v_mov_b32_e32 v64, v60
	v_pk_mul_f32 v[60:61], v[18:19], v[68:69]
	v_fmac_f32_e32 v73, 0x3f317217, v72
	v_pk_fma_f32 v[60:61], v[14:15], v[64:65], v[60:61]
	v_mov_b32_e32 v64, v62
	v_mov_b32_e32 v65, v70
	v_pk_fma_f32 v[60:61], v[16:17], v[64:65], v[60:61]
	v_mov_b32_e32 v70, v63
	v_pk_fma_f32 v[60:61], v[20:21], v[70:71], v[60:61]
	v_add_f32_e32 v60, v66, v60
	v_add_f32_e32 v60, v60, v61
	v_mul_f32_e64 v61, |v60|, s4
	v_exp_f32_e32 v61, v61
	s_nop 0
	v_add_f32_e32 v61, 1.0, v61
	v_mov_b32_e32 v62, v73
	v_min_f32_e32 v73, 0, v60
	v_log_f32_e32 v72, v61
	v_mov_b32_e32 v61, v62
	v_sub_f32_e32 v59, v59, v61
	ds_read_b128 v[60:63], v42 offset:36032
	ds_read_b128 v[64:67], v42 offset:36048
	v_mul_f32_e32 v68, 0x3f317217, v72
	v_fma_f32 v74, v72, s36, -v68
	v_fmac_f32_e32 v74, 0x3377d1cf, v72
	s_waitcnt lgkmcnt(1)
	v_mov_b32_e32 v68, v60
	s_waitcnt lgkmcnt(0)
	v_mov_b32_e32 v69, v64
	v_mov_b32_e32 v64, v61
	v_pk_mul_f32 v[60:61], v[26:27], v[64:65]
	v_mov_b32_e32 v64, v62
	v_pk_fma_f32 v[60:61], v[24:25], v[68:69], v[60:61]
	v_mov_b32_e32 v65, v66
	v_pk_fma_f32 v[64:65], v[22:23], v[64:65], v[60:61]
	v_mov_b32_e32 v66, v63
	ds_read_b128 v[60:63], v42 offset:36064
	ds_read_b128 v[68:71], v42 offset:36080
	v_pk_fma_f32 v[64:65], v[28:29], v[66:67], v[64:65]
	v_fmac_f32_e32 v74, 0x3f317217, v72
	v_add_f32_e32 v64, v2, v64
	v_add_f32_e32 v66, v64, v65
	s_waitcnt lgkmcnt(0)
	v_mov_b32_e32 v65, v68
	v_mov_b32_e32 v68, v61
	v_mov_b32_e32 v64, v60
	v_pk_mul_f32 v[60:61], v[18:19], v[68:69]
	v_pk_fma_f32 v[60:61], v[14:15], v[64:65], v[60:61]
	v_mov_b32_e32 v64, v62
	v_mov_b32_e32 v65, v70
	v_pk_fma_f32 v[60:61], v[16:17], v[64:65], v[60:61]
	v_mov_b32_e32 v70, v63
	v_pk_fma_f32 v[60:61], v[20:21], v[70:71], v[60:61]
	v_add_f32_e32 v60, v66, v60
	v_add_f32_e32 v61, v60, v61
	v_mul_f32_e64 v60, |v61|, s4
	v_exp_f32_e32 v60, v60
	v_mov_b32_e32 v62, v74
	v_min_f32_e32 v61, 0, v61
	v_add_f32_e32 v60, 1.0, v60
	s_nop 1
	v_log_f32_e32 v74, v60
	v_mov_b32_e32 v60, v62
	ds_read_b128 v[62:65], v42 offset:36096
	ds_read_b128 v[66:69], v42 offset:36112
	v_sub_f32_e32 v60, v73, v60
	v_mul_f32_e32 v70, 0x3f317217, v74
	v_fma_f32 v75, v74, s36, -v70
	s_waitcnt lgkmcnt(1)
	v_mov_b32_e32 v70, v62
	s_waitcnt lgkmcnt(0)
	v_mov_b32_e32 v71, v66
	v_mov_b32_e32 v66, v63
	v_pk_mul_f32 v[62:63], v[26:27], v[66:67]
	v_mov_b32_e32 v66, v64
	v_pk_fma_f32 v[62:63], v[24:25], v[70:71], v[62:63]
	v_mov_b32_e32 v67, v68
	v_pk_fma_f32 v[66:67], v[22:23], v[66:67], v[62:63]
	v_mov_b32_e32 v68, v65
	ds_read_b128 v[62:65], v42 offset:36128
	ds_read_b128 v[70:73], v42 offset:36144
	v_pk_fma_f32 v[66:67], v[28:29], v[68:69], v[66:67]
	v_fmac_f32_e32 v75, 0x3377d1cf, v74
	v_add_f32_e32 v66, v2, v66
	v_add_f32_e32 v68, v66, v67
	s_waitcnt lgkmcnt(0)
	v_mov_b32_e32 v67, v70
	v_mov_b32_e32 v70, v63
	v_mov_b32_e32 v66, v62
	v_pk_mul_f32 v[62:63], v[18:19], v[70:71]
	v_fmac_f32_e32 v75, 0x3f317217, v74
	v_pk_fma_f32 v[62:63], v[14:15], v[66:67], v[62:63]
	v_mov_b32_e32 v66, v64
	v_mov_b32_e32 v67, v72
	v_pk_fma_f32 v[62:63], v[16:17], v[66:67], v[62:63]
	v_mov_b32_e32 v72, v65
	v_pk_fma_f32 v[62:63], v[20:21], v[72:73], v[62:63]
	v_add_f32_e32 v62, v68, v62
	v_add_f32_e32 v62, v62, v63
	v_mul_f32_e64 v63, |v62|, s4
	v_exp_f32_e32 v63, v63
	s_nop 0
	v_add_f32_e32 v63, 1.0, v63
	v_mov_b32_e32 v64, v75
	v_min_f32_e32 v75, 0, v62
	v_log_f32_e32 v74, v63
	v_mov_b32_e32 v63, v64
	v_sub_f32_e32 v61, v61, v63
	ds_read_b128 v[62:65], v42 offset:36160
	ds_read_b128 v[66:69], v42 offset:36176
	v_mul_f32_e32 v70, 0x3f317217, v74
	v_fma_f32 v76, v74, s36, -v70
	v_fmac_f32_e32 v76, 0x3377d1cf, v74
	s_waitcnt lgkmcnt(1)
	v_mov_b32_e32 v70, v62
	s_waitcnt lgkmcnt(0)
	v_mov_b32_e32 v71, v66
	v_mov_b32_e32 v66, v63
	v_pk_mul_f32 v[62:63], v[26:27], v[66:67]
	v_mov_b32_e32 v66, v64
	v_pk_fma_f32 v[62:63], v[24:25], v[70:71], v[62:63]
	v_mov_b32_e32 v67, v68
	v_pk_fma_f32 v[66:67], v[22:23], v[66:67], v[62:63]
	v_mov_b32_e32 v68, v65
	ds_read_b128 v[62:65], v42 offset:36192
	ds_read_b128 v[70:73], v42 offset:36208
	v_pk_fma_f32 v[66:67], v[28:29], v[68:69], v[66:67]
	v_fmac_f32_e32 v76, 0x3f317217, v74
	v_add_f32_e32 v66, v2, v66
	v_add_f32_e32 v68, v66, v67
	s_waitcnt lgkmcnt(0)
	v_mov_b32_e32 v67, v70
	v_mov_b32_e32 v70, v63
	v_mov_b32_e32 v66, v62
	v_pk_mul_f32 v[62:63], v[18:19], v[70:71]
	v_pk_fma_f32 v[62:63], v[14:15], v[66:67], v[62:63]
	v_mov_b32_e32 v66, v64
	v_mov_b32_e32 v67, v72
	v_pk_fma_f32 v[62:63], v[16:17], v[66:67], v[62:63]
	v_mov_b32_e32 v72, v65
	v_pk_fma_f32 v[62:63], v[20:21], v[72:73], v[62:63]
	v_add_f32_e32 v62, v68, v62
	v_add_f32_e32 v63, v62, v63
	v_mul_f32_e64 v62, |v63|, s4
	v_exp_f32_e32 v62, v62
	v_mov_b32_e32 v64, v76
	v_min_f32_e32 v63, 0, v63
	v_add_f32_e32 v62, 1.0, v62
	s_nop 1
	v_log_f32_e32 v76, v62
	v_mov_b32_e32 v62, v64
	ds_read_b128 v[64:67], v42 offset:36224
	ds_read_b128 v[68:71], v42 offset:36240
	v_sub_f32_e32 v62, v75, v62
	v_mul_f32_e32 v72, 0x3f317217, v76
	v_fma_f32 v77, v76, s36, -v72
	s_waitcnt lgkmcnt(1)
	v_mov_b32_e32 v72, v64
	s_waitcnt lgkmcnt(0)
	v_mov_b32_e32 v73, v68
	v_mov_b32_e32 v68, v65
	v_pk_mul_f32 v[64:65], v[26:27], v[68:69]
	v_mov_b32_e32 v68, v66
	v_pk_fma_f32 v[64:65], v[24:25], v[72:73], v[64:65]
	v_mov_b32_e32 v69, v70
	v_pk_fma_f32 v[68:69], v[22:23], v[68:69], v[64:65]
	v_mov_b32_e32 v70, v67
	ds_read_b128 v[64:67], v42 offset:36256
	ds_read_b128 v[72:75], v42 offset:36272
	v_pk_fma_f32 v[68:69], v[28:29], v[70:71], v[68:69]
	v_fmac_f32_e32 v77, 0x3377d1cf, v76
	v_add_f32_e32 v68, v2, v68
	v_add_f32_e32 v70, v68, v69
	s_waitcnt lgkmcnt(0)
; #define LAS __attribute__((address_space(3)))
; __device__ __forceinline__ void gla_bcum(KArgs a, int tid, int t0, int h, LAS float* segtot, LAS float* glrs, float (&bc)[32], float& tot) {
;     ...
;     for (int r = 0; r < 32; ++r) { const LAS f32x4* gp = (const LAS f32x4*)(glrs + (seg * 32 + r) * 16);
;         float z = bias;
; #pragma unroll
;         for (int q = 0; q < 4; ++q) { const f32x4 g = gp[q]; z += g[0] * w2r[4 * q] + g[1] * w2r[4 * q + 1] + g[2] * w2r[4 * q + 2] + g[3] * w2r[4 * q + 3]; }
;         const float la = (fminf(z, 0.f) - __logf(1.0f + __expf(-fabsf(z)))) * (1.0f / 16.0f);
;         run += la; bc[r] = run; }
	v_mov_b32_e32 v69, v72
	v_mov_b32_e32 v72, v65
	v_mov_b32_e32 v68, v64
	v_pk_mul_f32 v[64:65], v[18:19], v[72:73]
	v_fmac_f32_e32 v77, 0x3f317217, v76
	v_pk_fma_f32 v[64:65], v[14:15], v[68:69], v[64:65]
	v_mov_b32_e32 v68, v66
	v_mov_b32_e32 v69, v74
	v_pk_fma_f32 v[64:65], v[16:17], v[68:69], v[64:65]
	v_mov_b32_e32 v74, v67
	v_pk_fma_f32 v[64:65], v[20:21], v[74:75], v[64:65]
	v_add_f32_e32 v64, v70, v64
	v_add_f32_e32 v64, v64, v65
	v_mul_f32_e64 v65, |v64|, s4
	v_exp_f32_e32 v65, v65
	s_nop 0
	v_add_f32_e32 v65, 1.0, v65
	v_mov_b32_e32 v66, v77
	v_min_f32_e32 v77, 0, v64
	v_log_f32_e32 v76, v65
	v_mov_b32_e32 v65, v66
	v_sub_f32_e32 v63, v63, v65
	ds_read_b128 v[64:67], v42 offset:36288
	ds_read_b128 v[68:71], v42 offset:36304
	v_mul_f32_e32 v72, 0x3f317217, v76
	v_fma_f32 v78, v76, s36, -v72
	v_fmac_f32_e32 v78, 0x3377d1cf, v76
	s_waitcnt lgkmcnt(1)
	v_mov_b32_e32 v72, v64
	s_waitcnt lgkmcnt(0)
	v_mov_b32_e32 v73, v68
	v_mov_b32_e32 v68, v65
	v_pk_mul_f32 v[64:65], v[26:27], v[68:69]
	v_mov_b32_e32 v68, v66
	v_pk_fma_f32 v[64:65], v[24:25], v[72:73], v[64:65]
	v_mov_b32_e32 v69, v70
	v_pk_fma_f32 v[68:69], v[22:23], v[68:69], v[64:65]
	v_mov_b32_e32 v70, v67
	ds_read_b128 v[64:67], v42 offset:36320
	ds_read_b128 v[72:75], v42 offset:36336
	v_pk_fma_f32 v[68:69], v[28:29], v[70:71], v[68:69]
	v_fmac_f32_e32 v78, 0x3f317217, v76
	v_add_f32_e32 v68, v2, v68
	v_add_f32_e32 v70, v68, v69
	s_waitcnt lgkmcnt(0)
	v_mov_b32_e32 v69, v72
	v_mov_b32_e32 v72, v65
	v_mov_b32_e32 v68, v64
	v_pk_mul_f32 v[64:65], v[18:19], v[72:73]
	v_pk_fma_f32 v[64:65], v[14:15], v[68:69], v[64:65]
	v_mov_b32_e32 v68, v66
	v_mov_b32_e32 v69, v74
	v_pk_fma_f32 v[64:65], v[16:17], v[68:69], v[64:65]
	v_mov_b32_e32 v74, v67
	v_pk_fma_f32 v[64:65], v[20:21], v[74:75], v[64:65]
	v_add_f32_e32 v64, v70, v64
	v_add_f32_e32 v65, v64, v65
	v_mul_f32_e64 v64, |v65|, s4
	v_exp_f32_e32 v64, v64
	v_mov_b32_e32 v66, v78
	v_min_f32_e32 v65, 0, v65
	v_add_f32_e32 v64, 1.0, v64
	s_nop 1
	v_log_f32_e32 v78, v64
	v_mov_b32_e32 v64, v66
	ds_read_b128 v[66:69], v42 offset:36352
	ds_read_b128 v[70:73], v42 offset:36368
	v_sub_f32_e32 v64, v77, v64
	v_mul_f32_e32 v74, 0x3f317217, v78
	v_fma_f32 v79, v78, s36, -v74
	s_waitcnt lgkmcnt(1)
	v_mov_b32_e32 v74, v66
	s_waitcnt lgkmcnt(0)
	v_mov_b32_e32 v75, v70
	v_mov_b32_e32 v70, v67
	v_pk_mul_f32 v[66:67], v[26:27], v[70:71]
	v_mov_b32_e32 v70, v68
	v_pk_fma_f32 v[66:67], v[24:25], v[74:75], v[66:67]
	v_mov_b32_e32 v71, v72
	v_pk_fma_f32 v[70:71], v[22:23], v[70:71], v[66:67]
	v_mov_b32_e32 v72, v69
	ds_read_b128 v[66:69], v42 offset:36384
	ds_read_b128 v[74:77], v42 offset:36400
	v_pk_fma_f32 v[70:71], v[28:29], v[72:73], v[70:71]
	v_fmac_f32_e32 v79, 0x3377d1cf, v78
	v_add_f32_e32 v70, v2, v70
	v_add_f32_e32 v72, v70, v71
	s_waitcnt lgkmcnt(0)
	v_mov_b32_e32 v71, v74
	v_mov_b32_e32 v74, v67
	v_mov_b32_e32 v70, v66
	v_pk_mul_f32 v[66:67], v[18:19], v[74:75]
	v_fmac_f32_e32 v79, 0x3f317217, v78
	v_pk_fma_f32 v[66:67], v[14:15], v[70:71], v[66:67]
	v_mov_b32_e32 v70, v68
	v_mov_b32_e32 v71, v76
	v_pk_fma_f32 v[66:67], v[16:17], v[70:71], v[66:67]
	v_mov_b32_e32 v76, v69
	v_pk_fma_f32 v[66:67], v[20:21], v[76:77], v[66:67]
	v_add_f32_e32 v66, v72, v66
	v_add_f32_e32 v66, v66, v67
	v_mul_f32_e64 v67, |v66|, s4
	v_exp_f32_e32 v67, v67
	s_nop 0
	v_add_f32_e32 v67, 1.0, v67
	v_mov_b32_e32 v68, v79
	v_min_f32_e32 v79, 0, v66
	v_log_f32_e32 v78, v67
	v_mov_b32_e32 v67, v68
	v_sub_f32_e32 v65, v65, v67
	ds_read_b128 v[66:69], v42 offset:36416
	ds_read_b128 v[70:73], v42 offset:36432
	v_mul_f32_e32 v74, 0x3f317217, v78
	v_fma_f32 v80, v78, s36, -v74
	v_fmac_f32_e32 v80, 0x3377d1cf, v78
	s_waitcnt lgkmcnt(1)
	v_mov_b32_e32 v74, v66
	s_waitcnt lgkmcnt(0)
	v_mov_b32_e32 v75, v70
	v_mov_b32_e32 v70, v67
	v_pk_mul_f32 v[66:67], v[26:27], v[70:71]
	v_mov_b32_e32 v70, v68
	v_pk_fma_f32 v[66:67], v[24:25], v[74:75], v[66:67]
	v_mov_b32_e32 v71, v72
	v_pk_fma_f32 v[70:71], v[22:23], v[70:71], v[66:67]
	v_mov_b32_e32 v72, v69
	ds_read_b128 v[66:69], v42 offset:36448
	ds_read_b128 v[74:77], v42 offset:36464
	v_pk_fma_f32 v[70:71], v[28:29], v[72:73], v[70:71]
	v_fmac_f32_e32 v80, 0x3f317217, v78
	v_add_f32_e32 v70, v2, v70
	v_add_f32_e32 v72, v70, v71
	s_waitcnt lgkmcnt(0)
	v_mov_b32_e32 v71, v74
	v_mov_b32_e32 v74, v67
	v_mov_b32_e32 v70, v66
	v_pk_mul_f32 v[66:67], v[18:19], v[74:75]
	v_pk_fma_f32 v[66:67], v[14:15], v[70:71], v[66:67]
	v_mov_b32_e32 v70, v68
	v_mov_b32_e32 v71, v76
	v_pk_fma_f32 v[66:67], v[16:17], v[70:71], v[66:67]
	v_mov_b32_e32 v76, v69
	v_pk_fma_f32 v[66:67], v[20:21], v[76:77], v[66:67]
	v_add_f32_e32 v66, v72, v66
	v_add_f32_e32 v66, v66, v67
	v_mul_f32_e64 v67, |v66|, s4
	v_exp_f32_e32 v67, v67
	v_mov_b32_e32 v68, v80
	v_min_f32_e32 v80, 0, v66
	v_add_f32_e32 v67, 1.0, v67
	s_nop 1
	v_log_f32_e32 v78, v67
	v_mov_b32_e32 v67, v68
	v_sub_f32_e32 v79, v79, v67
	ds_read_b128 v[66:69], v42 offset:36480
	ds_read_b128 v[70:73], v42 offset:36496
	v_mul_f32_e32 v74, 0x3f317217, v78
	v_fma_f32 v81, v78, s36, -v74
	v_fmac_f32_e32 v81, 0x3377d1cf, v78
	s_waitcnt lgkmcnt(1)
	v_mov_b32_e32 v74, v66
	s_waitcnt lgkmcnt(0)
	v_mov_b32_e32 v75, v70
	v_mov_b32_e32 v70, v67
	v_pk_mul_f32 v[66:67], v[26:27], v[70:71]
	v_mov_b32_e32 v70, v68
	v_pk_fma_f32 v[66:67], v[24:25], v[74:75], v[66:67]
	v_mov_b32_e32 v71, v72
	v_pk_fma_f32 v[70:71], v[22:23], v[70:71], v[66:67]
	v_mov_b32_e32 v72, v69
	ds_read_b128 v[66:69], v42 offset:36512
	ds_read_b128 v[74:77], v42 offset:36528
	v_pk_fma_f32 v[70:71], v[28:29], v[72:73], v[70:71]
	v_fmac_f32_e32 v81, 0x3f317217, v78
	v_add_f32_e32 v70, v2, v70
	v_add_f32_e32 v72, v70, v71
	s_waitcnt lgkmcnt(0)
; #define LAS __attribute__((address_space(3)))
; __device__ __forceinline__ void gla_bcum(KArgs a, int tid, int t0, int h, LAS float* segtot, LAS float* glrs, float (&bc)[32], float& tot) {
;     ...
;     for (int r = 0; r < 32; ++r) { const LAS f32x4* gp = (const LAS f32x4*)(glrs + (seg * 32 + r) * 16);
;         float z = bias;
; #pragma unroll
;         for (int q = 0; q < 4; ++q) { const f32x4 g = gp[q]; z += g[0] * w2r[4 * q] + g[1] * w2r[4 * q + 1] + g[2] * w2r[4 * q + 2] + g[3] * w2r[4 * q + 3]; }
;         const float la = (fminf(z, 0.f) - __logf(1.0f + __expf(-fabsf(z)))) * (1.0f / 16.0f);
;         run += la; bc[r] = run; }
	v_mov_b32_e32 v71, v74
	v_mov_b32_e32 v74, v67
	v_mov_b32_e32 v70, v66
	v_pk_mul_f32 v[66:67], v[18:19], v[74:75]
	v_pk_fma_f32 v[66:67], v[14:15], v[70:71], v[66:67]
	v_mov_b32_e32 v70, v68
	v_mov_b32_e32 v71, v76
	v_pk_fma_f32 v[66:67], v[16:17], v[70:71], v[66:67]
	v_mov_b32_e32 v76, v69
	v_pk_fma_f32 v[66:67], v[20:21], v[76:77], v[66:67]
	v_add_f32_e32 v66, v72, v66
	v_add_f32_e32 v66, v66, v67
	v_mul_f32_e64 v67, |v66|, s4
	v_exp_f32_e32 v67, v67
	v_mov_b32_e32 v68, v81
	v_min_f32_e32 v81, 0, v66
	v_add_f32_e32 v67, 1.0, v67
	s_nop 1
	v_log_f32_e32 v78, v67
	v_mov_b32_e32 v67, v68
	v_sub_f32_e32 v80, v80, v67
	ds_read_b128 v[66:69], v42 offset:36544
	ds_read_b128 v[70:73], v42 offset:36560
	v_mul_f32_e32 v74, 0x3f317217, v78
	v_fma_f32 v82, v78, s36, -v74
	v_fmac_f32_e32 v82, 0x3377d1cf, v78
	s_waitcnt lgkmcnt(1)
	v_mov_b32_e32 v74, v66
	s_waitcnt lgkmcnt(0)
	v_mov_b32_e32 v75, v70
	v_mov_b32_e32 v70, v67
	v_pk_mul_f32 v[66:67], v[26:27], v[70:71]
	v_mov_b32_e32 v70, v68
	v_pk_fma_f32 v[66:67], v[24:25], v[74:75], v[66:67]
	v_mov_b32_e32 v71, v72
	v_pk_fma_f32 v[70:71], v[22:23], v[70:71], v[66:67]
	v_mov_b32_e32 v72, v69
	ds_read_b128 v[66:69], v42 offset:36576
	ds_read_b128 v[74:77], v42 offset:36592
	v_pk_fma_f32 v[70:71], v[28:29], v[72:73], v[70:71]
	v_fmac_f32_e32 v82, 0x3f317217, v78
	v_add_f32_e32 v70, v2, v70
	v_add_f32_e32 v72, v70, v71
	s_waitcnt lgkmcnt(0)
	v_mov_b32_e32 v71, v74
	v_mov_b32_e32 v74, v67
	v_mov_b32_e32 v70, v66
	v_pk_mul_f32 v[66:67], v[18:19], v[74:75]
	v_pk_fma_f32 v[66:67], v[14:15], v[70:71], v[66:67]
	v_mov_b32_e32 v70, v68
	v_mov_b32_e32 v71, v76
	v_pk_fma_f32 v[66:67], v[16:17], v[70:71], v[66:67]
	v_mov_b32_e32 v76, v69
	v_pk_fma_f32 v[66:67], v[20:21], v[76:77], v[66:67]
	v_add_f32_e32 v66, v72, v66
	v_add_f32_e32 v66, v66, v67
	v_mul_f32_e64 v67, |v66|, s4
	v_exp_f32_e32 v67, v67
	v_mov_b32_e32 v68, v82
	v_min_f32_e32 v82, 0, v66
	v_add_f32_e32 v67, 1.0, v67
	s_nop 1
	v_log_f32_e32 v78, v67
	v_mov_b32_e32 v67, v68
	v_sub_f32_e32 v81, v81, v67
	ds_read_b128 v[66:69], v42 offset:36608
	ds_read_b128 v[70:73], v42 offset:36624
	v_mul_f32_e32 v74, 0x3f317217, v78
	v_fma_f32 v83, v78, s36, -v74
	v_fmac_f32_e32 v83, 0x3377d1cf, v78
	s_waitcnt lgkmcnt(1)
	v_mov_b32_e32 v74, v66
	s_waitcnt lgkmcnt(0)
	v_mov_b32_e32 v75, v70
	v_mov_b32_e32 v70, v67
	v_pk_mul_f32 v[66:67], v[26:27], v[70:71]
	v_mov_b32_e32 v70, v68
	v_pk_fma_f32 v[66:67], v[24:25], v[74:75], v[66:67]
	v_mov_b32_e32 v71, v72
	v_pk_fma_f32 v[70:71], v[22:23], v[70:71], v[66:67]
	v_mov_b32_e32 v72, v69
	ds_read_b128 v[66:69], v42 offset:36640
	ds_read_b128 v[74:77], v42 offset:36656
	v_pk_fma_f32 v[70:71], v[28:29], v[72:73], v[70:71]
	v_fmac_f32_e32 v83, 0x3f317217, v78
	v_add_f32_e32 v70, v2, v70
	v_add_f32_e32 v72, v70, v71
	s_waitcnt lgkmcnt(0)
	v_mov_b32_e32 v71, v74
	v_mov_b32_e32 v74, v67
	v_mov_b32_e32 v70, v66
	v_pk_mul_f32 v[66:67], v[18:19], v[74:75]
	v_pk_fma_f32 v[66:67], v[14:15], v[70:71], v[66:67]
	v_mov_b32_e32 v70, v68
	v_mov_b32_e32 v71, v76
	v_pk_fma_f32 v[66:67], v[16:17], v[70:71], v[66:67]
	v_mov_b32_e32 v76, v69
	v_pk_fma_f32 v[66:67], v[20:21], v[76:77], v[66:67]
	v_add_f32_e32 v66, v72, v66
	v_add_f32_e32 v66, v66, v67
	v_mul_f32_e64 v67, |v66|, s4
	v_exp_f32_e32 v67, v67
	v_mov_b32_e32 v68, v83
	v_min_f32_e32 v83, 0, v66
	v_add_f32_e32 v67, 1.0, v67
	s_nop 1
	v_log_f32_e32 v78, v67
	v_mov_b32_e32 v67, v68
	v_sub_f32_e32 v82, v82, v67
	ds_read_b128 v[66:69], v42 offset:36672
	ds_read_b128 v[70:73], v42 offset:36688
	v_mul_f32_e32 v74, 0x3f317217, v78
	v_fma_f32 v84, v78, s36, -v74
	v_fmac_f32_e32 v84, 0x3377d1cf, v78
	s_waitcnt lgkmcnt(1)
	v_mov_b32_e32 v74, v66
	s_waitcnt lgkmcnt(0)
	v_mov_b32_e32 v75, v70
	v_mov_b32_e32 v70, v67
	v_pk_mul_f32 v[66:67], v[26:27], v[70:71]
	v_mov_b32_e32 v70, v68
	v_pk_fma_f32 v[66:67], v[24:25], v[74:75], v[66:67]
	v_mov_b32_e32 v71, v72
	v_pk_fma_f32 v[70:71], v[22:23], v[70:71], v[66:67]
	v_mov_b32_e32 v72, v69
	ds_read_b128 v[66:69], v42 offset:36704
	ds_read_b128 v[74:77], v42 offset:36720
	v_pk_fma_f32 v[70:71], v[28:29], v[72:73], v[70:71]
	v_fmac_f32_e32 v84, 0x3f317217, v78
	v_add_f32_e32 v70, v2, v70
	v_add_f32_e32 v72, v70, v71
	s_waitcnt lgkmcnt(0)
	v_mov_b32_e32 v71, v74
	v_mov_b32_e32 v74, v67
	v_mov_b32_e32 v70, v66
	v_pk_mul_f32 v[66:67], v[18:19], v[74:75]
	v_pk_fma_f32 v[66:67], v[14:15], v[70:71], v[66:67]
	v_mov_b32_e32 v70, v68
	v_mov_b32_e32 v71, v76
	v_pk_fma_f32 v[66:67], v[16:17], v[70:71], v[66:67]
	v_mov_b32_e32 v76, v69
	v_pk_fma_f32 v[66:67], v[20:21], v[76:77], v[66:67]
	v_add_f32_e32 v66, v72, v66
	v_add_f32_e32 v66, v66, v67
	v_mul_f32_e64 v67, |v66|, s4
	v_exp_f32_e32 v67, v67
	v_mov_b32_e32 v68, v84
	v_min_f32_e32 v84, 0, v66
	v_add_f32_e32 v67, 1.0, v67
	s_nop 1
	v_log_f32_e32 v78, v67
	v_mov_b32_e32 v67, v68
	v_sub_f32_e32 v83, v83, v67
	ds_read_b128 v[66:69], v42 offset:36736
	ds_read_b128 v[70:73], v42 offset:36752
	v_mul_f32_e32 v74, 0x3f317217, v78
	v_fma_f32 v85, v78, s36, -v74
	v_fmac_f32_e32 v85, 0x3377d1cf, v78
	s_waitcnt lgkmcnt(1)
	v_mov_b32_e32 v74, v66
	s_waitcnt lgkmcnt(0)
	v_mov_b32_e32 v75, v70
	v_mov_b32_e32 v70, v67
	v_pk_mul_f32 v[66:67], v[26:27], v[70:71]
	v_mov_b32_e32 v70, v68
	v_pk_fma_f32 v[66:67], v[24:25], v[74:75], v[66:67]
	v_mov_b32_e32 v71, v72
	v_pk_fma_f32 v[70:71], v[22:23], v[70:71], v[66:67]
	v_mov_b32_e32 v72, v69
	ds_read_b128 v[66:69], v42 offset:36768
	ds_read_b128 v[74:77], v42 offset:36784
	v_pk_fma_f32 v[70:71], v[28:29], v[72:73], v[70:71]
	v_fmac_f32_e32 v85, 0x3f317217, v78
	v_add_f32_e32 v70, v2, v70
	v_add_f32_e32 v72, v70, v71
	s_waitcnt lgkmcnt(0)
; #define LAS __attribute__((address_space(3)))
; __device__ __forceinline__ float bf2f(bf16_t v) { return __uint_as_float((unsigned)v << 16); }
; __device__ __forceinline__ u32x4 pack8(const float* f) { u32x4 w; w.x = pk2(f[0], f[1]); w.y = pk2(f[2], f[3]); w.z = pk2(f[4], f[5]); w.w = pk2(f[6], f[7]); return w; }
; #define X make_ctx(lds_raw)
; __device__ __forceinline__ void gla_bcum(KArgs a, int tid, int t0, int h, LAS float* segtot, LAS float* glrs, float (&bc)[32], float& tot) {
;     ...
;     for (int r = 0; r < 32; ++r) { const LAS f32x4* gp = (const LAS f32x4*)(glrs + (seg * 32 + r) * 16);
;         float z = bias;
; #pragma unroll
;         for (int q = 0; q < 4; ++q) { const f32x4 g = gp[q]; z += g[0] * w2r[4 * q] + g[1] * w2r[4 * q + 1] + g[2] * w2r[4 * q + 2] + g[3] * w2r[4 * q + 3]; }
;         const float la = (fminf(z, 0.f) - __logf(1.0f + __expf(-fabsf(z)))) * (1.0f / 16.0f);
;         run += la; bc[r] = run; }
;     segtot[seg * 128 + d] = run;
;     __syncthreads();
;     float off = 0.f; tot = 0.f;
; #pragma unroll
;     for (int s2 = 0; s2 < 4; ++s2) { const float v = segtot[s2 * 128 + d]; tot += v; if (s2 < seg) off += v; }
; #pragma unroll
;     for (int r = 0; r < 32; ++r) bc[r] += off;
; __device__ __forceinline__ void gla_a1(const Ctx& X, KArgs a, float* kvt, float* decb) {
;     ...
;         { const int d = X.tid & 127, seg = X.tid >> 7;
; #pragma unroll
;           for (int r8 = 0; r8 < 4; ++r8) { float kd[8];
; #pragma unroll
;               for (int e = 0; e < 8; ++e) { const int r = r8 * 8 + e; kd[e] = bf2f(proj[(size_t)(t0 + seg * 32 + r) * NMAIN + C_GK + h * 128 + d]) * __expf(tot - bc[r]); }
;               *(LAS u32x4*)(kdT + d * GP + seg * 32 + r8 * 8) = pack8(kd); }
	v_mov_b32_e32 v71, v74
	v_mov_b32_e32 v74, v67
	v_mov_b32_e32 v70, v66
	v_pk_mul_f32 v[66:67], v[18:19], v[74:75]
	v_pk_fma_f32 v[66:67], v[14:15], v[70:71], v[66:67]
	v_mov_b32_e32 v70, v68
	v_mov_b32_e32 v71, v76
	v_pk_fma_f32 v[66:67], v[16:17], v[70:71], v[66:67]
	v_mov_b32_e32 v76, v69
	v_pk_fma_f32 v[66:67], v[20:21], v[76:77], v[66:67]
	v_add_f32_e32 v66, v72, v66
	v_add_f32_e32 v66, v66, v67
	v_mul_f32_e64 v67, |v66|, s4
	v_exp_f32_e32 v67, v67
	v_mov_b32_e32 v68, v85
	v_min_f32_e32 v78, 0, v66
	v_add_f32_e32 v67, 1.0, v67
	s_nop 1
	v_log_f32_e32 v76, v67
	v_mov_b32_e32 v67, v68
	v_sub_f32_e32 v77, v84, v67
	ds_read_b128 v[66:69], v42 offset:36800
	ds_read_b128 v[70:73], v42 offset:36816
	v_mul_f32_e32 v74, 0x3f317217, v76
	v_fma_f32 v84, v76, s36, -v74
	v_fmac_f32_e32 v84, 0x3377d1cf, v76
	s_waitcnt lgkmcnt(1)
	v_mov_b32_e32 v74, v66
	s_waitcnt lgkmcnt(0)
	v_mov_b32_e32 v75, v70
	v_mov_b32_e32 v70, v67
	v_pk_mul_f32 v[26:27], v[26:27], v[70:71]
	v_fmac_f32_e32 v84, 0x3f317217, v76
	v_pk_fma_f32 v[24:25], v[24:25], v[74:75], v[26:27]
	v_mov_b32_e32 v26, v68
	v_mov_b32_e32 v27, v72
	v_pk_fma_f32 v[26:27], v[22:23], v[26:27], v[24:25]
	v_mov_b32_e32 v72, v69
	ds_read_b128 v[22:25], v42 offset:36832
	ds_read_b128 v[66:69], v42 offset:36848
	v_pk_fma_f32 v[26:27], v[28:29], v[72:73], v[26:27]
	v_add_f32_e32 v2, v2, v26
	v_add_f32_e32 v2, v2, v27
	s_waitcnt lgkmcnt(0)
	v_mov_b32_e32 v27, v66
	v_mov_b32_e32 v66, v23
	v_mov_b32_e32 v26, v22
	v_pk_mul_f32 v[18:19], v[18:19], v[66:67]
	s_nop 0
	v_pk_fma_f32 v[14:15], v[14:15], v[26:27], v[18:19]
	v_mov_b32_e32 v18, v24
	v_mov_b32_e32 v19, v68
	v_pk_fma_f32 v[14:15], v[16:17], v[18:19], v[14:15]
	v_mov_b32_e32 v68, v25
	v_pk_fma_f32 v[14:15], v[20:21], v[68:69], v[14:15]
	v_add_f32_e32 v2, v2, v14
	v_add_f32_e32 v2, v2, v15
	v_mul_f32_e64 v14, |v2|, s4
	v_exp_f32_e32 v14, v14
	v_mov_b32_e32 v15, v84
	v_sub_f32_e32 v15, v78, v15
	v_add_f32_e32 v14, 1.0, v14
	v_min_f32_e32 v2, 0, v2
	s_nop 0
	v_fmamk_f32 v17, v49, 0x3d800000, v48
	v_fmamk_f32 v42, v50, 0x3d800000, v17
	v_fmamk_f32 v49, v51, 0x3d800000, v42
	v_fmamk_f32 v66, v52, 0x3d800000, v49
	v_fmamk_f32 v67, v53, 0x3d800000, v66
	v_fmamk_f32 v68, v54, 0x3d800000, v67
	v_fmamk_f32 v69, v55, 0x3d800000, v68
	v_fmamk_f32 v70, v56, 0x3d800000, v69
	v_fmamk_f32 v71, v57, 0x3d800000, v70
	v_fmamk_f32 v58, v58, 0x3d800000, v71
	v_fmamk_f32 v59, v59, 0x3d800000, v58
	v_fmamk_f32 v60, v60, 0x3d800000, v59
	v_fmamk_f32 v61, v61, 0x3d800000, v60
	v_log_f32_e32 v14, v14
	v_fmamk_f32 v62, v62, 0x3d800000, v61
	v_fmamk_f32 v63, v63, 0x3d800000, v62
	v_fmamk_f32 v64, v64, 0x3d800000, v63
	v_fmamk_f32 v65, v65, 0x3d800000, v64
	v_mul_f32_e32 v16, 0x3f317217, v14
	v_fmamk_f32 v72, v79, 0x3d800000, v65
	v_fma_f32 v16, v14, s36, -v16
	v_fmamk_f32 v73, v80, 0x3d800000, v72
	v_fmac_f32_e32 v16, 0x3377d1cf, v14
	v_fmamk_f32 v74, v81, 0x3d800000, v73
	v_fmac_f32_e32 v16, 0x3f317217, v14
	v_fmamk_f32 v75, v82, 0x3d800000, v74
	v_fmamk_f32 v76, v83, 0x3d800000, v75
	v_mov_b32_e32 v14, v16
	v_fmamk_f32 v77, v77, 0x3d800000, v76
	v_sub_f32_e32 v2, v2, v14
	v_fmamk_f32 v78, v15, 0x3d800000, v77
	v_lshl_add_u32 v14, s1, 2, v34
	v_fmamk_f32 v79, v2, 0x3d800000, v78
	ds_write_b32 v14, v79
	s_waitcnt lgkmcnt(0)
	s_barrier
	ds_read2st64_b32 v[14:15], v34 offset1:2
	ds_read2st64_b32 v[20:21], v34 offset0:4 offset1:6
	s_cselect_b64 s[6:7], -1, 0
	s_cmp_gt_i32 s0, 1
	s_waitcnt lgkmcnt(1)
	v_add_f32_e32 v2, 0, v14
	v_cndmask_b32_e64 v14, 0, v2, s[6:7]
	v_add_f32_e32 v16, v15, v14
	s_cselect_b64 s[6:7], -1, 0
	s_cmp_gt_i32 s0, 2
	v_cndmask_b32_e64 v14, v14, v16, s[6:7]
	s_waitcnt lgkmcnt(0)
	v_add_f32_e32 v18, v20, v14
	s_cselect_b64 s[6:7], -1, 0
	v_add_f32_e32 v2, v15, v2
	s_cmp_gt_i32 s0, 3
	v_add_f32_e32 v16, v20, v2
	v_cndmask_b32_e64 v2, v14, v18, s[6:7]
	v_add_f32_e32 v14, v21, v2
	s_cselect_b64 s[6:7], -1, 0
	v_add_u32_e32 v20, s20, v35
	v_cndmask_b32_e64 v19, v2, v14, s[6:7]
	v_mov_b64_e32 v[14:15], s[18:19]
	v_or_b32_e32 v18, 1, v20
	v_mad_i64_i32 v[24:25], s[0:1], v18, s35, v[14:15]
	v_or_b32_e32 v18, 2, v20
	v_mad_i64_i32 v[26:27], s[0:1], v18, s35, v[14:15]
	v_or_b32_e32 v18, 3, v20
	v_mad_i64_i32 v[28:29], s[0:1], v18, s35, v[14:15]
	v_or_b32_e32 v18, 4, v20
	v_mad_i64_i32 v[50:51], s[0:1], v18, s35, v[14:15]
	v_or_b32_e32 v18, 5, v20
	v_mad_i64_i32 v[52:53], s[0:1], v18, s35, v[14:15]
	v_or_b32_e32 v18, 6, v20
	v_mad_i64_i32 v[22:23], s[0:1], v20, s35, v[14:15]
	s_lshl_b32 s38, s5, 8
	v_mad_i64_i32 v[54:55], s[0:1], v18, s35, v[14:15]
	v_or_b32_e32 v18, 7, v20
	v_lshl_add_u64 v[22:23], v[22:23], 0, s[38:39]
	v_lshlrev_b32_e32 v2, 1, v8
	v_mad_i64_i32 v[56:57], s[0:1], v18, s35, v[14:15]
	v_lshl_add_u64 v[22:23], v[22:23], 0, v[2:3]
	v_lshl_add_u64 v[24:25], v[24:25], 0, s[38:39]
	v_lshl_add_u64 v[26:27], v[26:27], 0, s[38:39]
	v_lshl_add_u64 v[28:29], v[28:29], 0, s[38:39]
	v_lshl_add_u64 v[50:51], v[50:51], 0, s[38:39]
	v_lshl_add_u64 v[52:53], v[52:53], 0, s[38:39]
	v_lshl_add_u64 v[54:55], v[54:55], 0, s[38:39]
	v_lshl_add_u64 v[56:57], v[56:57], 0, s[38:39]
	v_lshl_add_u64 v[24:25], v[24:25], 0, v[2:3]
	v_lshl_add_u64 v[26:27], v[26:27], 0, v[2:3]
	v_lshl_add_u64 v[28:29], v[28:29], 0, v[2:3]
	v_lshl_add_u64 v[50:51], v[50:51], 0, v[2:3]
	v_lshl_add_u64 v[52:53], v[52:53], 0, v[2:3]
	v_lshl_add_u64 v[54:55], v[54:55], 0, v[2:3]
	v_lshl_add_u64 v[56:57], v[56:57], 0, v[2:3]
	global_load_ushort v80, v[22:23], off offset:1024
	global_load_ushort v81, v[24:25], off offset:1024
	global_load_ushort v82, v[26:27], off offset:1024
	global_load_ushort v83, v[28:29], off offset:1024
	global_load_ushort v84, v[50:51], off offset:1024
	global_load_ushort v85, v[52:53], off offset:1024
; #define LAS __attribute__((address_space(3)))
; __device__ __forceinline__ float bf2f(bf16_t v) { return __uint_as_float((unsigned)v << 16); }
; __device__ __forceinline__ u32x4 pack8(const float* f) { u32x4 w; w.x = pk2(f[0], f[1]); w.y = pk2(f[2], f[3]); w.z = pk2(f[4], f[5]); w.w = pk2(f[6], f[7]); return w; }
; #define X make_ctx(lds_raw)
; __device__ __forceinline__ void gla_a1(const Ctx& X, KArgs a, float* kvt, float* decb) {
;     ...
;         { const int d = X.tid & 127, seg = X.tid >> 7;
; #pragma unroll
;           for (int r8 = 0; r8 < 4; ++r8) { float kd[8];
; #pragma unroll
;               for (int e = 0; e < 8; ++e) { const int r = r8 * 8 + e; kd[e] = bf2f(proj[(size_t)(t0 + seg * 32 + r) * NMAIN + C_GK + h * 128 + d]) * __expf(tot - bc[r]); }
;               *(LAS u32x4*)(kdT + d * GP + seg * 32 + r8 * 8) = pack8(kd); }
	global_load_ushort v86, v[54:55], off offset:1024
	global_load_ushort v87, v[56:57], off offset:1024
	v_or_b32_e32 v18, 8, v20
	v_mad_i64_i32 v[22:23], s[0:1], v18, s35, v[14:15]
	v_or_b32_e32 v18, 9, v20
	v_mad_i64_i32 v[24:25], s[0:1], v18, s35, v[14:15]
	v_or_b32_e32 v18, 10, v20
	v_mad_i64_i32 v[26:27], s[0:1], v18, s35, v[14:15]
	v_or_b32_e32 v18, 11, v20
	v_mad_i64_i32 v[28:29], s[0:1], v18, s35, v[14:15]
	v_or_b32_e32 v18, 12, v20
	v_mad_i64_i32 v[50:51], s[0:1], v18, s35, v[14:15]
	v_or_b32_e32 v18, 13, v20
	v_mad_i64_i32 v[52:53], s[0:1], v18, s35, v[14:15]
	v_or_b32_e32 v18, 14, v20
	v_mad_i64_i32 v[54:55], s[0:1], v18, s35, v[14:15]
	v_or_b32_e32 v18, 15, v20
	v_lshl_add_u64 v[24:25], v[24:25], 0, s[38:39]
	v_lshl_add_u64 v[50:51], v[50:51], 0, s[38:39]
	v_lshl_add_u64 v[52:53], v[52:53], 0, s[38:39]
	v_lshl_add_u64 v[54:55], v[54:55], 0, s[38:39]
	v_mad_i64_i32 v[56:57], s[0:1], v18, s35, v[14:15]
	v_lshl_add_u64 v[22:23], v[22:23], 0, s[38:39]
	v_lshl_add_u64 v[24:25], v[24:25], 0, v[2:3]
	v_lshl_add_u64 v[26:27], v[26:27], 0, s[38:39]
	v_lshl_add_u64 v[28:29], v[28:29], 0, s[38:39]
	v_lshl_add_u64 v[50:51], v[50:51], 0, v[2:3]
	v_lshl_add_u64 v[52:53], v[52:53], 0, v[2:3]
	v_lshl_add_u64 v[54:55], v[54:55], 0, v[2:3]
	v_lshl_add_u64 v[56:57], v[56:57], 0, s[38:39]
	v_lshl_add_u64 v[22:23], v[22:23], 0, v[2:3]
	v_lshl_add_u64 v[26:27], v[26:27], 0, v[2:3]
	v_lshl_add_u64 v[28:29], v[28:29], 0, v[2:3]
	v_lshl_add_u64 v[56:57], v[56:57], 0, v[2:3]
	global_load_ushort v88, v[24:25], off offset:1024
	global_load_ushort v89, v[26:27], off offset:1024
	global_load_ushort v90, v[28:29], off offset:1024
	global_load_ushort v91, v[50:51], off offset:1024
	s_nop 0
	global_load_ushort v52, v[52:53], off offset:1024
	s_nop 0
	global_load_ushort v53, v[54:55], off offset:1024
	s_nop 0
	global_load_ushort v54, v[56:57], off offset:1024
	global_load_ushort v50, v[22:23], off offset:1024
	v_mov_b32_e32 v18, v21
	v_add_f32_e32 v13, v13, v19
	v_pk_add_f32 v[16:17], v[18:19], v[16:17]
	v_add_f32_e32 v44, v44, v19
	v_add_f32_e32 v46, v46, v19
	v_sub_f32_e32 v13, v16, v13
	v_add_f32_e32 v25, v43, v19
	v_add_f32_e32 v26, v45, v19
	v_add_f32_e32 v27, v47, v19
	v_add_f32_e32 v28, v48, v19
	v_add_f32_e32 v21, v42, v19
	v_add_f32_e32 v42, v49, v19
	v_add_f32_e32 v43, v66, v19
	v_add_f32_e32 v55, v67, v19
	v_add_f32_e32 v56, v68, v19
	v_add_f32_e32 v57, v69, v19
	v_add_f32_e32 v66, v70, v19
	v_add_f32_e32 v67, v71, v19
	v_add_f32_e32 v58, v58, v19
	v_add_f32_e32 v59, v59, v19
	v_add_f32_e32 v60, v60, v19
	v_add_f32_e32 v61, v61, v19
	v_add_f32_e32 v62, v62, v19
	v_add_f32_e32 v63, v63, v19
	v_add_f32_e32 v64, v64, v19
	v_add_f32_e32 v65, v65, v19
	v_add_f32_e32 v68, v72, v19
	v_add_f32_e32 v69, v73, v19
	v_add_f32_e32 v70, v74, v19
	v_add_f32_e32 v71, v75, v19
	v_add_f32_e32 v72, v76, v19
	v_add_f32_e32 v73, v77, v19
	v_add_f32_e32 v74, v78, v19
	v_add_f32_e32 v75, v19, v79
	v_sub_f32_e32 v18, v16, v44
	v_sub_f32_e32 v19, v16, v46
	v_mul_f32_e32 v13, 0x3fb8aa3b, v13
	v_mul_f32_e32 v18, 0x3fb8aa3b, v18
	v_mul_f32_e32 v19, 0x3fb8aa3b, v19
	v_exp_f32_e32 v24, v13
	v_sub_f32_e32 v13, v16, v25
	v_exp_f32_e32 v18, v18
	v_exp_f32_e32 v19, v19
	v_mul_f32_e32 v13, 0x3fb8aa3b, v13
	v_exp_f32_e32 v25, v13
	s_waitcnt vmcnt(14)
	v_lshlrev_b32_e32 v23, 16, v81
	v_lshlrev_b32_e32 v22, 16, v80
	v_sub_f32_e32 v13, v16, v26
	v_pk_mul_f32 v[18:19], v[18:19], v[22:23]
	s_waitcnt vmcnt(12)
	v_lshlrev_b32_e32 v23, 16, v83
	v_lshlrev_b32_e32 v22, 16, v82
	v_mul_f32_e32 v13, 0x3fb8aa3b, v13
	v_pk_mul_f32 v[24:25], v[24:25], v[22:23]
	v_exp_f32_e32 v22, v13
	v_sub_f32_e32 v13, v16, v27
	v_mul_f32_e32 v13, 0x3fb8aa3b, v13
	v_exp_f32_e32 v23, v13
	v_sub_f32_e32 v13, v16, v28
	v_mul_f32_e32 v13, 0x3fb8aa3b, v13
	v_exp_f32_e32 v28, v13
	v_sub_f32_e32 v13, v16, v17
	v_mul_f32_e32 v13, 0x3fb8aa3b, v13
	v_exp_f32_e32 v29, v13
	s_waitcnt vmcnt(10)
	v_lshlrev_b32_e32 v27, 16, v85
	v_lshlrev_b32_e32 v26, 16, v84
	v_pk_mul_f32 v[26:27], v[22:23], v[26:27]
	s_waitcnt vmcnt(8)
	v_lshlrev_b32_e32 v23, 16, v87
	v_lshlrev_b32_e32 v22, 16, v86
	v_pk_mul_f32 v[28:29], v[28:29], v[22:23]
	v_cvt_pk_bf16_f32 v22, v18, v19
	v_cvt_pk_bf16_f32 v23, v24, v25
	v_cvt_pk_bf16_f32 v24, v26, v27
	v_cvt_pk_bf16_f32 v25, v28, v29
	v_sub_f32_e32 v13, v16, v21
	v_or_b32_e32 v17, 16, v20
	ds_write_b128 v37, v[22:25]
	v_mul_f32_e32 v13, 0x3fb8aa3b, v13
	v_mad_i64_i32 v[24:25], s[0:1], v17, s35, v[14:15]
	v_or_b32_e32 v17, 17, v20
	v_exp_f32_e32 v18, v13
	v_sub_f32_e32 v13, v16, v42
	v_mad_i64_i32 v[26:27], s[0:1], v17, s35, v[14:15]
	v_or_b32_e32 v17, 18, v20
	v_mul_f32_e32 v13, 0x3fb8aa3b, v13
	v_mad_i64_i32 v[28:29], s[0:1], v17, s35, v[14:15]
	v_or_b32_e32 v17, 19, v20
	v_exp_f32_e32 v19, v13
	v_sub_f32_e32 v13, v16, v43
	v_mad_i64_i32 v[42:43], s[0:1], v17, s35, v[14:15]
	v_or_b32_e32 v17, 20, v20
	v_mad_i64_i32 v[44:45], s[0:1], v17, s35, v[14:15]
	v_or_b32_e32 v17, 21, v20
	v_mad_i64_i32 v[46:47], s[0:1], v17, s35, v[14:15]
	v_or_b32_e32 v17, 22, v20
	v_mad_i64_i32 v[48:49], s[0:1], v17, s35, v[14:15]
	v_or_b32_e32 v17, 23, v20
	s_waitcnt vmcnt(0)
; #define LAS __attribute__((address_space(3)))
; __device__ __forceinline__ float bf2f(bf16_t v) { return __uint_as_float((unsigned)v << 16); }
; __device__ __forceinline__ u32x4 pack8(const float* f) { u32x4 w; w.x = pk2(f[0], f[1]); w.y = pk2(f[2], f[3]); w.z = pk2(f[4], f[5]); w.w = pk2(f[6], f[7]); return w; }
; #define X make_ctx(lds_raw)
; __device__ __forceinline__ void gla_a1(const Ctx& X, KArgs a, float* kvt, float* decb) {
;     ...
;         { const int d = X.tid & 127, seg = X.tid >> 7;
; #pragma unroll
;           for (int r8 = 0; r8 < 4; ++r8) { float kd[8];
; #pragma unroll
;               for (int e = 0; e < 8; ++e) { const int r = r8 * 8 + e; kd[e] = bf2f(proj[(size_t)(t0 + seg * 32 + r) * NMAIN + C_GK + h * 128 + d]) * __expf(tot - bc[r]); }
;               *(LAS u32x4*)(kdT + d * GP + seg * 32 + r8 * 8) = pack8(kd); }
;           if (seg == 0) decb[unit * 128 + d] = __expf(tot); }
	v_lshlrev_b32_e32 v22, 16, v50
	v_mad_i64_i32 v[50:51], s[0:1], v17, s35, v[14:15]
	v_lshl_add_u64 v[24:25], v[24:25], 0, s[38:39]
	v_lshl_add_u64 v[50:51], v[50:51], 0, s[38:39]
	v_lshl_add_u64 v[24:25], v[24:25], 0, v[2:3]
	v_lshl_add_u64 v[26:27], v[26:27], 0, s[38:39]
	v_lshl_add_u64 v[28:29], v[28:29], 0, s[38:39]
	v_lshl_add_u64 v[42:43], v[42:43], 0, s[38:39]
	v_lshl_add_u64 v[44:45], v[44:45], 0, s[38:39]
	v_lshl_add_u64 v[46:47], v[46:47], 0, s[38:39]
	v_lshl_add_u64 v[48:49], v[48:49], 0, s[38:39]
	v_lshl_add_u64 v[50:51], v[50:51], 0, v[2:3]
	v_lshl_add_u64 v[26:27], v[26:27], 0, v[2:3]
	v_lshl_add_u64 v[28:29], v[28:29], 0, v[2:3]
	v_lshl_add_u64 v[42:43], v[42:43], 0, v[2:3]
	v_lshl_add_u64 v[44:45], v[44:45], 0, v[2:3]
	v_lshl_add_u64 v[46:47], v[46:47], 0, v[2:3]
	v_lshl_add_u64 v[48:49], v[48:49], 0, v[2:3]
	global_load_ushort v17, v[24:25], off offset:1024
	global_load_ushort v76, v[26:27], off offset:1024
	global_load_ushort v77, v[28:29], off offset:1024
	global_load_ushort v78, v[42:43], off offset:1024
	global_load_ushort v79, v[44:45], off offset:1024
	global_load_ushort v80, v[46:47], off offset:1024
	global_load_ushort v81, v[48:49], off offset:1024
	s_nop 0
	global_load_ushort v50, v[50:51], off offset:1024
	v_or_b32_e32 v21, 24, v20
	v_mad_i64_i32 v[24:25], s[0:1], v21, s35, v[14:15]
	v_or_b32_e32 v21, 25, v20
	v_mad_i64_i32 v[26:27], s[0:1], v21, s35, v[14:15]
	v_or_b32_e32 v21, 26, v20
	v_mad_i64_i32 v[28:29], s[0:1], v21, s35, v[14:15]
	v_or_b32_e32 v21, 27, v20
	v_mad_i64_i32 v[42:43], s[0:1], v21, s35, v[14:15]
	v_or_b32_e32 v21, 28, v20
	v_mad_i64_i32 v[44:45], s[0:1], v21, s35, v[14:15]
	v_or_b32_e32 v21, 29, v20
	v_mad_i64_i32 v[46:47], s[0:1], v21, s35, v[14:15]
	v_or_b32_e32 v21, 30, v20
	v_or_b32_e32 v20, 31, v20
	v_lshl_add_u64 v[26:27], v[26:27], 0, s[38:39]
	v_lshl_add_u64 v[28:29], v[28:29], 0, s[38:39]
	v_lshl_add_u64 v[42:43], v[42:43], 0, s[38:39]
	v_lshl_add_u64 v[44:45], v[44:45], 0, s[38:39]
	v_mad_i64_i32 v[48:49], s[0:1], v21, s35, v[14:15]
	v_mad_i64_i32 v[14:15], s[0:1], v20, s35, v[14:15]
	v_lshl_add_u64 v[24:25], v[24:25], 0, s[38:39]
	v_lshl_add_u64 v[26:27], v[26:27], 0, v[2:3]
	v_lshl_add_u64 v[28:29], v[28:29], 0, v[2:3]
	v_lshl_add_u64 v[42:43], v[42:43], 0, v[2:3]
	v_lshl_add_u64 v[44:45], v[44:45], 0, v[2:3]
	v_lshl_add_u64 v[46:47], v[46:47], 0, s[38:39]
	v_lshl_add_u64 v[48:49], v[48:49], 0, s[38:39]
	v_lshl_add_u64 v[14:15], v[14:15], 0, s[38:39]
	v_lshl_add_u64 v[24:25], v[24:25], 0, v[2:3]
	v_lshl_add_u64 v[46:47], v[46:47], 0, v[2:3]
	v_lshl_add_u64 v[48:49], v[48:49], 0, v[2:3]
	v_lshl_add_u64 v[14:15], v[14:15], 0, v[2:3]
	global_load_ushort v2, v[26:27], off offset:1024
	s_nop 0
	global_load_ushort v26, v[28:29], off offset:1024
	global_load_ushort v27, v[42:43], off offset:1024
	s_nop 0
	global_load_ushort v28, v[44:45], off offset:1024
	global_load_ushort v29, v[46:47], off offset:1024
	global_load_ushort v42, v[48:49], off offset:1024
	global_load_ushort v43, v[14:15], off offset:1024
	s_nop 0
	global_load_ushort v44, v[24:25], off offset:1024
	v_mul_f32_e32 v13, 0x3fb8aa3b, v13
	v_exp_f32_e32 v14, v13
	v_sub_f32_e32 v13, v16, v55
	v_mul_f32_e32 v13, 0x3fb8aa3b, v13
	v_exp_f32_e32 v15, v13
	v_sub_f32_e32 v13, v16, v56
	v_lshlrev_b32_e32 v21, 16, v90
	v_lshlrev_b32_e32 v20, 16, v89
	v_mul_f32_e32 v13, 0x3fb8aa3b, v13
	v_pk_mul_f32 v[14:15], v[14:15], v[20:21]
	v_exp_f32_e32 v20, v13
	v_sub_f32_e32 v13, v16, v57
	v_mul_f32_e32 v13, 0x3fb8aa3b, v13
	v_exp_f32_e32 v21, v13
	v_sub_f32_e32 v13, v16, v66
	v_mul_f32_e32 v13, 0x3fb8aa3b, v13
	v_exp_f32_e32 v24, v13
	v_sub_f32_e32 v13, v16, v67
	v_mul_f32_e32 v13, 0x3fb8aa3b, v13
	v_lshlrev_b32_e32 v23, 16, v88
	v_exp_f32_e32 v25, v13
	v_sub_f32_e32 v13, v16, v58
	v_pk_mul_f32 v[18:19], v[18:19], v[22:23]
	v_mul_f32_e32 v13, 0x3fb8aa3b, v13
	v_lshlrev_b32_e32 v23, 16, v52
	v_lshlrev_b32_e32 v22, 16, v91
	v_cvt_pk_bf16_f32 v18, v18, v19
	v_cvt_pk_bf16_f32 v19, v14, v15
	v_exp_f32_e32 v14, v13
	v_sub_f32_e32 v13, v16, v59
	v_pk_mul_f32 v[20:21], v[20:21], v[22:23]
	v_lshlrev_b32_e32 v23, 16, v54
	v_lshlrev_b32_e32 v22, 16, v53
	v_mul_f32_e32 v13, 0x3fb8aa3b, v13
	v_pk_mul_f32 v[22:23], v[24:25], v[22:23]
	v_exp_f32_e32 v15, v13
	v_sub_f32_e32 v13, v16, v60
	v_cvt_pk_bf16_f32 v20, v20, v21
	v_cvt_pk_bf16_f32 v21, v22, v23
	v_mul_f32_e32 v13, 0x3fb8aa3b, v13
	ds_write_b128 v37, v[18:21] offset:16
	v_exp_f32_e32 v20, v13
	v_sub_f32_e32 v13, v16, v61
	v_mul_f32_e32 v13, 0x3fb8aa3b, v13
	v_exp_f32_e32 v21, v13
	s_waitcnt vmcnt(14)
	v_lshlrev_b32_e32 v19, 16, v76
	v_lshlrev_b32_e32 v18, 16, v17
	v_sub_f32_e32 v13, v16, v62
	v_pk_mul_f32 v[14:15], v[14:15], v[18:19]
	s_waitcnt vmcnt(12)
	v_lshlrev_b32_e32 v19, 16, v78
	v_lshlrev_b32_e32 v18, 16, v77
	v_mul_f32_e32 v13, 0x3fb8aa3b, v13
	v_pk_mul_f32 v[20:21], v[20:21], v[18:19]
	v_exp_f32_e32 v18, v13
	v_sub_f32_e32 v13, v16, v63
	v_mul_f32_e32 v13, 0x3fb8aa3b, v13
	v_exp_f32_e32 v19, v13
	v_sub_f32_e32 v13, v16, v64
	v_mul_f32_e32 v13, 0x3fb8aa3b, v13
	v_exp_f32_e32 v24, v13
	v_sub_f32_e32 v13, v16, v65
	v_mul_f32_e32 v13, 0x3fb8aa3b, v13
	v_exp_f32_e32 v25, v13
	s_waitcnt vmcnt(10)
	v_lshlrev_b32_e32 v23, 16, v80
	v_lshlrev_b32_e32 v22, 16, v79
	v_pk_mul_f32 v[22:23], v[18:19], v[22:23]
	s_waitcnt vmcnt(8)
	v_lshlrev_b32_e32 v19, 16, v50
	v_lshlrev_b32_e32 v18, 16, v81
	v_pk_mul_f32 v[24:25], v[24:25], v[18:19]
	v_cvt_pk_bf16_f32 v18, v14, v15
	v_cvt_pk_bf16_f32 v19, v20, v21
	v_cvt_pk_bf16_f32 v20, v22, v23
	v_cvt_pk_bf16_f32 v21, v24, v25
	v_sub_f32_e32 v13, v16, v68
	ds_write_b128 v37, v[18:21] offset:32
	v_mul_f32_e32 v13, 0x3fb8aa3b, v13
	s_waitcnt vmcnt(7)
	v_lshlrev_b32_e32 v19, 16, v2
	v_sub_f32_e32 v2, v16, v70
	v_exp_f32_e32 v14, v13
	v_sub_f32_e32 v13, v16, v69
	v_mul_f32_e32 v2, 0x3fb8aa3b, v2
	v_mul_f32_e32 v13, 0x3fb8aa3b, v13
	v_exp_f32_e32 v20, v2
	v_sub_f32_e32 v2, v16, v71
	v_exp_f32_e32 v15, v13
	v_mul_f32_e32 v2, 0x3fb8aa3b, v2
	v_exp_f32_e32 v21, v2
	s_waitcnt vmcnt(0)
	v_lshlrev_b32_e32 v18, 16, v44
	v_sub_f32_e32 v2, v16, v72
	v_pk_mul_f32 v[14:15], v[14:15], v[18:19]
	v_lshlrev_b32_e32 v19, 16, v27
	v_lshlrev_b32_e32 v18, 16, v26
	v_mul_f32_e32 v2, 0x3fb8aa3b, v2
	v_pk_mul_f32 v[20:21], v[20:21], v[18:19]
	v_exp_f32_e32 v18, v2
	v_sub_f32_e32 v2, v16, v73
	v_mul_f32_e32 v2, 0x3fb8aa3b, v2
	v_exp_f32_e32 v19, v2
	v_sub_f32_e32 v2, v16, v74
	v_mul_f32_e32 v2, 0x3fb8aa3b, v2
	v_exp_f32_e32 v24, v2
	v_sub_f32_e32 v2, v16, v75
	v_mul_f32_e32 v2, 0x3fb8aa3b, v2
	v_exp_f32_e32 v25, v2
	v_lshlrev_b32_e32 v23, 16, v29
	v_lshlrev_b32_e32 v22, 16, v28
	v_pk_mul_f32 v[22:23], v[18:19], v[22:23]
	v_lshlrev_b32_e32 v19, 16, v43
	v_lshlrev_b32_e32 v18, 16, v42
	v_pk_mul_f32 v[24:25], v[24:25], v[18:19]
	v_cvt_pk_bf16_f32 v18, v14, v15
	v_cvt_pk_bf16_f32 v19, v20, v21
	v_cvt_pk_bf16_f32 v20, v22, v23
	v_cvt_pk_bf16_f32 v21, v24, v25
	ds_write_b128 v37, v[18:21] offset:48
	s_and_saveexec_b64 s[0:1], vcc
	s_cbranch_execz .LBB0_340
; __device__ __forceinline__ void gla_a1(const Ctx& X, KArgs a, float* kvt, float* decb) {
;     ...
;           if (seg == 0) decb[unit * 128 + d] = __expf(tot); }
	v_mul_f32_e32 v2, 0x3fb8aa3b, v16
	v_exp_f32_e32 v2, v2
	v_add_u32_e32 v14, s3, v32
	v_ashrrev_i32_e32 v15, 31, v14
	v_lshl_add_u64 v[14:15], v[14:15], 2, s[16:17]
	global_store_dword v[14:15], v2, off
	s_branch .LBB0_340

; #define LAS __attribute__((address_space(3)))
; __device__ __forceinline__ void gla_bcum(KArgs a, int tid, int t0, int h, LAS float* segtot, LAS float* glrs, float (&bc)[32], float& tot) {
;     const int d = tid & 127, seg = __builtin_amdgcn_readfirstlane(tid >> 7), col = h * 128 + d;
;     const float* glr = (const float*)(a->ws + WS_GLR);
;     float w2r[16];
; #pragma unroll
;     for (int j = 0; j < 16; ++j) w2r[j] = a->gate_w2[j * 512 + col];
;     const float bias = a->gate_b[col];
;     *(LAS f32x4*)(glrs + tid * 4) = *(const f32x4*)(glr + (size_t)t0 * 16 + tid * 4);
;     __syncthreads();
;     float run = 0.f;
; #pragma unroll
;     for (int r = 0; r < 32; ++r) { const LAS f32x4* gp = (const LAS f32x4*)(glrs + (seg * 32 + r) * 16);
;         float z = bias;
; #pragma unroll
;         for (int q = 0; q < 4; ++q) { const f32x4 g = gp[q]; z += g[0] * w2r[4 * q] + g[1] * w2r[4 * q + 1] + g[2] * w2r[4 * q + 2] + g[3] * w2r[4 * q + 3]; }
;         const float la = (fminf(z, 0.f) - __logf(1.0f + __expf(-fabsf(z)))) * (1.0f / 16.0f);
;         run += la; bc[r] = run; }
.LBB0_478:
	s_bfe_u32 s1, s42, 0x20005
	s_lshl_b32 s8, s1, 9
	v_lshl_or_b32 v0, v88, 2, s8
	v_lshl_add_u64 v[16:17], s[16:17], 0, v[0:1]
	v_add_co_u32_e32 v18, vcc, s25, v16
	s_and_b32 s0, s42, 31
	s_nop 0
	v_addc_co_u32_e32 v19, vcc, 0, v17, vcc
	v_add_co_u32_e32 v2, vcc, s26, v16
	s_lshl_b32 s6, s42, 5
	s_nop 0
	v_addc_co_u32_e32 v3, vcc, 0, v17, vcc
	v_add_co_u32_e32 v24, vcc, s27, v16
	s_and_b32 s6, s6, 0xfffff000
	s_lshl_b32 s7, s0, 7
	v_addc_co_u32_e32 v25, vcc, 0, v17, vcc
	s_or_b32 s44, s6, s7
	v_add_co_u32_e32 v4, vcc, s28, v16
	s_ashr_i32 s45, s44, 31
	s_nop 0
	v_addc_co_u32_e32 v5, vcc, 0, v17, vcc
	s_lshl_b64 s[6:7], s[44:45], 6
	v_add_co_u32_e32 v26, vcc, s30, v16
	v_lshl_add_u64 v[6:7], v[90:91], 0, s[6:7]
	s_nop 0
	v_addc_co_u32_e32 v27, vcc, 0, v17, vcc
	s_barrier
	global_load_dwordx4 v[20:23], v[6:7], off
	global_load_dword v12, v0, s[16:17]
	global_load_dword v15, v0, s[16:17] offset:2048
	global_load_dword v14, v[2:3], off offset:-4096
	global_load_dword v11, v[2:3], off
	global_load_dword v13, v[2:3], off offset:2048
	global_load_dword v9, v[4:5], off offset:-4096
	s_nop 0
	global_load_dword v3, v[4:5], off
	global_load_dword v7, v[4:5], off offset:2048
	s_nop 0
	global_load_dword v5, v[26:27], off offset:-4096
	global_load_dword v2, v[26:27], off
	global_load_dword v4, v[26:27], off offset:2048
	v_add_co_u32_e32 v26, vcc, s29, v16
	v_readfirstlane_b32 s36, v84
	s_nop 0
	v_addc_co_u32_e32 v27, vcc, 0, v17, vcc
	v_add_co_u32_e32 v28, vcc, s31, v16
	s_ashr_i32 s9, s36, 7
	s_nop 0
	v_addc_co_u32_e32 v29, vcc, 0, v17, vcc
	global_load_dword v6, v[28:29], off
	global_load_dword v17, v[18:19], off offset:2048
	global_load_dword v16, v[24:25], off offset:2048
	global_load_dword v10, v[26:27], off offset:2048
	global_load_dword v8, v[28:29], off offset:2048
	s_nop 0
	global_load_dword v19, v0, s[18:19]
	s_lshl_b32 s6, s9, 11
	s_add_i32 s6, s6, 0
	s_add_i32 s6, s6, 0x11000
	v_mov_b32_e32 v0, s6
	v_mov_b32_e32 v111, v1
	s_waitcnt vmcnt(17)
	ds_write_b128 v117, v[20:23]
	s_waitcnt lgkmcnt(0)
	s_barrier
	ds_read_b128 v[20:23], v0
	ds_read_b128 v[24:27], v0 offset:16
	ds_read_b128 v[28:31], v0 offset:32
	ds_read_b128 v[32:35], v0 offset:48
	ds_read_b128 v[36:39], v0 offset:64
	ds_read_b128 v[40:43], v0 offset:80
	s_waitcnt vmcnt(15) lgkmcnt(5)
	v_mul_f32_e32 v18, v15, v21
	s_waitcnt vmcnt(12) lgkmcnt(4)
	v_mul_f32_e32 v21, v13, v25
	v_fmac_f32_e32 v18, v12, v20
	s_waitcnt vmcnt(9) lgkmcnt(3)
	v_mul_f32_e32 v25, v7, v29
	v_fmac_f32_e32 v21, v11, v24
	v_fmac_f32_e32 v18, v14, v22
	s_waitcnt vmcnt(6) lgkmcnt(2)
	v_mul_f32_e32 v29, v4, v33
	v_fmac_f32_e32 v25, v3, v28
	v_fmac_f32_e32 v21, v9, v26
	v_fmac_f32_e32 v29, v2, v32
	s_waitcnt vmcnt(4)
	v_fmac_f32_e32 v18, v17, v23
	v_fmac_f32_e32 v25, v5, v30
	s_waitcnt vmcnt(3)
	v_fmac_f32_e32 v21, v16, v27
	v_fmac_f32_e32 v29, v6, v34
	s_waitcnt vmcnt(0)
	v_add_f32_e32 v18, v19, v18
	v_fmac_f32_e32 v25, v10, v31
	v_add_f32_e32 v18, v18, v21
	v_fmac_f32_e32 v29, v8, v35
	v_add_f32_e32 v18, v18, v25
	v_add_f32_e32 v18, v18, v29
	v_mul_f32_e64 v20, |v18|, s33
	v_exp_f32_e32 v20, v20
	s_waitcnt lgkmcnt(1)
	v_mul_f32_e32 v33, v15, v37
	s_waitcnt lgkmcnt(0)
	v_mul_f32_e32 v24, v13, v41
	v_fmac_f32_e32 v33, v12, v36
	v_add_f32_e32 v20, 1.0, v20
	v_fmac_f32_e32 v33, v14, v38
	v_fmac_f32_e32 v24, v11, v40
	v_log_f32_e32 v28, v20
	v_fmac_f32_e32 v33, v17, v39
	v_fmac_f32_e32 v24, v9, v42
	v_add_f32_e32 v25, v19, v33
	v_mul_f32_e32 v20, 0x3f317217, v28
	v_fma_f32 v29, v28, s35, -v20
	ds_read_b128 v[20:23], v0 offset:96
	v_fmac_f32_e32 v24, v16, v43
	v_add_f32_e32 v30, v25, v24
	ds_read_b128 v[24:27], v0 offset:112
	v_fmac_f32_e32 v29, 0x3377d1cf, v28
	s_waitcnt lgkmcnt(1)
	v_mul_f32_e32 v21, v7, v21
	v_fmac_f32_e32 v21, v3, v20
	v_fmac_f32_e32 v21, v5, v22
	v_fmac_f32_e32 v21, v10, v23
	v_add_f32_e32 v20, v30, v21
	s_waitcnt lgkmcnt(0)
	v_mul_f32_e32 v21, v4, v25
	v_fmac_f32_e32 v21, v2, v24
	v_fmac_f32_e32 v21, v6, v26
	v_fmac_f32_e32 v21, v8, v27
	v_add_f32_e32 v20, v20, v21
	v_mul_f32_e64 v21, |v20|, s33
	v_exp_f32_e32 v21, v21
	v_fmac_f32_e32 v29, 0x3f317217, v28
	v_add_f32_e32 v21, 1.0, v21
	v_mov_b32_e32 v22, v29
	v_min_f32_e32 v18, 0, v18
	v_log_f32_e32 v28, v21
	v_sub_f32_e32 v18, v18, v22
	v_min_f32_e32 v29, 0, v20
	ds_read_b128 v[20:23], v0 offset:128
	v_mul_f32_e32 v24, 0x3f317217, v28
	v_fma_f32 v30, v28, s35, -v24
	ds_read_b128 v[24:27], v0 offset:144
	v_fmac_f32_e32 v30, 0x3377d1cf, v28
	s_waitcnt lgkmcnt(1)
	v_mul_f32_e32 v21, v15, v21
	v_fmac_f32_e32 v21, v12, v20
	v_fmac_f32_e32 v21, v14, v22
	v_fmac_f32_e32 v21, v17, v23
	v_add_f32_e32 v31, v19, v21
	s_waitcnt lgkmcnt(0)
	v_mul_f32_e32 v25, v13, v25
	ds_read_b128 v[20:23], v0 offset:160
	v_fmac_f32_e32 v25, v11, v24
	v_fmac_f32_e32 v25, v9, v26
	v_fmac_f32_e32 v25, v16, v27
	v_add_f32_e32 v31, v31, v25
	ds_read_b128 v[24:27], v0 offset:176
	s_waitcnt lgkmcnt(1)
	v_mul_f32_e32 v21, v7, v21
	v_fmac_f32_e32 v21, v3, v20
	v_fmac_f32_e32 v21, v5, v22
	v_fmac_f32_e32 v21, v10, v23
	v_add_f32_e32 v20, v31, v21
	s_waitcnt lgkmcnt(0)
	v_mul_f32_e32 v21, v4, v25
	v_fmac_f32_e32 v21, v2, v24
	v_fmac_f32_e32 v21, v6, v26
	v_fmac_f32_e32 v21, v8, v27
	v_add_f32_e32 v21, v20, v21
	v_mul_f32_e64 v20, |v21|, s33
	v_exp_f32_e32 v20, v20
	v_fmac_f32_e32 v30, 0x3f317217, v28
	v_add_f32_e32 v20, 1.0, v20
	v_mov_b32_e32 v22, v30
	v_min_f32_e32 v21, 0, v21
	v_log_f32_e32 v30, v20
	v_sub_f32_e32 v20, v29, v22
	ds_read_b128 v[22:25], v0 offset:192
	v_fma_f32 v18, v18, s47, 0
	v_mul_f32_e32 v26, 0x3f317217, v30
	v_fma_f32 v31, v30, s35, -v26
	ds_read_b128 v[26:29], v0 offset:208
	s_waitcnt lgkmcnt(1)
; #define LAS __attribute__((address_space(3)))
; __device__ __forceinline__ void gla_bcum(KArgs a, int tid, int t0, int h, LAS float* segtot, LAS float* glrs, float (&bc)[32], float& tot) {
;     ...
;     for (int r = 0; r < 32; ++r) { const LAS f32x4* gp = (const LAS f32x4*)(glrs + (seg * 32 + r) * 16);
;         float z = bias;
; #pragma unroll
;         for (int q = 0; q < 4; ++q) { const f32x4 g = gp[q]; z += g[0] * w2r[4 * q] + g[1] * w2r[4 * q + 1] + g[2] * w2r[4 * q + 2] + g[3] * w2r[4 * q + 3]; }
;         const float la = (fminf(z, 0.f) - __logf(1.0f + __expf(-fabsf(z)))) * (1.0f / 16.0f);
;         run += la; bc[r] = run; }
	v_mul_f32_e32 v23, v15, v23
	v_fmac_f32_e32 v23, v12, v22
	v_fmac_f32_e32 v23, v14, v24
	v_fmac_f32_e32 v23, v17, v25
	v_add_f32_e32 v32, v19, v23
	s_waitcnt lgkmcnt(0)
	v_mul_f32_e32 v27, v13, v27
	ds_read_b128 v[22:25], v0 offset:224
	v_fmac_f32_e32 v27, v11, v26
	v_fmac_f32_e32 v27, v9, v28
	v_fmac_f32_e32 v27, v16, v29
	v_add_f32_e32 v32, v32, v27
	ds_read_b128 v[26:29], v0 offset:240
	s_waitcnt lgkmcnt(1)
	v_mul_f32_e32 v23, v7, v23
	v_fmac_f32_e32 v23, v3, v22
	v_fmac_f32_e32 v23, v5, v24
	v_fmac_f32_e32 v23, v10, v25
	v_add_f32_e32 v22, v32, v23
	s_waitcnt lgkmcnt(0)
	v_mul_f32_e32 v23, v4, v27
	v_fmac_f32_e32 v23, v2, v26
	v_fmac_f32_e32 v23, v6, v28
	v_fmac_f32_e32 v23, v8, v29
	v_add_f32_e32 v22, v22, v23
	v_mul_f32_e64 v23, |v22|, s33
	v_exp_f32_e32 v23, v23
	v_fmac_f32_e32 v31, 0x3377d1cf, v30
	v_fmac_f32_e32 v31, 0x3f317217, v30
	v_add_f32_e32 v23, 1.0, v23
	v_mov_b32_e32 v24, v31
	v_sub_f32_e32 v21, v21, v24
	v_log_f32_e32 v30, v23
	v_min_f32_e32 v31, 0, v22
	ds_read_b128 v[22:25], v0 offset:256
	v_fmamk_f32 v20, v20, 0x3d800000, v18
	v_mul_f32_e32 v26, 0x3f317217, v30
	v_fma_f32 v32, v30, s35, -v26
	ds_read_b128 v[26:29], v0 offset:272
	s_waitcnt lgkmcnt(1)
	v_mul_f32_e32 v23, v15, v23
	v_fmac_f32_e32 v23, v12, v22
	v_fmac_f32_e32 v23, v14, v24
	v_fmac_f32_e32 v23, v17, v25
	v_add_f32_e32 v33, v19, v23
	s_waitcnt lgkmcnt(0)
	v_mul_f32_e32 v27, v13, v27
	ds_read_b128 v[22:25], v0 offset:288
	v_fmac_f32_e32 v27, v11, v26
	v_fmac_f32_e32 v27, v9, v28
	v_fmac_f32_e32 v27, v16, v29
	v_add_f32_e32 v33, v33, v27
	ds_read_b128 v[26:29], v0 offset:304
	s_waitcnt lgkmcnt(1)
	v_mul_f32_e32 v23, v7, v23
	v_fmac_f32_e32 v23, v3, v22
	v_fmac_f32_e32 v23, v5, v24
	v_fmac_f32_e32 v23, v10, v25
	v_add_f32_e32 v22, v33, v23
	s_waitcnt lgkmcnt(0)
	v_mul_f32_e32 v23, v4, v27
	v_fmac_f32_e32 v23, v2, v26
	v_fmac_f32_e32 v23, v6, v28
	v_fmac_f32_e32 v23, v8, v29
	v_add_f32_e32 v23, v22, v23
	v_mul_f32_e64 v22, |v23|, s33
	v_exp_f32_e32 v22, v22
	v_fmac_f32_e32 v32, 0x3377d1cf, v30
	v_fmac_f32_e32 v32, 0x3f317217, v30
	v_add_f32_e32 v22, 1.0, v22
	v_mov_b32_e32 v24, v32
	v_min_f32_e32 v23, 0, v23
	v_log_f32_e32 v32, v22
	v_sub_f32_e32 v22, v31, v24
	ds_read_b128 v[24:27], v0 offset:320
	v_fmamk_f32 v21, v21, 0x3d800000, v20
	v_mul_f32_e32 v28, 0x3f317217, v32
	v_fma_f32 v33, v32, s35, -v28
	ds_read_b128 v[28:31], v0 offset:336
	s_waitcnt lgkmcnt(1)
	v_mul_f32_e32 v25, v15, v25
	v_fmac_f32_e32 v25, v12, v24
	v_fmac_f32_e32 v25, v14, v26
	v_fmac_f32_e32 v25, v17, v27
	v_add_f32_e32 v34, v19, v25
	s_waitcnt lgkmcnt(0)
	v_mul_f32_e32 v29, v13, v29
	ds_read_b128 v[24:27], v0 offset:352
	v_fmac_f32_e32 v29, v11, v28
	v_fmac_f32_e32 v29, v9, v30
	v_fmac_f32_e32 v29, v16, v31
	v_add_f32_e32 v34, v34, v29
	ds_read_b128 v[28:31], v0 offset:368
	s_waitcnt lgkmcnt(1)
	v_mul_f32_e32 v25, v7, v25
	v_fmac_f32_e32 v25, v3, v24
	v_fmac_f32_e32 v25, v5, v26
	v_fmac_f32_e32 v25, v10, v27
	v_add_f32_e32 v24, v34, v25
	s_waitcnt lgkmcnt(0)
	v_mul_f32_e32 v25, v4, v29
	v_fmac_f32_e32 v25, v2, v28
	v_fmac_f32_e32 v25, v6, v30
	v_fmac_f32_e32 v25, v8, v31
	v_add_f32_e32 v24, v24, v25
	v_mul_f32_e64 v25, |v24|, s33
	v_exp_f32_e32 v25, v25
	v_fmac_f32_e32 v33, 0x3377d1cf, v32
	v_fmac_f32_e32 v33, 0x3f317217, v32
	v_add_f32_e32 v25, 1.0, v25
	v_mov_b32_e32 v26, v33
	v_sub_f32_e32 v23, v23, v26
	v_log_f32_e32 v32, v25
	v_min_f32_e32 v33, 0, v24
	ds_read_b128 v[24:27], v0 offset:384
	v_fmamk_f32 v22, v22, 0x3d800000, v21
	v_mul_f32_e32 v28, 0x3f317217, v32
	v_fma_f32 v34, v32, s35, -v28
	ds_read_b128 v[28:31], v0 offset:400
	s_waitcnt lgkmcnt(1)
	v_mul_f32_e32 v25, v15, v25
	v_fmac_f32_e32 v25, v12, v24
	v_fmac_f32_e32 v25, v14, v26
	v_fmac_f32_e32 v25, v17, v27
	v_add_f32_e32 v35, v19, v25
	s_waitcnt lgkmcnt(0)
	v_mul_f32_e32 v29, v13, v29
	ds_read_b128 v[24:27], v0 offset:416
	v_fmac_f32_e32 v29, v11, v28
	v_fmac_f32_e32 v29, v9, v30
	v_fmac_f32_e32 v29, v16, v31
	v_add_f32_e32 v35, v35, v29
	ds_read_b128 v[28:31], v0 offset:432
	s_waitcnt lgkmcnt(1)
	v_mul_f32_e32 v25, v7, v25
	v_fmac_f32_e32 v25, v3, v24
	v_fmac_f32_e32 v25, v5, v26
	v_fmac_f32_e32 v25, v10, v27
	v_add_f32_e32 v24, v35, v25
	s_waitcnt lgkmcnt(0)
	v_mul_f32_e32 v25, v4, v29
	v_fmac_f32_e32 v25, v2, v28
	v_fmac_f32_e32 v25, v6, v30
	v_fmac_f32_e32 v25, v8, v31
	v_add_f32_e32 v25, v24, v25
	v_mul_f32_e64 v24, |v25|, s33
	v_exp_f32_e32 v24, v24
	v_fmac_f32_e32 v34, 0x3377d1cf, v32
	v_fmac_f32_e32 v34, 0x3f317217, v32
	v_add_f32_e32 v24, 1.0, v24
	v_mov_b32_e32 v26, v34
	v_min_f32_e32 v25, 0, v25
	v_log_f32_e32 v34, v24
	v_sub_f32_e32 v24, v33, v26
	ds_read_b128 v[26:29], v0 offset:448
	v_fmamk_f32 v23, v23, 0x3d800000, v22
	v_mul_f32_e32 v30, 0x3f317217, v34
	v_fma_f32 v35, v34, s35, -v30
	ds_read_b128 v[30:33], v0 offset:464
	s_waitcnt lgkmcnt(1)
	v_mul_f32_e32 v27, v15, v27
	v_fmac_f32_e32 v27, v12, v26
	v_fmac_f32_e32 v27, v14, v28
	v_fmac_f32_e32 v27, v17, v29
	v_add_f32_e32 v36, v19, v27
	s_waitcnt lgkmcnt(0)
	v_mul_f32_e32 v31, v13, v31
	ds_read_b128 v[26:29], v0 offset:480
	v_fmac_f32_e32 v31, v11, v30
	v_fmac_f32_e32 v31, v9, v32
	v_fmac_f32_e32 v31, v16, v33
	v_add_f32_e32 v36, v36, v31
	ds_read_b128 v[30:33], v0 offset:496
	s_waitcnt lgkmcnt(1)
	v_mul_f32_e32 v27, v7, v27
	v_fmac_f32_e32 v27, v3, v26
	v_fmac_f32_e32 v27, v5, v28
	v_fmac_f32_e32 v27, v10, v29
	v_add_f32_e32 v26, v36, v27
	s_waitcnt lgkmcnt(0)
; #define LAS __attribute__((address_space(3)))
; __device__ __forceinline__ void gla_bcum(KArgs a, int tid, int t0, int h, LAS float* segtot, LAS float* glrs, float (&bc)[32], float& tot) {
;     ...
;     float run = 0.f;
; #pragma unroll
;     for (int r = 0; r < 32; ++r) { const LAS f32x4* gp = (const LAS f32x4*)(glrs + (seg * 32 + r) * 16);
;         float z = bias;
; #pragma unroll
;         for (int q = 0; q < 4; ++q) { const f32x4 g = gp[q]; z += g[0] * w2r[4 * q] + g[1] * w2r[4 * q + 1] + g[2] * w2r[4 * q + 2] + g[3] * w2r[4 * q + 3]; }
;         const float la = (fminf(z, 0.f) - __logf(1.0f + __expf(-fabsf(z)))) * (1.0f / 16.0f);
;         run += la; bc[r] = run; }
	v_mul_f32_e32 v27, v4, v31
	v_fmac_f32_e32 v27, v2, v30
	v_fmac_f32_e32 v27, v6, v32
	v_fmac_f32_e32 v27, v8, v33
	v_add_f32_e32 v26, v26, v27
	v_mul_f32_e64 v27, |v26|, s33
	v_exp_f32_e32 v27, v27
	v_fmac_f32_e32 v35, 0x3377d1cf, v34
	v_fmac_f32_e32 v35, 0x3f317217, v34
	v_add_f32_e32 v27, 1.0, v27
	v_mov_b32_e32 v28, v35
	v_sub_f32_e32 v25, v25, v28
	v_log_f32_e32 v34, v27
	v_min_f32_e32 v35, 0, v26
	ds_read_b128 v[26:29], v0 offset:512
	v_fmamk_f32 v24, v24, 0x3d800000, v23
	v_mul_f32_e32 v30, 0x3f317217, v34
	v_fma_f32 v36, v34, s35, -v30
	ds_read_b128 v[30:33], v0 offset:528
	s_waitcnt lgkmcnt(1)
	v_mul_f32_e32 v27, v15, v27
	v_fmac_f32_e32 v27, v12, v26
	v_fmac_f32_e32 v27, v14, v28
	v_fmac_f32_e32 v27, v17, v29
	v_add_f32_e32 v37, v19, v27
	s_waitcnt lgkmcnt(0)
	v_mul_f32_e32 v31, v13, v31
	ds_read_b128 v[26:29], v0 offset:544
	v_fmac_f32_e32 v31, v11, v30
	v_fmac_f32_e32 v31, v9, v32
	v_fmac_f32_e32 v31, v16, v33
	v_add_f32_e32 v37, v37, v31
	ds_read_b128 v[30:33], v0 offset:560
	s_waitcnt lgkmcnt(1)
	v_mul_f32_e32 v27, v7, v27
	v_fmac_f32_e32 v27, v3, v26
	v_fmac_f32_e32 v27, v5, v28
	v_fmac_f32_e32 v27, v10, v29
	v_add_f32_e32 v26, v37, v27
	s_waitcnt lgkmcnt(0)
	v_mul_f32_e32 v27, v4, v31
	v_fmac_f32_e32 v27, v2, v30
	v_fmac_f32_e32 v27, v6, v32
	v_fmac_f32_e32 v27, v8, v33
	v_add_f32_e32 v27, v26, v27
	v_mul_f32_e64 v26, |v27|, s33
	v_exp_f32_e32 v26, v26
	v_fmac_f32_e32 v36, 0x3377d1cf, v34
	v_fmac_f32_e32 v36, 0x3f317217, v34
	v_add_f32_e32 v26, 1.0, v26
	v_mov_b32_e32 v28, v36
	v_min_f32_e32 v27, 0, v27
	v_log_f32_e32 v36, v26
	v_sub_f32_e32 v26, v35, v28
	ds_read_b128 v[28:31], v0 offset:576
	v_fmamk_f32 v25, v25, 0x3d800000, v24
	v_mul_f32_e32 v32, 0x3f317217, v36
	v_fma_f32 v37, v36, s35, -v32
	ds_read_b128 v[32:35], v0 offset:592
	s_waitcnt lgkmcnt(1)
	v_mul_f32_e32 v29, v15, v29
	v_fmac_f32_e32 v29, v12, v28
	v_fmac_f32_e32 v29, v14, v30
	v_fmac_f32_e32 v29, v17, v31
	v_add_f32_e32 v38, v19, v29
	s_waitcnt lgkmcnt(0)
	v_mul_f32_e32 v33, v13, v33
	ds_read_b128 v[28:31], v0 offset:608
	v_fmac_f32_e32 v33, v11, v32
	v_fmac_f32_e32 v33, v9, v34
	v_fmac_f32_e32 v33, v16, v35
	v_add_f32_e32 v38, v38, v33
	ds_read_b128 v[32:35], v0 offset:624
	s_waitcnt lgkmcnt(1)
	v_mul_f32_e32 v29, v7, v29
	v_fmac_f32_e32 v29, v3, v28
	v_fmac_f32_e32 v29, v5, v30
	v_fmac_f32_e32 v29, v10, v31
	v_add_f32_e32 v28, v38, v29
	s_waitcnt lgkmcnt(0)
	v_mul_f32_e32 v29, v4, v33
	v_fmac_f32_e32 v29, v2, v32
	v_fmac_f32_e32 v29, v6, v34
	v_fmac_f32_e32 v29, v8, v35
	v_add_f32_e32 v28, v28, v29
	v_mul_f32_e64 v29, |v28|, s33
	v_exp_f32_e32 v29, v29
	v_fmac_f32_e32 v37, 0x3377d1cf, v36
	v_fmac_f32_e32 v37, 0x3f317217, v36
	v_add_f32_e32 v29, 1.0, v29
	v_mov_b32_e32 v30, v37
	v_sub_f32_e32 v27, v27, v30
	v_log_f32_e32 v36, v29
	v_min_f32_e32 v37, 0, v28
	ds_read_b128 v[28:31], v0 offset:640
	v_fmamk_f32 v26, v26, 0x3d800000, v25
	v_mul_f32_e32 v32, 0x3f317217, v36
	v_fma_f32 v38, v36, s35, -v32
	ds_read_b128 v[32:35], v0 offset:656
	s_waitcnt lgkmcnt(1)
	v_mul_f32_e32 v29, v15, v29
	v_fmac_f32_e32 v29, v12, v28
	v_fmac_f32_e32 v29, v14, v30
	v_fmac_f32_e32 v29, v17, v31
	v_add_f32_e32 v39, v19, v29
	s_waitcnt lgkmcnt(0)
	v_mul_f32_e32 v33, v13, v33
	ds_read_b128 v[28:31], v0 offset:672
	v_fmac_f32_e32 v33, v11, v32
	v_fmac_f32_e32 v33, v9, v34
	v_fmac_f32_e32 v33, v16, v35
	v_add_f32_e32 v39, v39, v33
	ds_read_b128 v[32:35], v0 offset:688
	s_waitcnt lgkmcnt(1)
	v_mul_f32_e32 v29, v7, v29
	v_fmac_f32_e32 v29, v3, v28
	v_fmac_f32_e32 v29, v5, v30
	v_fmac_f32_e32 v29, v10, v31
	v_add_f32_e32 v28, v39, v29
	s_waitcnt lgkmcnt(0)
	v_mul_f32_e32 v29, v4, v33
	v_fmac_f32_e32 v29, v2, v32
	v_fmac_f32_e32 v29, v6, v34
	v_fmac_f32_e32 v29, v8, v35
	v_add_f32_e32 v29, v28, v29
	v_mul_f32_e64 v28, |v29|, s33
	v_exp_f32_e32 v28, v28
	v_fmac_f32_e32 v38, 0x3377d1cf, v36
	v_fmac_f32_e32 v38, 0x3f317217, v36
	v_add_f32_e32 v28, 1.0, v28
	v_mov_b32_e32 v30, v38
	v_min_f32_e32 v29, 0, v29
	v_log_f32_e32 v38, v28
	v_sub_f32_e32 v28, v37, v30
	ds_read_b128 v[30:33], v0 offset:704
	v_fmamk_f32 v27, v27, 0x3d800000, v26
	v_mul_f32_e32 v34, 0x3f317217, v38
	v_fma_f32 v39, v38, s35, -v34
	ds_read_b128 v[34:37], v0 offset:720
	s_waitcnt lgkmcnt(1)
	v_mul_f32_e32 v31, v15, v31
	v_fmac_f32_e32 v31, v12, v30
	v_fmac_f32_e32 v31, v14, v32
	v_fmac_f32_e32 v31, v17, v33
	v_add_f32_e32 v40, v19, v31
	s_waitcnt lgkmcnt(0)
	v_mul_f32_e32 v35, v13, v35
	ds_read_b128 v[30:33], v0 offset:736
	v_fmac_f32_e32 v35, v11, v34
	v_fmac_f32_e32 v35, v9, v36
	v_fmac_f32_e32 v35, v16, v37
	v_add_f32_e32 v40, v40, v35
	ds_read_b128 v[34:37], v0 offset:752
	s_waitcnt lgkmcnt(1)
	v_mul_f32_e32 v31, v7, v31
	v_fmac_f32_e32 v31, v3, v30
	v_fmac_f32_e32 v31, v5, v32
	v_fmac_f32_e32 v31, v10, v33
	v_add_f32_e32 v30, v40, v31
	s_waitcnt lgkmcnt(0)
	v_mul_f32_e32 v31, v4, v35
	v_fmac_f32_e32 v31, v2, v34
	v_fmac_f32_e32 v31, v6, v36
	v_fmac_f32_e32 v31, v8, v37
	v_add_f32_e32 v30, v30, v31
	v_mul_f32_e64 v31, |v30|, s33
	v_exp_f32_e32 v31, v31
	v_fmac_f32_e32 v39, 0x3377d1cf, v38
	v_fmac_f32_e32 v39, 0x3f317217, v38
	v_add_f32_e32 v31, 1.0, v31
	v_mov_b32_e32 v32, v39
	v_sub_f32_e32 v29, v29, v32
	v_log_f32_e32 v38, v31
	v_min_f32_e32 v39, 0, v30
	ds_read_b128 v[30:33], v0 offset:768
	v_fmamk_f32 v28, v28, 0x3d800000, v27
	v_mul_f32_e32 v34, 0x3f317217, v38
	v_fma_f32 v40, v38, s35, -v34
	ds_read_b128 v[34:37], v0 offset:784
	s_waitcnt lgkmcnt(1)
	v_mul_f32_e32 v31, v15, v31
	v_fmac_f32_e32 v31, v12, v30
	v_fmac_f32_e32 v31, v14, v32
	v_fmac_f32_e32 v31, v17, v33
	v_add_f32_e32 v41, v19, v31
	s_waitcnt lgkmcnt(0)
; #define LAS __attribute__((address_space(3)))
; __device__ __forceinline__ void gla_bcum(KArgs a, int tid, int t0, int h, LAS float* segtot, LAS float* glrs, float (&bc)[32], float& tot) {
;     ...
;     float run = 0.f;
; #pragma unroll
;     for (int r = 0; r < 32; ++r) { const LAS f32x4* gp = (const LAS f32x4*)(glrs + (seg * 32 + r) * 16);
;         float z = bias;
; #pragma unroll
;         for (int q = 0; q < 4; ++q) { const f32x4 g = gp[q]; z += g[0] * w2r[4 * q] + g[1] * w2r[4 * q + 1] + g[2] * w2r[4 * q + 2] + g[3] * w2r[4 * q + 3]; }
;         const float la = (fminf(z, 0.f) - __logf(1.0f + __expf(-fabsf(z)))) * (1.0f / 16.0f);
;         run += la; bc[r] = run; }
	v_mul_f32_e32 v35, v13, v35
	ds_read_b128 v[30:33], v0 offset:800
	v_fmac_f32_e32 v35, v11, v34
	v_fmac_f32_e32 v35, v9, v36
	v_fmac_f32_e32 v35, v16, v37
	v_add_f32_e32 v41, v41, v35
	ds_read_b128 v[34:37], v0 offset:816
	s_waitcnt lgkmcnt(1)
	v_mul_f32_e32 v31, v7, v31
	v_fmac_f32_e32 v31, v3, v30
	v_fmac_f32_e32 v31, v5, v32
	v_fmac_f32_e32 v31, v10, v33
	v_add_f32_e32 v30, v41, v31
	s_waitcnt lgkmcnt(0)
	v_mul_f32_e32 v31, v4, v35
	v_fmac_f32_e32 v31, v2, v34
	v_fmac_f32_e32 v31, v6, v36
	v_fmac_f32_e32 v31, v8, v37
	v_add_f32_e32 v31, v30, v31
	v_mul_f32_e64 v30, |v31|, s33
	v_exp_f32_e32 v30, v30
	v_fmac_f32_e32 v40, 0x3377d1cf, v38
	v_fmac_f32_e32 v40, 0x3f317217, v38
	v_add_f32_e32 v30, 1.0, v30
	v_mov_b32_e32 v32, v40
	v_min_f32_e32 v31, 0, v31
	v_log_f32_e32 v40, v30
	v_sub_f32_e32 v30, v39, v32
	ds_read_b128 v[32:35], v0 offset:832
	v_fmamk_f32 v29, v29, 0x3d800000, v28
	v_mul_f32_e32 v36, 0x3f317217, v40
	v_fma_f32 v41, v40, s35, -v36
	ds_read_b128 v[36:39], v0 offset:848
	s_waitcnt lgkmcnt(1)
	v_mul_f32_e32 v33, v15, v33
	v_fmac_f32_e32 v33, v12, v32
	v_fmac_f32_e32 v33, v14, v34
	v_fmac_f32_e32 v33, v17, v35
	v_add_f32_e32 v42, v19, v33
	s_waitcnt lgkmcnt(0)
	v_mul_f32_e32 v37, v13, v37
	ds_read_b128 v[32:35], v0 offset:864
	v_fmac_f32_e32 v37, v11, v36
	v_fmac_f32_e32 v37, v9, v38
	v_fmac_f32_e32 v37, v16, v39
	v_add_f32_e32 v42, v42, v37
	ds_read_b128 v[36:39], v0 offset:880
	s_waitcnt lgkmcnt(1)
	v_mul_f32_e32 v33, v7, v33
	v_fmac_f32_e32 v33, v3, v32
	v_fmac_f32_e32 v33, v5, v34
	v_fmac_f32_e32 v33, v10, v35
	v_add_f32_e32 v32, v42, v33
	s_waitcnt lgkmcnt(0)
	v_mul_f32_e32 v33, v4, v37
	v_fmac_f32_e32 v33, v2, v36
	v_fmac_f32_e32 v33, v6, v38
	v_fmac_f32_e32 v33, v8, v39
	v_add_f32_e32 v32, v32, v33
	v_mul_f32_e64 v33, |v32|, s33
	v_exp_f32_e32 v33, v33
	v_fmac_f32_e32 v41, 0x3377d1cf, v40
	v_fmac_f32_e32 v41, 0x3f317217, v40
	v_add_f32_e32 v33, 1.0, v33
	v_mov_b32_e32 v34, v41
	v_sub_f32_e32 v31, v31, v34
	v_log_f32_e32 v40, v33
	v_min_f32_e32 v41, 0, v32
	ds_read_b128 v[32:35], v0 offset:896
	v_fmamk_f32 v30, v30, 0x3d800000, v29
	v_mul_f32_e32 v36, 0x3f317217, v40
	v_fma_f32 v42, v40, s35, -v36
	ds_read_b128 v[36:39], v0 offset:912
	s_waitcnt lgkmcnt(1)
	v_mul_f32_e32 v33, v15, v33
	v_fmac_f32_e32 v33, v12, v32
	v_fmac_f32_e32 v33, v14, v34
	v_fmac_f32_e32 v33, v17, v35
	v_add_f32_e32 v43, v19, v33
	s_waitcnt lgkmcnt(0)
	v_mul_f32_e32 v37, v13, v37
	ds_read_b128 v[32:35], v0 offset:928
	v_fmac_f32_e32 v37, v11, v36
	v_fmac_f32_e32 v37, v9, v38
	v_fmac_f32_e32 v37, v16, v39
	v_add_f32_e32 v43, v43, v37
	ds_read_b128 v[36:39], v0 offset:944
	s_waitcnt lgkmcnt(1)
	v_mul_f32_e32 v33, v7, v33
	v_fmac_f32_e32 v33, v3, v32
	v_fmac_f32_e32 v33, v5, v34
	v_fmac_f32_e32 v33, v10, v35
	v_add_f32_e32 v32, v43, v33
	s_waitcnt lgkmcnt(0)
	v_mul_f32_e32 v33, v4, v37
	v_fmac_f32_e32 v33, v2, v36
	v_fmac_f32_e32 v33, v6, v38
	v_fmac_f32_e32 v33, v8, v39
	v_add_f32_e32 v33, v32, v33
	v_mul_f32_e64 v32, |v33|, s33
	v_exp_f32_e32 v32, v32
	v_fmac_f32_e32 v42, 0x3377d1cf, v40
	v_fmac_f32_e32 v42, 0x3f317217, v40
	v_add_f32_e32 v32, 1.0, v32
	v_mov_b32_e32 v34, v42
	v_min_f32_e32 v33, 0, v33
	v_log_f32_e32 v42, v32
	v_sub_f32_e32 v32, v41, v34
	ds_read_b128 v[34:37], v0 offset:960
	v_fmamk_f32 v31, v31, 0x3d800000, v30
	v_mul_f32_e32 v38, 0x3f317217, v42
	v_fma_f32 v43, v42, s35, -v38
	ds_read_b128 v[38:41], v0 offset:976
	s_waitcnt lgkmcnt(1)
	v_mul_f32_e32 v35, v15, v35
	v_fmac_f32_e32 v35, v12, v34
	v_fmac_f32_e32 v35, v14, v36
	v_fmac_f32_e32 v35, v17, v37
	v_add_f32_e32 v44, v19, v35
	s_waitcnt lgkmcnt(0)
	v_mul_f32_e32 v39, v13, v39
	ds_read_b128 v[34:37], v0 offset:992
	v_fmac_f32_e32 v39, v11, v38
	v_fmac_f32_e32 v39, v9, v40
	v_fmac_f32_e32 v39, v16, v41
	v_add_f32_e32 v44, v44, v39
	ds_read_b128 v[38:41], v0 offset:1008
	s_waitcnt lgkmcnt(1)
	v_mul_f32_e32 v35, v7, v35
	v_fmac_f32_e32 v35, v3, v34
	v_fmac_f32_e32 v35, v5, v36
	v_fmac_f32_e32 v35, v10, v37
	v_add_f32_e32 v34, v44, v35
	s_waitcnt lgkmcnt(0)
	v_mul_f32_e32 v35, v4, v39
	v_fmac_f32_e32 v35, v2, v38
	v_fmac_f32_e32 v35, v6, v40
	v_fmac_f32_e32 v35, v8, v41
	v_add_f32_e32 v34, v34, v35
	v_mul_f32_e64 v35, |v34|, s33
	v_exp_f32_e32 v35, v35
	v_fmac_f32_e32 v43, 0x3377d1cf, v42
	v_fmac_f32_e32 v43, 0x3f317217, v42
	v_add_f32_e32 v35, 1.0, v35
	v_mov_b32_e32 v36, v43
	v_sub_f32_e32 v33, v33, v36
	v_log_f32_e32 v42, v35
	v_min_f32_e32 v43, 0, v34
	ds_read_b128 v[34:37], v0 offset:1024
	v_fmamk_f32 v32, v32, 0x3d800000, v31
	v_mul_f32_e32 v38, 0x3f317217, v42
	v_fma_f32 v44, v42, s35, -v38
	ds_read_b128 v[38:41], v0 offset:1040
	s_waitcnt lgkmcnt(1)
	v_mul_f32_e32 v35, v15, v35
	v_fmac_f32_e32 v35, v12, v34
	v_fmac_f32_e32 v35, v14, v36
	v_fmac_f32_e32 v35, v17, v37
	v_add_f32_e32 v45, v19, v35
	s_waitcnt lgkmcnt(0)
	v_mul_f32_e32 v39, v13, v39
	ds_read_b128 v[34:37], v0 offset:1056
	v_fmac_f32_e32 v39, v11, v38
	v_fmac_f32_e32 v39, v9, v40
	v_fmac_f32_e32 v39, v16, v41
	v_add_f32_e32 v45, v45, v39
	ds_read_b128 v[38:41], v0 offset:1072
	s_waitcnt lgkmcnt(1)
	v_mul_f32_e32 v35, v7, v35
	v_fmac_f32_e32 v35, v3, v34
	v_fmac_f32_e32 v35, v5, v36
	v_fmac_f32_e32 v35, v10, v37
	v_add_f32_e32 v34, v45, v35
	s_waitcnt lgkmcnt(0)
	v_mul_f32_e32 v35, v4, v39
	v_fmac_f32_e32 v35, v2, v38
	v_fmac_f32_e32 v35, v6, v40
	v_fmac_f32_e32 v35, v8, v41
	v_add_f32_e32 v35, v34, v35
	v_mul_f32_e64 v34, |v35|, s33
	v_exp_f32_e32 v34, v34
	v_fmac_f32_e32 v44, 0x3377d1cf, v42
	v_fmac_f32_e32 v44, 0x3f317217, v42
	v_add_f32_e32 v34, 1.0, v34
	v_mov_b32_e32 v36, v44
	v_min_f32_e32 v35, 0, v35
	v_log_f32_e32 v44, v34
	v_sub_f32_e32 v34, v43, v36
	ds_read_b128 v[36:39], v0 offset:1088
	v_fmamk_f32 v33, v33, 0x3d800000, v32
	v_mul_f32_e32 v40, 0x3f317217, v44
	v_fma_f32 v45, v44, s35, -v40
	ds_read_b128 v[40:43], v0 offset:1104
	s_waitcnt lgkmcnt(1)
; #define LAS __attribute__((address_space(3)))
; __device__ __forceinline__ void gla_bcum(KArgs a, int tid, int t0, int h, LAS float* segtot, LAS float* glrs, float (&bc)[32], float& tot) {
;     ...
;     float run = 0.f;
; #pragma unroll
;     for (int r = 0; r < 32; ++r) { const LAS f32x4* gp = (const LAS f32x4*)(glrs + (seg * 32 + r) * 16);
;         float z = bias;
; #pragma unroll
;         for (int q = 0; q < 4; ++q) { const f32x4 g = gp[q]; z += g[0] * w2r[4 * q] + g[1] * w2r[4 * q + 1] + g[2] * w2r[4 * q + 2] + g[3] * w2r[4 * q + 3]; }
;         const float la = (fminf(z, 0.f) - __logf(1.0f + __expf(-fabsf(z)))) * (1.0f / 16.0f);
;         run += la; bc[r] = run; }
	v_mul_f32_e32 v37, v15, v37
	v_fmac_f32_e32 v37, v12, v36
	v_fmac_f32_e32 v37, v14, v38
	v_fmac_f32_e32 v37, v17, v39
	v_add_f32_e32 v46, v19, v37
	s_waitcnt lgkmcnt(0)
	v_mul_f32_e32 v41, v13, v41
	ds_read_b128 v[36:39], v0 offset:1120
	v_fmac_f32_e32 v41, v11, v40
	v_fmac_f32_e32 v41, v9, v42
	v_fmac_f32_e32 v41, v16, v43
	v_add_f32_e32 v46, v46, v41
	ds_read_b128 v[40:43], v0 offset:1136
	s_waitcnt lgkmcnt(1)
	v_mul_f32_e32 v37, v7, v37
	v_fmac_f32_e32 v37, v3, v36
	v_fmac_f32_e32 v37, v5, v38
	v_fmac_f32_e32 v37, v10, v39
	v_add_f32_e32 v36, v46, v37
	s_waitcnt lgkmcnt(0)
	v_mul_f32_e32 v37, v4, v41
	v_fmac_f32_e32 v37, v2, v40
	v_fmac_f32_e32 v37, v6, v42
	v_fmac_f32_e32 v37, v8, v43
	v_add_f32_e32 v36, v36, v37
	v_mul_f32_e64 v37, |v36|, s33
	v_exp_f32_e32 v37, v37
	v_fmac_f32_e32 v45, 0x3377d1cf, v44
	v_fmac_f32_e32 v45, 0x3f317217, v44
	v_add_f32_e32 v37, 1.0, v37
	v_mov_b32_e32 v38, v45
	v_sub_f32_e32 v35, v35, v38
	v_log_f32_e32 v44, v37
	v_min_f32_e32 v45, 0, v36
	ds_read_b128 v[36:39], v0 offset:1152
	v_fmamk_f32 v34, v34, 0x3d800000, v33
	v_mul_f32_e32 v40, 0x3f317217, v44
	v_fma_f32 v46, v44, s35, -v40
	ds_read_b128 v[40:43], v0 offset:1168
	s_waitcnt lgkmcnt(1)
	v_mul_f32_e32 v37, v15, v37
	v_fmac_f32_e32 v37, v12, v36
	v_fmac_f32_e32 v37, v14, v38
	v_fmac_f32_e32 v37, v17, v39
	v_add_f32_e32 v47, v19, v37
	s_waitcnt lgkmcnt(0)
	v_mul_f32_e32 v41, v13, v41
	ds_read_b128 v[36:39], v0 offset:1184
	v_fmac_f32_e32 v41, v11, v40
	v_fmac_f32_e32 v41, v9, v42
	v_fmac_f32_e32 v41, v16, v43
	v_add_f32_e32 v47, v47, v41
	ds_read_b128 v[40:43], v0 offset:1200
	s_waitcnt lgkmcnt(1)
	v_mul_f32_e32 v37, v7, v37
	v_fmac_f32_e32 v37, v3, v36
	v_fmac_f32_e32 v37, v5, v38
	v_fmac_f32_e32 v37, v10, v39
	v_add_f32_e32 v36, v47, v37
	s_waitcnt lgkmcnt(0)
	v_mul_f32_e32 v37, v4, v41
	v_fmac_f32_e32 v37, v2, v40
	v_fmac_f32_e32 v37, v6, v42
	v_fmac_f32_e32 v37, v8, v43
	v_add_f32_e32 v37, v36, v37
	v_mul_f32_e64 v36, |v37|, s33
	v_exp_f32_e32 v36, v36
	v_fmac_f32_e32 v46, 0x3377d1cf, v44
	v_fmac_f32_e32 v46, 0x3f317217, v44
	v_add_f32_e32 v36, 1.0, v36
	v_mov_b32_e32 v38, v46
	v_min_f32_e32 v37, 0, v37
	v_log_f32_e32 v46, v36
	v_sub_f32_e32 v36, v45, v38
	ds_read_b128 v[38:41], v0 offset:1216
	v_fmamk_f32 v35, v35, 0x3d800000, v34
	v_mul_f32_e32 v42, 0x3f317217, v46
	v_fma_f32 v47, v46, s35, -v42
	ds_read_b128 v[42:45], v0 offset:1232
	s_waitcnt lgkmcnt(1)
	v_mul_f32_e32 v39, v15, v39
	v_fmac_f32_e32 v39, v12, v38
	v_fmac_f32_e32 v39, v14, v40
	v_fmac_f32_e32 v39, v17, v41
	v_add_f32_e32 v48, v19, v39
	s_waitcnt lgkmcnt(0)
	v_mul_f32_e32 v43, v13, v43
	ds_read_b128 v[38:41], v0 offset:1248
	v_fmac_f32_e32 v43, v11, v42
	v_fmac_f32_e32 v43, v9, v44
	v_fmac_f32_e32 v43, v16, v45
	v_add_f32_e32 v48, v48, v43
	ds_read_b128 v[42:45], v0 offset:1264
	s_waitcnt lgkmcnt(1)
	v_mul_f32_e32 v39, v7, v39
	v_fmac_f32_e32 v39, v3, v38
	v_fmac_f32_e32 v39, v5, v40
	v_fmac_f32_e32 v39, v10, v41
	v_add_f32_e32 v38, v48, v39
	s_waitcnt lgkmcnt(0)
	v_mul_f32_e32 v39, v4, v43
	v_fmac_f32_e32 v39, v2, v42
	v_fmac_f32_e32 v39, v6, v44
	v_fmac_f32_e32 v39, v8, v45
	v_add_f32_e32 v38, v38, v39
	v_mul_f32_e64 v39, |v38|, s33
	v_exp_f32_e32 v39, v39
	v_fmac_f32_e32 v47, 0x3377d1cf, v46
	v_fmac_f32_e32 v47, 0x3f317217, v46
	v_add_f32_e32 v39, 1.0, v39
	v_mov_b32_e32 v40, v47
	v_sub_f32_e32 v37, v37, v40
	v_log_f32_e32 v46, v39
	v_min_f32_e32 v47, 0, v38
	ds_read_b128 v[38:41], v0 offset:1280
	v_fmamk_f32 v36, v36, 0x3d800000, v35
	v_mul_f32_e32 v42, 0x3f317217, v46
	v_fma_f32 v48, v46, s35, -v42
	ds_read_b128 v[42:45], v0 offset:1296
	s_waitcnt lgkmcnt(1)
	v_mul_f32_e32 v39, v15, v39
	v_fmac_f32_e32 v39, v12, v38
	v_fmac_f32_e32 v39, v14, v40
	v_fmac_f32_e32 v39, v17, v41
	v_add_f32_e32 v49, v19, v39
	s_waitcnt lgkmcnt(0)
	v_mul_f32_e32 v43, v13, v43
	ds_read_b128 v[38:41], v0 offset:1312
	v_fmac_f32_e32 v43, v11, v42
	v_fmac_f32_e32 v43, v9, v44
	v_fmac_f32_e32 v43, v16, v45
	v_add_f32_e32 v49, v49, v43
	ds_read_b128 v[42:45], v0 offset:1328
	s_waitcnt lgkmcnt(1)
	v_mul_f32_e32 v39, v7, v39
	v_fmac_f32_e32 v39, v3, v38
	v_fmac_f32_e32 v39, v5, v40
	v_fmac_f32_e32 v39, v10, v41
	v_add_f32_e32 v38, v49, v39
	s_waitcnt lgkmcnt(0)
	v_mul_f32_e32 v39, v4, v43
	v_fmac_f32_e32 v39, v2, v42
	v_fmac_f32_e32 v39, v6, v44
	v_fmac_f32_e32 v39, v8, v45
	v_add_f32_e32 v39, v38, v39
	v_mul_f32_e64 v38, |v39|, s33
	v_exp_f32_e32 v38, v38
	v_fmac_f32_e32 v48, 0x3377d1cf, v46
	v_fmac_f32_e32 v48, 0x3f317217, v46
	v_add_f32_e32 v38, 1.0, v38
	v_mov_b32_e32 v40, v48
	v_min_f32_e32 v39, 0, v39
	v_log_f32_e32 v48, v38
	v_sub_f32_e32 v38, v47, v40
	ds_read_b128 v[40:43], v0 offset:1344
	v_fmamk_f32 v37, v37, 0x3d800000, v36
	v_mul_f32_e32 v44, 0x3f317217, v48
	v_fma_f32 v49, v48, s35, -v44
	ds_read_b128 v[44:47], v0 offset:1360
	s_waitcnt lgkmcnt(1)
	v_mul_f32_e32 v41, v15, v41
	v_fmac_f32_e32 v41, v12, v40
	v_fmac_f32_e32 v41, v14, v42
	v_fmac_f32_e32 v41, v17, v43
	v_add_f32_e32 v50, v19, v41
	s_waitcnt lgkmcnt(0)
	v_mul_f32_e32 v45, v13, v45
	ds_read_b128 v[40:43], v0 offset:1376
	v_fmac_f32_e32 v45, v11, v44
	v_fmac_f32_e32 v45, v9, v46
	v_fmac_f32_e32 v45, v16, v47
	v_add_f32_e32 v50, v50, v45
	ds_read_b128 v[44:47], v0 offset:1392
	s_waitcnt lgkmcnt(1)
	v_mul_f32_e32 v41, v7, v41
	v_fmac_f32_e32 v41, v3, v40
	v_fmac_f32_e32 v41, v5, v42
	v_fmac_f32_e32 v41, v10, v43
	v_add_f32_e32 v40, v50, v41
	s_waitcnt lgkmcnt(0)
; #define LAS __attribute__((address_space(3)))
; __device__ __forceinline__ void gla_bcum(KArgs a, int tid, int t0, int h, LAS float* segtot, LAS float* glrs, float (&bc)[32], float& tot) {
;     ...
;     float run = 0.f;
; #pragma unroll
;     for (int r = 0; r < 32; ++r) { const LAS f32x4* gp = (const LAS f32x4*)(glrs + (seg * 32 + r) * 16);
;         float z = bias;
; #pragma unroll
;         for (int q = 0; q < 4; ++q) { const f32x4 g = gp[q]; z += g[0] * w2r[4 * q] + g[1] * w2r[4 * q + 1] + g[2] * w2r[4 * q + 2] + g[3] * w2r[4 * q + 3]; }
;         const float la = (fminf(z, 0.f) - __logf(1.0f + __expf(-fabsf(z)))) * (1.0f / 16.0f);
;         run += la; bc[r] = run; }
	v_mul_f32_e32 v41, v4, v45
	v_fmac_f32_e32 v41, v2, v44
	v_fmac_f32_e32 v41, v6, v46
	v_fmac_f32_e32 v41, v8, v47
	v_add_f32_e32 v40, v40, v41
	v_mul_f32_e64 v41, |v40|, s33
	v_exp_f32_e32 v41, v41
	v_fmac_f32_e32 v49, 0x3377d1cf, v48
	v_fmac_f32_e32 v49, 0x3f317217, v48
	v_add_f32_e32 v41, 1.0, v41
	v_mov_b32_e32 v42, v49
	v_sub_f32_e32 v39, v39, v42
	v_log_f32_e32 v48, v41
	v_min_f32_e32 v49, 0, v40
	ds_read_b128 v[40:43], v0 offset:1408
	v_fmamk_f32 v38, v38, 0x3d800000, v37
	v_mul_f32_e32 v44, 0x3f317217, v48
	v_fma_f32 v50, v48, s35, -v44
	ds_read_b128 v[44:47], v0 offset:1424
	s_waitcnt lgkmcnt(1)
	v_mul_f32_e32 v41, v15, v41
	v_fmac_f32_e32 v41, v12, v40
	v_fmac_f32_e32 v41, v14, v42
	v_fmac_f32_e32 v41, v17, v43
	v_add_f32_e32 v51, v19, v41
	s_waitcnt lgkmcnt(0)
	v_mul_f32_e32 v45, v13, v45
	ds_read_b128 v[40:43], v0 offset:1440
	v_fmac_f32_e32 v45, v11, v44
	v_fmac_f32_e32 v45, v9, v46
	v_fmac_f32_e32 v45, v16, v47
	v_add_f32_e32 v51, v51, v45
	ds_read_b128 v[44:47], v0 offset:1456
	s_waitcnt lgkmcnt(1)
	v_mul_f32_e32 v41, v7, v41
	v_fmac_f32_e32 v41, v3, v40
	v_fmac_f32_e32 v41, v5, v42
	v_fmac_f32_e32 v41, v10, v43
	v_add_f32_e32 v40, v51, v41
	s_waitcnt lgkmcnt(0)
	v_mul_f32_e32 v41, v4, v45
	v_fmac_f32_e32 v41, v2, v44
	v_fmac_f32_e32 v41, v6, v46
	v_fmac_f32_e32 v41, v8, v47
	v_add_f32_e32 v41, v40, v41
	v_mul_f32_e64 v40, |v41|, s33
	v_exp_f32_e32 v40, v40
	v_fmac_f32_e32 v50, 0x3377d1cf, v48
	v_fmac_f32_e32 v50, 0x3f317217, v48
	v_add_f32_e32 v40, 1.0, v40
	v_mov_b32_e32 v42, v50
	v_min_f32_e32 v41, 0, v41
	v_log_f32_e32 v50, v40
	v_sub_f32_e32 v40, v49, v42
	ds_read_b128 v[42:45], v0 offset:1472
	v_fmamk_f32 v39, v39, 0x3d800000, v38
	v_mul_f32_e32 v46, 0x3f317217, v50
	v_fma_f32 v51, v50, s35, -v46
	ds_read_b128 v[46:49], v0 offset:1488
	s_waitcnt lgkmcnt(1)
	v_mul_f32_e32 v43, v15, v43
	v_fmac_f32_e32 v43, v12, v42
	v_fmac_f32_e32 v43, v14, v44
	v_fmac_f32_e32 v43, v17, v45
	v_add_f32_e32 v52, v19, v43
	s_waitcnt lgkmcnt(0)
	v_mul_f32_e32 v47, v13, v47
	ds_read_b128 v[42:45], v0 offset:1504
	v_fmac_f32_e32 v47, v11, v46
	v_fmac_f32_e32 v47, v9, v48
	v_fmac_f32_e32 v47, v16, v49
	v_add_f32_e32 v52, v52, v47
	ds_read_b128 v[46:49], v0 offset:1520
	s_waitcnt lgkmcnt(1)
	v_mul_f32_e32 v43, v7, v43
	v_fmac_f32_e32 v43, v3, v42
	v_fmac_f32_e32 v43, v5, v44
	v_fmac_f32_e32 v43, v10, v45
	v_add_f32_e32 v42, v52, v43
	s_waitcnt lgkmcnt(0)
	v_mul_f32_e32 v43, v4, v47
	v_fmac_f32_e32 v43, v2, v46
	v_fmac_f32_e32 v43, v6, v48
	v_fmac_f32_e32 v43, v8, v49
	v_add_f32_e32 v42, v42, v43
	v_mul_f32_e64 v43, |v42|, s33
	v_exp_f32_e32 v43, v43
	v_fmac_f32_e32 v51, 0x3377d1cf, v50
	v_fmac_f32_e32 v51, 0x3f317217, v50
	v_add_f32_e32 v43, 1.0, v43
	v_mov_b32_e32 v44, v51
	v_sub_f32_e32 v41, v41, v44
	v_log_f32_e32 v50, v43
	v_min_f32_e32 v51, 0, v42
	ds_read_b128 v[42:45], v0 offset:1536
	v_fmamk_f32 v40, v40, 0x3d800000, v39
	v_mul_f32_e32 v46, 0x3f317217, v50
	v_fma_f32 v52, v50, s35, -v46
	ds_read_b128 v[46:49], v0 offset:1552
	s_waitcnt lgkmcnt(1)
	v_mul_f32_e32 v43, v15, v43
	v_fmac_f32_e32 v43, v12, v42
	v_fmac_f32_e32 v43, v14, v44
	v_fmac_f32_e32 v43, v17, v45
	v_add_f32_e32 v53, v19, v43
	s_waitcnt lgkmcnt(0)
	v_mul_f32_e32 v47, v13, v47
	ds_read_b128 v[42:45], v0 offset:1568
	v_fmac_f32_e32 v47, v11, v46
	v_fmac_f32_e32 v47, v9, v48
	v_fmac_f32_e32 v47, v16, v49
	v_add_f32_e32 v53, v53, v47
	ds_read_b128 v[46:49], v0 offset:1584
	s_waitcnt lgkmcnt(1)
	v_mul_f32_e32 v43, v7, v43
	v_fmac_f32_e32 v43, v3, v42
	v_fmac_f32_e32 v43, v5, v44
	v_fmac_f32_e32 v43, v10, v45
	v_add_f32_e32 v42, v53, v43
	s_waitcnt lgkmcnt(0)
	v_mul_f32_e32 v43, v4, v47
	v_fmac_f32_e32 v43, v2, v46
	v_fmac_f32_e32 v43, v6, v48
	v_fmac_f32_e32 v43, v8, v49
	v_add_f32_e32 v43, v42, v43
	v_mul_f32_e64 v42, |v43|, s33
	v_exp_f32_e32 v42, v42
	v_fmac_f32_e32 v52, 0x3377d1cf, v50
	v_fmac_f32_e32 v52, 0x3f317217, v50
	v_add_f32_e32 v42, 1.0, v42
	v_mov_b32_e32 v44, v52
	v_min_f32_e32 v43, 0, v43
	v_log_f32_e32 v52, v42
	v_sub_f32_e32 v42, v51, v44
	ds_read_b128 v[44:47], v0 offset:1600
	v_fmamk_f32 v41, v41, 0x3d800000, v40
	v_mul_f32_e32 v48, 0x3f317217, v52
	v_fma_f32 v53, v52, s35, -v48
	ds_read_b128 v[48:51], v0 offset:1616
	s_waitcnt lgkmcnt(1)
	v_mul_f32_e32 v45, v15, v45
	v_fmac_f32_e32 v45, v12, v44
	v_fmac_f32_e32 v45, v14, v46
	v_fmac_f32_e32 v45, v17, v47
	v_add_f32_e32 v54, v19, v45
	s_waitcnt lgkmcnt(0)
	v_mul_f32_e32 v49, v13, v49
	ds_read_b128 v[44:47], v0 offset:1632
	v_fmac_f32_e32 v49, v11, v48
	v_fmac_f32_e32 v49, v9, v50
	v_fmac_f32_e32 v49, v16, v51
	v_add_f32_e32 v54, v54, v49
	ds_read_b128 v[48:51], v0 offset:1648
	s_waitcnt lgkmcnt(1)
	v_mul_f32_e32 v45, v7, v45
	v_fmac_f32_e32 v45, v3, v44
	v_fmac_f32_e32 v45, v5, v46
	v_fmac_f32_e32 v45, v10, v47
	v_add_f32_e32 v44, v54, v45
	s_waitcnt lgkmcnt(0)
	v_mul_f32_e32 v45, v4, v49
	v_fmac_f32_e32 v45, v2, v48
	v_fmac_f32_e32 v45, v6, v50
	v_fmac_f32_e32 v45, v8, v51
	v_add_f32_e32 v44, v44, v45
	v_mul_f32_e64 v45, |v44|, s33
	v_exp_f32_e32 v45, v45
	v_fmac_f32_e32 v53, 0x3377d1cf, v52
	v_fmac_f32_e32 v53, 0x3f317217, v52
	v_add_f32_e32 v45, 1.0, v45
	v_mov_b32_e32 v46, v53
	v_sub_f32_e32 v43, v43, v46
	v_log_f32_e32 v52, v45
	v_min_f32_e32 v53, 0, v44
	ds_read_b128 v[44:47], v0 offset:1664
	v_fmamk_f32 v42, v42, 0x3d800000, v41
	v_mul_f32_e32 v48, 0x3f317217, v52
	v_fma_f32 v54, v52, s35, -v48
	ds_read_b128 v[48:51], v0 offset:1680
	s_waitcnt lgkmcnt(1)
	v_mul_f32_e32 v45, v15, v45
	v_fmac_f32_e32 v45, v12, v44
	v_fmac_f32_e32 v45, v14, v46
	v_fmac_f32_e32 v45, v17, v47
	v_add_f32_e32 v55, v19, v45
	s_waitcnt lgkmcnt(0)
; #define LAS __attribute__((address_space(3)))
; __device__ __forceinline__ void gla_bcum(KArgs a, int tid, int t0, int h, LAS float* segtot, LAS float* glrs, float (&bc)[32], float& tot) {
;     ...
;     float run = 0.f;
; #pragma unroll
;     for (int r = 0; r < 32; ++r) { const LAS f32x4* gp = (const LAS f32x4*)(glrs + (seg * 32 + r) * 16);
;         float z = bias;
; #pragma unroll
;         for (int q = 0; q < 4; ++q) { const f32x4 g = gp[q]; z += g[0] * w2r[4 * q] + g[1] * w2r[4 * q + 1] + g[2] * w2r[4 * q + 2] + g[3] * w2r[4 * q + 3]; }
;         const float la = (fminf(z, 0.f) - __logf(1.0f + __expf(-fabsf(z)))) * (1.0f / 16.0f);
;         run += la; bc[r] = run; }
	v_mul_f32_e32 v49, v13, v49
	ds_read_b128 v[44:47], v0 offset:1696
	v_fmac_f32_e32 v49, v11, v48
	v_fmac_f32_e32 v49, v9, v50
	v_fmac_f32_e32 v49, v16, v51
	v_add_f32_e32 v55, v55, v49
	ds_read_b128 v[48:51], v0 offset:1712
	s_waitcnt lgkmcnt(1)
	v_mul_f32_e32 v45, v7, v45
	v_fmac_f32_e32 v45, v3, v44
	v_fmac_f32_e32 v45, v5, v46
	v_fmac_f32_e32 v45, v10, v47
	v_add_f32_e32 v44, v55, v45
	s_waitcnt lgkmcnt(0)
	v_mul_f32_e32 v45, v4, v49
	v_fmac_f32_e32 v45, v2, v48
	v_fmac_f32_e32 v45, v6, v50
	v_fmac_f32_e32 v45, v8, v51
	v_add_f32_e32 v45, v44, v45
	v_mul_f32_e64 v44, |v45|, s33
	v_exp_f32_e32 v44, v44
	v_fmac_f32_e32 v54, 0x3377d1cf, v52
	v_fmac_f32_e32 v54, 0x3f317217, v52
	v_add_f32_e32 v44, 1.0, v44
	v_mov_b32_e32 v46, v54
	v_min_f32_e32 v45, 0, v45
	v_log_f32_e32 v54, v44
	v_sub_f32_e32 v44, v53, v46
	ds_read_b128 v[46:49], v0 offset:1728
	v_fmamk_f32 v43, v43, 0x3d800000, v42
	v_mul_f32_e32 v50, 0x3f317217, v54
	v_fma_f32 v55, v54, s35, -v50
	ds_read_b128 v[50:53], v0 offset:1744
	s_waitcnt lgkmcnt(1)
	v_mul_f32_e32 v47, v15, v47
	v_fmac_f32_e32 v47, v12, v46
	v_fmac_f32_e32 v47, v14, v48
	v_fmac_f32_e32 v47, v17, v49
	v_add_f32_e32 v56, v19, v47
	s_waitcnt lgkmcnt(0)
	v_mul_f32_e32 v51, v13, v51
	ds_read_b128 v[46:49], v0 offset:1760
	v_fmac_f32_e32 v51, v11, v50
	v_fmac_f32_e32 v51, v9, v52
	v_fmac_f32_e32 v51, v16, v53
	v_add_f32_e32 v56, v56, v51
	ds_read_b128 v[50:53], v0 offset:1776
	s_waitcnt lgkmcnt(1)
	v_mul_f32_e32 v47, v7, v47
	v_fmac_f32_e32 v47, v3, v46
	v_fmac_f32_e32 v47, v5, v48
	v_fmac_f32_e32 v47, v10, v49
	v_add_f32_e32 v46, v56, v47
	s_waitcnt lgkmcnt(0)
	v_mul_f32_e32 v47, v4, v51
	v_fmac_f32_e32 v47, v2, v50
	v_fmac_f32_e32 v47, v6, v52
	v_fmac_f32_e32 v47, v8, v53
	v_add_f32_e32 v46, v46, v47
	v_mul_f32_e64 v47, |v46|, s33
	v_exp_f32_e32 v47, v47
	v_fmac_f32_e32 v55, 0x3377d1cf, v54
	v_fmac_f32_e32 v55, 0x3f317217, v54
	v_add_f32_e32 v47, 1.0, v47
	v_mov_b32_e32 v48, v55
	v_sub_f32_e32 v45, v45, v48
	v_log_f32_e32 v54, v47
	v_min_f32_e32 v55, 0, v46
	ds_read_b128 v[46:49], v0 offset:1792
	v_fmamk_f32 v44, v44, 0x3d800000, v43
	v_mul_f32_e32 v50, 0x3f317217, v54
	v_fma_f32 v56, v54, s35, -v50
	ds_read_b128 v[50:53], v0 offset:1808
	s_waitcnt lgkmcnt(1)
	v_mul_f32_e32 v47, v15, v47
	v_fmac_f32_e32 v47, v12, v46
	v_fmac_f32_e32 v47, v14, v48
	v_fmac_f32_e32 v47, v17, v49
	v_add_f32_e32 v57, v19, v47
	s_waitcnt lgkmcnt(0)
	v_mul_f32_e32 v51, v13, v51
	ds_read_b128 v[46:49], v0 offset:1824
	v_fmac_f32_e32 v51, v11, v50
	v_fmac_f32_e32 v51, v9, v52
	v_fmac_f32_e32 v51, v16, v53
	v_add_f32_e32 v57, v57, v51
	ds_read_b128 v[50:53], v0 offset:1840
	s_waitcnt lgkmcnt(1)
	v_mul_f32_e32 v47, v7, v47
	v_fmac_f32_e32 v47, v3, v46
	v_fmac_f32_e32 v47, v5, v48
	v_fmac_f32_e32 v47, v10, v49
	v_add_f32_e32 v46, v57, v47
	s_waitcnt lgkmcnt(0)
	v_mul_f32_e32 v47, v4, v51
	v_fmac_f32_e32 v47, v2, v50
	v_fmac_f32_e32 v47, v6, v52
	v_fmac_f32_e32 v47, v8, v53
	v_add_f32_e32 v46, v46, v47
	v_mul_f32_e64 v47, |v46|, s33
	v_exp_f32_e32 v47, v47
	v_fmac_f32_e32 v56, 0x3377d1cf, v54
	v_fmac_f32_e32 v56, 0x3f317217, v54
	v_add_f32_e32 v47, 1.0, v47
	v_mov_b32_e32 v48, v56
	v_fmamk_f32 v45, v45, 0x3d800000, v44
	v_log_f32_e32 v54, v47
	v_sub_f32_e32 v47, v55, v48
	v_fmamk_f32 v55, v47, 0x3d800000, v45
	v_min_f32_e32 v56, 0, v46
	ds_read_b128 v[46:49], v0 offset:1856
	v_mul_f32_e32 v50, 0x3f317217, v54
	v_fma_f32 v57, v54, s35, -v50
	ds_read_b128 v[50:53], v0 offset:1872
	v_fmac_f32_e32 v57, 0x3377d1cf, v54
	s_waitcnt lgkmcnt(1)
	v_mul_f32_e32 v47, v15, v47
	v_fmac_f32_e32 v47, v12, v46
	v_fmac_f32_e32 v47, v14, v48
	v_fmac_f32_e32 v47, v17, v49
	v_add_f32_e32 v58, v19, v47
	s_waitcnt lgkmcnt(0)
	v_mul_f32_e32 v51, v13, v51
	ds_read_b128 v[46:49], v0 offset:1888
	v_fmac_f32_e32 v51, v11, v50
	v_fmac_f32_e32 v51, v9, v52
	v_fmac_f32_e32 v51, v16, v53
	v_add_f32_e32 v58, v58, v51
	ds_read_b128 v[50:53], v0 offset:1904
	s_waitcnt lgkmcnt(1)
	v_mul_f32_e32 v47, v7, v47
	v_fmac_f32_e32 v47, v3, v46
	v_fmac_f32_e32 v47, v5, v48
	v_fmac_f32_e32 v47, v10, v49
	v_add_f32_e32 v46, v58, v47
	s_waitcnt lgkmcnt(0)
	v_mul_f32_e32 v47, v4, v51
	v_fmac_f32_e32 v47, v2, v50
	v_fmac_f32_e32 v47, v6, v52
	v_fmac_f32_e32 v47, v8, v53
	v_add_f32_e32 v46, v46, v47
	v_mul_f32_e64 v47, |v46|, s33
	v_exp_f32_e32 v47, v47
	v_fmac_f32_e32 v57, 0x3f317217, v54
	v_add_f32_e32 v47, 1.0, v47
	v_mov_b32_e32 v48, v57
	v_min_f32_e32 v57, 0, v46
	v_log_f32_e32 v54, v47
	v_sub_f32_e32 v47, v56, v48
	v_fmamk_f32 v56, v47, 0x3d800000, v55
	ds_read_b128 v[46:49], v0 offset:1920
	v_mul_f32_e32 v50, 0x3f317217, v54
	v_fma_f32 v58, v54, s35, -v50
	ds_read_b128 v[50:53], v0 offset:1936
	v_fmac_f32_e32 v58, 0x3377d1cf, v54
	s_waitcnt lgkmcnt(1)
	v_mul_f32_e32 v47, v15, v47
	v_fmac_f32_e32 v47, v12, v46
	v_fmac_f32_e32 v47, v14, v48
	v_fmac_f32_e32 v47, v17, v49
	v_add_f32_e32 v59, v19, v47
	s_waitcnt lgkmcnt(0)
	v_mul_f32_e32 v51, v13, v51
	ds_read_b128 v[46:49], v0 offset:1952
	v_fmac_f32_e32 v51, v11, v50
	v_fmac_f32_e32 v51, v9, v52
	v_fmac_f32_e32 v51, v16, v53
	v_add_f32_e32 v59, v59, v51
	ds_read_b128 v[50:53], v0 offset:1968
	s_waitcnt lgkmcnt(1)
	v_mul_f32_e32 v47, v7, v47
	v_fmac_f32_e32 v47, v3, v46
	v_fmac_f32_e32 v47, v5, v48
	v_fmac_f32_e32 v47, v10, v49
	v_add_f32_e32 v46, v59, v47
	s_waitcnt lgkmcnt(0)
	v_mul_f32_e32 v47, v4, v51
	v_fmac_f32_e32 v47, v2, v50
	v_fmac_f32_e32 v47, v6, v52
	v_fmac_f32_e32 v47, v8, v53
	v_add_f32_e32 v46, v46, v47
	v_mul_f32_e64 v47, |v46|, s33
	v_exp_f32_e32 v47, v47
	v_fmac_f32_e32 v58, 0x3f317217, v54
	v_add_f32_e32 v47, 1.0, v47
	v_mov_b32_e32 v48, v58
	v_min_f32_e32 v58, 0, v46
	v_log_f32_e32 v54, v47
	v_sub_f32_e32 v47, v57, v48
	v_fmamk_f32 v57, v47, 0x3d800000, v56
	ds_read_b128 v[46:49], v0 offset:1984
	v_mul_f32_e32 v50, 0x3f317217, v54
	v_fma_f32 v59, v54, s35, -v50
	ds_read_b128 v[50:53], v0 offset:2000
	v_fmac_f32_e32 v59, 0x3377d1cf, v54
	s_waitcnt lgkmcnt(1)
; #define LAS __attribute__((address_space(3)))
; __device__ __forceinline__ float bf2f(bf16_t v) { return __uint_as_float((unsigned)v << 16); }
; __device__ __forceinline__ unsigned f2bf(float f) { return (unsigned)__builtin_bit_cast(unsigned short, (__bf16)f); }
; #define X make_ctx(lds_raw)
; __device__ __forceinline__ void gla_bcum(KArgs a, int tid, int t0, int h, LAS float* segtot, LAS float* glrs, float (&bc)[32], float& tot) {
;     ...
;     for (int r = 0; r < 32; ++r) { const LAS f32x4* gp = (const LAS f32x4*)(glrs + (seg * 32 + r) * 16);
;         float z = bias;
; #pragma unroll
;         for (int q = 0; q < 4; ++q) { const f32x4 g = gp[q]; z += g[0] * w2r[4 * q] + g[1] * w2r[4 * q + 1] + g[2] * w2r[4 * q + 2] + g[3] * w2r[4 * q + 3]; }
;         const float la = (fminf(z, 0.f) - __logf(1.0f + __expf(-fabsf(z)))) * (1.0f / 16.0f);
;         run += la; bc[r] = run; }
;     segtot[seg * 128 + d] = run;
;     __syncthreads();
;     float off = 0.f; tot = 0.f;
; #pragma unroll
;     for (int s2 = 0; s2 < 4; ++s2) { const float v = segtot[s2 * 128 + d]; tot += v; if (s2 < seg) off += v; }
; #pragma unroll
;     for (int r = 0; r < 32; ++r) bc[r] += off;
;     ...
;         { float bc[32], tot; gla_bcum(a, X.tid, t0, h, segtot, (LAS float*)vT, bc, tot);
;           const int d = X.tid & 127, seg = X.tid >> 7;
; #pragma unroll
;           for (int r = 0; r < 32; ++r) { const int i = seg * 32 + r; const bf16_t* row = proj + (size_t)(t0 + i) * NMAIN + h * 128 + d;
;               const float qv = bf2f(row[C_GQ]), kv = bf2f(row[C_GK]);
;               qgs[i * GP + d] = (bf16_t)f2bf(qv * 0.08838834764831845f * __expf(bc[r])); kgs[i * GP + d] = (bf16_t)f2bf(kv * __expf(-bc[r])); } }
	v_mul_f32_e32 v15, v15, v47
	v_fmac_f32_e32 v15, v12, v46
	v_fmac_f32_e32 v15, v14, v48
	v_fmac_f32_e32 v15, v17, v49
	v_add_f32_e32 v17, v19, v15
	s_waitcnt lgkmcnt(0)
	v_mul_f32_e32 v19, v13, v51
	ds_read_b128 v[12:15], v0 offset:2016
	ds_read_b128 v[46:49], v0 offset:2032
	v_fmac_f32_e32 v19, v11, v50
	v_fmac_f32_e32 v19, v9, v52
	v_fmac_f32_e32 v19, v16, v53
	s_waitcnt lgkmcnt(1)
	v_mul_f32_e32 v0, v7, v13
	v_fmac_f32_e32 v0, v3, v12
	s_waitcnt lgkmcnt(0)
	v_mul_f32_e32 v3, v4, v47
	v_fmac_f32_e32 v0, v5, v14
	v_fmac_f32_e32 v3, v2, v46
	v_add_f32_e32 v9, v17, v19
	v_fmac_f32_e32 v0, v10, v15
	v_fmac_f32_e32 v3, v6, v48
	v_add_f32_e32 v0, v9, v0
	v_fmac_f32_e32 v3, v8, v49
	v_add_f32_e32 v0, v0, v3
	v_mul_f32_e64 v2, |v0|, s33
	v_exp_f32_e32 v2, v2
	v_fmac_f32_e32 v59, 0x3f317217, v54
	v_add_f32_e32 v2, 1.0, v2
	v_mov_b32_e32 v3, v59
	v_sub_f32_e32 v3, v58, v3
	v_log_f32_e32 v2, v2
	v_fmamk_f32 v19, v3, 0x3d800000, v57
	v_min_f32_e32 v0, 0, v0
	v_mul_f32_e32 v3, 0x3f317217, v2
	v_fma_f32 v3, v2, s35, -v3
	v_fmac_f32_e32 v3, 0x3377d1cf, v2
	v_fmac_f32_e32 v3, 0x3f317217, v2
	s_nop 1
	v_mov_b32_e32 v2, v3
	v_sub_f32_e32 v0, v0, v2
	s_and_b32 s6, s36, 0x3fffff80
	v_fmamk_f32 v0, v0, 0x3d800000, v19
	v_lshl_add_u32 v2, s6, 2, v118
	ds_write_b32 v2, v0
	s_waitcnt lgkmcnt(0)
	s_barrier
	ds_read2st64_b32 v[2:3], v118 offset1:2
	s_cmp_gt_i32 s9, 0
	ds_read2st64_b32 v[4:5], v118 offset0:4 offset1:6
	s_cselect_b64 vcc, -1, 0
	s_cmp_gt_i32 s9, 1
	s_waitcnt lgkmcnt(1)
	v_add_f32_e32 v2, 0, v2
	v_cndmask_b32_e32 v2, 0, v2, vcc
	v_add_f32_e32 v3, v3, v2
	s_cselect_b64 vcc, -1, 0
	v_cndmask_b32_e32 v2, v2, v3, vcc
	s_cmp_gt_i32 s9, 2
	s_waitcnt lgkmcnt(0)
	v_add_f32_e32 v3, v4, v2
	s_cselect_b64 vcc, -1, 0
	s_cmp_gt_i32 s9, 3
	v_cndmask_b32_e32 v6, v2, v3, vcc
	s_cselect_b64 vcc, -1, 0
	s_lshl_b32 s36, s1, 8
	v_lshl_add_u64 v[2:3], v[92:93], 0, s[36:37]
	v_add_u32_e32 v4, s44, v120
	v_add_f32_e32 v7, v5, v6
	v_mad_i64_i32 v[4:5], s[6:7], v4, s48, v[2:3]
	global_load_ushort v46, v[4:5], off
	global_load_ushort v47, v[4:5], off offset:1024
	v_add_u32_e32 v4, s44, v122
	v_mad_i64_i32 v[4:5], s[6:7], v4, s48, v[2:3]
	global_load_ushort v48, v[4:5], off
	global_load_ushort v49, v[4:5], off offset:1024
	v_add_u32_e32 v4, s44, v124
	v_mad_i64_i32 v[4:5], s[6:7], v4, s48, v[2:3]
	global_load_ushort v51, v[4:5], off
	global_load_ushort v52, v[4:5], off offset:1024
	v_add_u32_e32 v4, s44, v126
	v_mad_i64_i32 v[4:5], s[6:7], v4, s48, v[2:3]
	global_load_ushort v59, v[4:5], off
	global_load_ushort v60, v[4:5], off offset:1024
	v_add_u32_e32 v4, s44, v128
	v_cndmask_b32_e32 v50, v6, v7, vcc
	v_mad_i64_i32 v[4:5], s[6:7], v4, s48, v[2:3]
	v_add_f32_e32 v53, v18, v50
	v_add_f32_e32 v18, v35, v50
	v_add_f32_e32 v17, v36, v50
	global_load_ushort v35, v[4:5], off
	global_load_ushort v36, v[4:5], off offset:1024
	v_add_f32_e32 v54, v20, v50
	v_mul_f32_e32 v20, 0x3fb8aa3b, v53
	v_add_f32_e32 v15, v38, v50
	v_exp_f32_e32 v38, v20
	v_mul_f32_e32 v20, 0xbfb8aa3b, v53
	v_add_f32_e32 v14, v39, v50
	v_exp_f32_e32 v39, v20
	v_add_u32_e32 v20, s44, v130
	v_add_f32_e32 v58, v21, v50
	v_mad_i64_i32 v[20:21], s[6:7], v20, s48, v[2:3]
	v_add_f32_e32 v13, v40, v50
	v_add_f32_e32 v12, v41, v50
	global_load_ushort v40, v[20:21], off
	global_load_ushort v41, v[20:21], off offset:1024
	v_add_f32_e32 v4, v19, v50
	v_add_f32_e32 v16, v37, v50
	v_mul_f32_e32 v20, 0x3fb8aa3b, v54
	v_add_f32_e32 v11, v42, v50
	v_add_f32_e32 v10, v43, v50
	v_add_f32_e32 v9, v44, v50
	v_add_f32_e32 v8, v45, v50
	v_add_f32_e32 v22, v22, v50
	v_add_f32_e32 v23, v23, v50
	v_add_f32_e32 v24, v24, v50
	v_add_f32_e32 v25, v25, v50
	v_add_f32_e32 v26, v26, v50
	v_add_f32_e32 v27, v27, v50
	v_add_f32_e32 v28, v28, v50
	v_add_f32_e32 v29, v29, v50
	v_add_f32_e32 v30, v30, v50
	v_add_f32_e32 v31, v31, v50
	v_add_f32_e32 v32, v32, v50
	v_add_f32_e32 v33, v33, v50
	v_add_f32_e32 v34, v34, v50
	s_mov_b32 s9, s37
	v_add_f32_e32 v7, v55, v50
	v_add_f32_e32 v6, v56, v50
	v_add_f32_e32 v5, v57, v50
	v_add_f32_e32 v0, v50, v0
	s_andn2_b64 vcc, exec, s[38:39]
	s_waitcnt vmcnt(11)
	v_lshlrev_b32_e32 v19, 16, v46
	v_mul_f32_e32 v19, 0x3db504f3, v19
	v_mul_f32_e32 v19, v19, v38
	s_waitcnt vmcnt(10)
	v_lshlrev_b32_e32 v37, 16, v47
	v_cvt_pk_bf16_f32 v19, v19, s0
	ds_write_b16 v121, v19
	v_mul_f32_e32 v19, v39, v37
	v_exp_f32_e32 v38, v20
	v_mul_f32_e32 v20, 0xbfb8aa3b, v54
	v_cvt_pk_bf16_f32 v19, v19, s0
	v_exp_f32_e32 v39, v20
	v_add_u32_e32 v20, s44, v132
	ds_write_b16 v121, v19 offset:34816
	v_mad_i64_i32 v[20:21], s[6:7], v20, s48, v[2:3]
	global_load_ushort v42, v[20:21], off
	global_load_ushort v43, v[20:21], off offset:1024
	s_waitcnt vmcnt(11)
	v_lshlrev_b32_e32 v19, 16, v48
	v_mul_f32_e32 v19, 0x3db504f3, v19
	v_mul_f32_e32 v19, v38, v19
	s_waitcnt vmcnt(10)
	v_lshlrev_b32_e32 v37, 16, v49
	v_cvt_pk_bf16_f32 v19, v19, s0
	v_mul_f32_e32 v20, 0x3fb8aa3b, v58
	ds_write_b16 v123, v19
	v_mul_f32_e32 v19, v39, v37
	v_exp_f32_e32 v38, v20
	v_mul_f32_e32 v20, 0xbfb8aa3b, v58
	v_cvt_pk_bf16_f32 v19, v19, s0
	v_exp_f32_e32 v39, v20
	v_add_u32_e32 v20, s44, v134
	ds_write_b16 v123, v19 offset:34816
	v_mad_i64_i32 v[20:21], s[6:7], v20, s48, v[2:3]
	s_waitcnt vmcnt(9)
	v_lshlrev_b32_e32 v19, 16, v51
	global_load_ushort v44, v[20:21], off
	global_load_ushort v45, v[20:21], off offset:1024
	v_mul_f32_e32 v19, 0x3db504f3, v19
	v_mul_f32_e32 v19, v38, v19
	s_waitcnt vmcnt(10)
	v_lshlrev_b32_e32 v37, 16, v52
	v_cvt_pk_bf16_f32 v19, v19, s0
	v_mul_f32_e32 v20, 0x3fb8aa3b, v22
	ds_write_b16 v125, v19
	v_mul_f32_e32 v19, v39, v37
	v_exp_f32_e32 v38, v20
	v_mul_f32_e32 v20, 0xbfb8aa3b, v22
	v_cvt_pk_bf16_f32 v19, v19, s0
	v_exp_f32_e32 v22, v20
	v_add_u32_e32 v20, s44, v136
	ds_write_b16 v125, v19 offset:34816
	v_mad_i64_i32 v[20:21], s[6:7], v20, s48, v[2:3]
	s_waitcnt vmcnt(9)
; __device__ __forceinline__ float bf2f(bf16_t v) { return __uint_as_float((unsigned)v << 16); }
; __device__ __forceinline__ unsigned f2bf(float f) { return (unsigned)__builtin_bit_cast(unsigned short, (__bf16)f); }
;     ...
; #pragma unroll
;           for (int r = 0; r < 32; ++r) { const int i = seg * 32 + r; const bf16_t* row = proj + (size_t)(t0 + i) * NMAIN + h * 128 + d;
;               const float qv = bf2f(row[C_GQ]), kv = bf2f(row[C_GK]);
;               qgs[i * GP + d] = (bf16_t)f2bf(qv * 0.08838834764831845f * __expf(bc[r])); kgs[i * GP + d] = (bf16_t)f2bf(kv * __expf(-bc[r])); } }
	v_lshlrev_b32_e32 v19, 16, v59
	global_load_ushort v39, v[20:21], off
	global_load_ushort v46, v[20:21], off offset:1024
	v_mul_f32_e32 v19, 0x3db504f3, v19
	v_mul_f32_e32 v19, v38, v19
	s_waitcnt vmcnt(10)
	v_lshlrev_b32_e32 v37, 16, v60
	v_cvt_pk_bf16_f32 v19, v19, s0
	ds_write_b16 v127, v19
	v_mul_f32_e32 v19, v22, v37
	v_cvt_pk_bf16_f32 v19, v19, s0
	v_mul_f32_e32 v20, 0x3fb8aa3b, v23
	ds_write_b16 v127, v19 offset:34816
	s_waitcnt vmcnt(9)
	v_lshlrev_b32_e32 v19, 16, v35
	v_exp_f32_e32 v35, v20
	v_mul_f32_e32 v20, 0xbfb8aa3b, v23
	v_exp_f32_e32 v23, v20
	v_add_u32_e32 v20, s44, v138
	v_mad_i64_i32 v[20:21], s[6:7], v20, s48, v[2:3]
	s_waitcnt vmcnt(8)
	v_lshlrev_b32_e32 v22, 16, v36
	global_load_ushort v36, v[20:21], off
	global_load_ushort v37, v[20:21], off offset:1024
	v_mul_f32_e32 v19, 0x3db504f3, v19
	v_mul_f32_e32 v19, v35, v19
	v_cvt_pk_bf16_f32 v19, v19, s0
	v_mul_f32_e32 v20, 0x3fb8aa3b, v24
	ds_write_b16 v129, v19
	v_mul_f32_e32 v19, v23, v22
	v_exp_f32_e32 v23, v20
	v_mul_f32_e32 v20, 0xbfb8aa3b, v24
	v_cvt_pk_bf16_f32 v19, v19, s0
	v_exp_f32_e32 v24, v20
	v_add_u32_e32 v20, s44, v140
	ds_write_b16 v129, v19 offset:34816
	v_mad_i64_i32 v[20:21], s[6:7], v20, s48, v[2:3]
	global_load_ushort v35, v[20:21], off
	global_load_ushort v38, v[20:21], off offset:1024
	s_waitcnt vmcnt(11)
	v_lshlrev_b32_e32 v19, 16, v40
	v_mul_f32_e32 v19, 0x3db504f3, v19
	v_mul_f32_e32 v19, v23, v19
	s_waitcnt vmcnt(10)
	v_lshlrev_b32_e32 v22, 16, v41
	v_cvt_pk_bf16_f32 v19, v19, s0
	v_mul_f32_e32 v20, 0x3fb8aa3b, v25
	ds_write_b16 v131, v19
	v_mul_f32_e32 v19, v24, v22
	v_exp_f32_e32 v23, v20
	v_mul_f32_e32 v20, 0xbfb8aa3b, v25
	v_cvt_pk_bf16_f32 v19, v19, s0
	v_exp_f32_e32 v24, v20
	v_add_u32_e32 v20, s44, v142
	ds_write_b16 v131, v19 offset:34816
	v_mad_i64_i32 v[20:21], s[6:7], v20, s48, v[2:3]
	global_load_ushort v25, v[20:21], off
	global_load_ushort v40, v[20:21], off offset:1024
	s_waitcnt vmcnt(11)
	v_lshlrev_b32_e32 v19, 16, v42
	v_mul_f32_e32 v19, 0x3db504f3, v19
	v_mul_f32_e32 v19, v23, v19
	s_waitcnt vmcnt(10)
	v_lshlrev_b32_e32 v22, 16, v43
	v_cvt_pk_bf16_f32 v19, v19, s0
	v_mul_f32_e32 v20, 0x3fb8aa3b, v26
	ds_write_b16 v133, v19
	v_mul_f32_e32 v19, v24, v22
	v_exp_f32_e32 v23, v20
	v_mul_f32_e32 v20, 0xbfb8aa3b, v26
	v_cvt_pk_bf16_f32 v19, v19, s0
	v_exp_f32_e32 v24, v20
	v_add_u32_e32 v20, s44, v144
	ds_write_b16 v133, v19 offset:34816
	v_mad_i64_i32 v[20:21], s[6:7], v20, s48, v[2:3]
	global_load_ushort v26, v[20:21], off
	global_load_ushort v41, v[20:21], off offset:1024
	s_waitcnt vmcnt(11)
	v_lshlrev_b32_e32 v19, 16, v44
	v_mul_f32_e32 v19, 0x3db504f3, v19
	v_mul_f32_e32 v19, v23, v19
	s_waitcnt vmcnt(10)
	v_lshlrev_b32_e32 v22, 16, v45
	v_cvt_pk_bf16_f32 v19, v19, s0
	v_mul_f32_e32 v20, 0x3fb8aa3b, v27
	ds_write_b16 v135, v19
	v_mul_f32_e32 v19, v24, v22
	v_exp_f32_e32 v23, v20
	v_mul_f32_e32 v20, 0xbfb8aa3b, v27
	v_cvt_pk_bf16_f32 v19, v19, s0
	v_exp_f32_e32 v24, v20
	v_add_u32_e32 v20, s44, v146
	ds_write_b16 v135, v19 offset:34816
	v_mad_i64_i32 v[20:21], s[6:7], v20, s48, v[2:3]
	s_waitcnt vmcnt(9)
	v_lshlrev_b32_e32 v19, 16, v39
	global_load_ushort v27, v[20:21], off
	global_load_ushort v39, v[20:21], off offset:1024
	v_mul_f32_e32 v19, 0x3db504f3, v19
	v_mul_f32_e32 v19, v23, v19
	s_waitcnt vmcnt(10)
	v_lshlrev_b32_e32 v22, 16, v46
	v_cvt_pk_bf16_f32 v19, v19, s0
	v_mul_f32_e32 v20, 0x3fb8aa3b, v28
	ds_write_b16 v137, v19
	v_mul_f32_e32 v19, v24, v22
	v_exp_f32_e32 v23, v20
	v_mul_f32_e32 v20, 0xbfb8aa3b, v28
	v_cvt_pk_bf16_f32 v19, v19, s0
	v_exp_f32_e32 v24, v20
	v_add_u32_e32 v20, s44, v148
	ds_write_b16 v137, v19 offset:34816
	v_mad_i64_i32 v[20:21], s[6:7], v20, s48, v[2:3]
	s_waitcnt vmcnt(9)
	v_lshlrev_b32_e32 v19, 16, v36
	global_load_ushort v28, v[20:21], off
	global_load_ushort v36, v[20:21], off offset:1024
	v_mul_f32_e32 v19, 0x3db504f3, v19
	v_mul_f32_e32 v19, v23, v19
	s_waitcnt vmcnt(10)
	v_lshlrev_b32_e32 v22, 16, v37
	v_cvt_pk_bf16_f32 v19, v19, s0
	v_mul_f32_e32 v20, 0x3fb8aa3b, v29
	ds_write_b16 v139, v19
	v_mul_f32_e32 v19, v24, v22
	v_exp_f32_e32 v23, v20
	v_mul_f32_e32 v20, 0xbfb8aa3b, v29
	v_cvt_pk_bf16_f32 v19, v19, s0
	v_exp_f32_e32 v24, v20
	v_add_u32_e32 v20, s44, v150
	ds_write_b16 v139, v19 offset:34816
	v_mad_i64_i32 v[20:21], s[6:7], v20, s48, v[2:3]
	s_waitcnt vmcnt(9)
	v_lshlrev_b32_e32 v19, 16, v35
	global_load_ushort v29, v[20:21], off
	global_load_ushort v35, v[20:21], off offset:1024
	v_mul_f32_e32 v19, 0x3db504f3, v19
	v_mul_f32_e32 v19, v23, v19
	s_waitcnt vmcnt(10)
	v_lshlrev_b32_e32 v22, 16, v38
	v_cvt_pk_bf16_f32 v19, v19, s0
	v_mul_f32_e32 v20, 0x3fb8aa3b, v30
	ds_write_b16 v141, v19
	v_mul_f32_e32 v19, v24, v22
	v_exp_f32_e32 v23, v20
	v_mul_f32_e32 v20, 0xbfb8aa3b, v30
	v_cvt_pk_bf16_f32 v19, v19, s0
	v_exp_f32_e32 v24, v20
	v_add_u32_e32 v20, s44, v152
	ds_write_b16 v141, v19 offset:34816
	v_mad_i64_i32 v[20:21], s[6:7], v20, s48, v[2:3]
	s_waitcnt vmcnt(9)
	v_lshlrev_b32_e32 v19, 16, v25
	global_load_ushort v25, v[20:21], off
	global_load_ushort v30, v[20:21], off offset:1024
	v_mul_f32_e32 v19, 0x3db504f3, v19
	v_mul_f32_e32 v19, v23, v19
	s_waitcnt vmcnt(10)
	v_lshlrev_b32_e32 v22, 16, v40
	v_cvt_pk_bf16_f32 v19, v19, s0
	v_mul_f32_e32 v20, 0x3fb8aa3b, v31
	ds_write_b16 v143, v19
	v_mul_f32_e32 v19, v24, v22
	v_exp_f32_e32 v23, v20
	v_mul_f32_e32 v20, 0xbfb8aa3b, v31
	v_cvt_pk_bf16_f32 v19, v19, s0
	v_exp_f32_e32 v24, v20
	v_add_u32_e32 v20, s44, v154
	ds_write_b16 v143, v19 offset:34816
	v_mad_i64_i32 v[20:21], s[6:7], v20, s48, v[2:3]
	s_waitcnt vmcnt(9)
	v_lshlrev_b32_e32 v19, 16, v26
	global_load_ushort v26, v[20:21], off
	global_load_ushort v31, v[20:21], off offset:1024
	v_mul_f32_e32 v19, 0x3db504f3, v19
	v_mul_f32_e32 v19, v23, v19
	s_waitcnt vmcnt(10)
; __device__ __forceinline__ float bf2f(bf16_t v) { return __uint_as_float((unsigned)v << 16); }
; __device__ __forceinline__ unsigned f2bf(float f) { return (unsigned)__builtin_bit_cast(unsigned short, (__bf16)f); }
;     ...
; #pragma unroll
;           for (int r = 0; r < 32; ++r) { const int i = seg * 32 + r; const bf16_t* row = proj + (size_t)(t0 + i) * NMAIN + h * 128 + d;
;               const float qv = bf2f(row[C_GQ]), kv = bf2f(row[C_GK]);
;               qgs[i * GP + d] = (bf16_t)f2bf(qv * 0.08838834764831845f * __expf(bc[r])); kgs[i * GP + d] = (bf16_t)f2bf(kv * __expf(-bc[r])); } }
	v_lshlrev_b32_e32 v22, 16, v41
	v_cvt_pk_bf16_f32 v19, v19, s0
	v_mul_f32_e32 v20, 0x3fb8aa3b, v32
	ds_write_b16 v145, v19
	v_mul_f32_e32 v19, v24, v22
	v_exp_f32_e32 v23, v20
	v_mul_f32_e32 v20, 0xbfb8aa3b, v32
	v_cvt_pk_bf16_f32 v19, v19, s0
	v_exp_f32_e32 v24, v20
	v_add_u32_e32 v20, s44, v156
	ds_write_b16 v145, v19 offset:34816
	v_mad_i64_i32 v[20:21], s[6:7], v20, s48, v[2:3]
	s_waitcnt vmcnt(9)
	v_lshlrev_b32_e32 v19, 16, v27
	global_load_ushort v27, v[20:21], off
	global_load_ushort v32, v[20:21], off offset:1024
	v_mul_f32_e32 v19, 0x3db504f3, v19
	v_mul_f32_e32 v19, v23, v19
	s_waitcnt vmcnt(10)
	v_lshlrev_b32_e32 v22, 16, v39
	v_cvt_pk_bf16_f32 v19, v19, s0
	v_mul_f32_e32 v20, 0x3fb8aa3b, v33
	ds_write_b16 v147, v19
	v_mul_f32_e32 v19, v24, v22
	v_exp_f32_e32 v23, v20
	v_cvt_pk_bf16_f32 v19, v19, s0
	v_mul_f32_e32 v20, 0xbfb8aa3b, v33
	ds_write_b16 v147, v19 offset:34816
	s_waitcnt vmcnt(9)
	v_lshlrev_b32_e32 v19, 16, v28
	v_exp_f32_e32 v24, v20
	v_mul_f32_e32 v19, 0x3db504f3, v19
	v_add_u32_e32 v20, s44, v158
	v_mad_i64_i32 v[20:21], s[6:7], v20, s48, v[2:3]
	v_mul_f32_e32 v19, v23, v19
	s_waitcnt vmcnt(8)
	v_lshlrev_b32_e32 v22, 16, v36
	global_load_ushort v28, v[20:21], off
	global_load_ushort v33, v[20:21], off offset:1024
	v_cvt_pk_bf16_f32 v19, v19, s0
	v_mul_f32_e32 v20, 0x3fb8aa3b, v34
	ds_write_b16 v149, v19
	v_mul_f32_e32 v19, v24, v22
	v_exp_f32_e32 v23, v20
	v_mul_f32_e32 v20, 0xbfb8aa3b, v34
	v_cvt_pk_bf16_f32 v19, v19, s0
	v_exp_f32_e32 v24, v20
	v_add_u32_e32 v20, s44, v160
	ds_write_b16 v149, v19 offset:34816
	v_mad_i64_i32 v[20:21], s[6:7], v20, s48, v[2:3]
	s_waitcnt vmcnt(9)
	v_lshlrev_b32_e32 v19, 16, v29
	global_load_ushort v29, v[20:21], off
	s_nop 0
	global_load_ushort v20, v[20:21], off offset:1024
	v_mul_f32_e32 v19, 0x3db504f3, v19
	v_mul_f32_e32 v19, v23, v19
	s_waitcnt vmcnt(10)
	v_lshlrev_b32_e32 v22, 16, v35
	v_cvt_pk_bf16_f32 v19, v19, s0
	ds_write_b16 v151, v19
	v_mul_f32_e32 v19, v24, v22
	v_cvt_pk_bf16_f32 v19, v19, s0
	ds_write_b16 v151, v19 offset:34816
	s_waitcnt vmcnt(9)
	v_lshlrev_b32_e32 v19, 16, v25
	v_mul_f32_e32 v22, 0x3db504f3, v19
	v_mul_f32_e32 v19, 0x3fb8aa3b, v18
	v_mul_f32_e32 v18, 0xbfb8aa3b, v18
	v_exp_f32_e32 v24, v18
	v_add_u32_e32 v18, s44, v162
	v_exp_f32_e32 v23, v19
	v_mad_i64_i32 v[18:19], s[6:7], v18, s48, v[2:3]
	s_waitcnt vmcnt(8)
	v_lshlrev_b32_e32 v21, 16, v30
	global_load_ushort v25, v[18:19], off
	global_load_ushort v30, v[18:19], off offset:1024
	v_mul_f32_e32 v18, v23, v22
	v_cvt_pk_bf16_f32 v18, v18, s0
	ds_write_b16 v153, v18
	v_mul_f32_e32 v18, v24, v21
	v_cvt_pk_bf16_f32 v18, v18, s0
	ds_write_b16 v153, v18 offset:34816
	s_waitcnt vmcnt(9)
	v_lshlrev_b32_e32 v18, 16, v26
	v_mul_f32_e32 v22, 0x3db504f3, v18
	v_mul_f32_e32 v18, 0x3fb8aa3b, v17
	v_exp_f32_e32 v23, v18
	v_mul_f32_e32 v17, 0xbfb8aa3b, v17
	v_exp_f32_e32 v17, v17
	v_add_u32_e32 v18, s44, v164
	v_mad_i64_i32 v[18:19], s[6:7], v18, s48, v[2:3]
	s_waitcnt vmcnt(8)
	v_lshlrev_b32_e32 v21, 16, v31
	global_load_ushort v24, v[18:19], off
	global_load_ushort v26, v[18:19], off offset:1024
	v_mul_f32_e32 v18, v23, v22
	v_cvt_pk_bf16_f32 v18, v18, s0
	v_mul_f32_e32 v17, v17, v21
	ds_write_b16 v155, v18
	v_cvt_pk_bf16_f32 v17, v17, s0
	v_add_u32_e32 v18, s44, v166
	ds_write_b16 v155, v17 offset:34816
	v_mad_i64_i32 v[18:19], s[6:7], v18, s48, v[2:3]
	global_load_ushort v22, v[18:19], off
	s_nop 0
	global_load_ushort v18, v[18:19], off offset:1024
	v_mul_f32_e32 v19, 0x3fb8aa3b, v16
	v_mul_f32_e32 v16, 0xbfb8aa3b, v16
	v_exp_f32_e32 v16, v16
	v_exp_f32_e32 v19, v19
	s_waitcnt vmcnt(11)
	v_lshlrev_b32_e32 v17, 16, v27
	s_waitcnt vmcnt(10)
	v_lshlrev_b32_e32 v21, 16, v32
	v_mul_f32_e32 v17, 0x3db504f3, v17
	v_mul_f32_e32 v16, v16, v21
	v_mul_f32_e32 v17, v19, v17
	v_cvt_pk_bf16_f32 v16, v16, s0
	v_cvt_pk_bf16_f32 v17, v17, s0
	ds_write_b16 v157, v16 offset:34816
	v_add_u32_e32 v16, s44, v168
	ds_write_b16 v157, v17
	v_mad_i64_i32 v[16:17], s[6:7], v16, s48, v[2:3]
	global_load_ushort v23, v[16:17], off
	s_nop 0
	global_load_ushort v16, v[16:17], off offset:1024
	v_mul_f32_e32 v17, 0x3fb8aa3b, v15
	v_mul_f32_e32 v15, 0xbfb8aa3b, v15
	v_exp_f32_e32 v15, v15
	s_waitcnt vmcnt(10)
	v_lshlrev_b32_e32 v21, 16, v33
	v_exp_f32_e32 v17, v17
	v_lshlrev_b32_e32 v19, 16, v28
	v_mul_f32_e32 v15, v15, v21
	v_cvt_pk_bf16_f32 v15, v15, s0
	v_mul_f32_e32 v19, 0x3db504f3, v19
	ds_write_b16 v159, v15 offset:34816
	v_mul_f32_e32 v17, v17, v19
	v_cvt_pk_bf16_f32 v17, v17, s0
	ds_write_b16 v159, v17
	s_waitcnt vmcnt(9)
	v_lshlrev_b32_e32 v15, 16, v29
	v_mul_f32_e32 v19, 0x3db504f3, v15
	v_mul_f32_e32 v15, 0x3fb8aa3b, v14
	v_mul_f32_e32 v14, 0xbfb8aa3b, v14
	v_exp_f32_e32 v21, v14
	v_add_u32_e32 v14, s44, v170
	s_waitcnt vmcnt(8)
	v_lshlrev_b32_e32 v17, 16, v20
	v_exp_f32_e32 v20, v15
	v_mad_i64_i32 v[14:15], s[6:7], v14, s48, v[2:3]
	global_load_ushort v27, v[14:15], off
	global_load_ushort v28, v[14:15], off offset:1024
	v_mul_f32_e32 v14, v20, v19
	v_cvt_pk_bf16_f32 v14, v14, s0
	ds_write_b16 v161, v14
	v_mul_f32_e32 v14, v21, v17
	v_cvt_pk_bf16_f32 v14, v14, s0
	ds_write_b16 v161, v14 offset:34816
	s_waitcnt vmcnt(9)
	v_lshlrev_b32_e32 v14, 16, v25
	v_mul_f32_e32 v19, 0x3db504f3, v14
	v_mul_f32_e32 v14, 0x3fb8aa3b, v13
	v_exp_f32_e32 v20, v14
	v_add_u32_e32 v14, s44, v172
	v_mad_i64_i32 v[14:15], s[6:7], v14, s48, v[2:3]
	global_load_ushort v21, v[14:15], off
	s_nop 0
	global_load_ushort v14, v[14:15], off offset:1024
	v_mul_f32_e32 v13, 0xbfb8aa3b, v13
	v_exp_f32_e32 v13, v13
	s_waitcnt vmcnt(10)
; #define LAS __attribute__((address_space(3)))
; __device__ __forceinline__ float bf2f(bf16_t v) { return __uint_as_float((unsigned)v << 16); }
; __device__ __forceinline__ unsigned f2bf(float f) { return (unsigned)__builtin_bit_cast(unsigned short, (__bf16)f); }
; __device__ __forceinline__ void gla_stage_vT(const bf16_t* proj, int tid, int t0, int h, LAS bf16_t* vT) {
;     ...
;     for (int q = 0; q < 8; ++q) { const int i = tid >> 2, c = (tid & 3) + 4 * q;
;         const u32x4 wv = *(const u32x4*)(proj + (size_t)(t0 + i) * NMAIN + C_GV + h * 256 + 8 * c);
;         LAS bf16_t* vp = vT + (8 * c) * GP + i;
;         vp[0 * GP] = (bf16_t)(wv.x & 0xffff); vp[1 * GP] = (bf16_t)(wv.x >> 16); vp[2 * GP] = (bf16_t)(wv.y & 0xffff); vp[3 * GP] = (bf16_t)(wv.y >> 16);
;         vp[4 * GP] = (bf16_t)(wv.z & 0xffff); vp[5 * GP] = (bf16_t)(wv.z >> 16); vp[6 * GP] = (bf16_t)(wv.w & 0xffff); vp[7 * GP] = (bf16_t)(wv.w >> 16); }
;     ...
; #pragma unroll
;           for (int r = 0; r < 32; ++r) { const int i = seg * 32 + r; const bf16_t* row = proj + (size_t)(t0 + i) * NMAIN + h * 128 + d;
;               const float qv = bf2f(row[C_GQ]), kv = bf2f(row[C_GK]);
;               qgs[i * GP + d] = (bf16_t)f2bf(qv * 0.08838834764831845f * __expf(bc[r])); kgs[i * GP + d] = (bf16_t)f2bf(kv * __expf(-bc[r])); } }
	v_lshlrev_b32_e32 v17, 16, v30
	v_mul_f32_e32 v15, v20, v19
	v_cvt_pk_bf16_f32 v15, v15, s0
	v_mul_f32_e32 v13, v13, v17
	v_mul_f32_e32 v17, 0x3fb8aa3b, v12
	v_mul_f32_e32 v12, 0xbfb8aa3b, v12
	v_exp_f32_e32 v12, v12
	v_exp_f32_e32 v17, v17
	ds_write_b16 v163, v15
	v_cvt_pk_bf16_f32 v13, v13, s0
	s_waitcnt vmcnt(8)
	v_lshlrev_b32_e32 v15, 16, v26
	ds_write_b16 v163, v13 offset:34816
	v_lshlrev_b32_e32 v13, 16, v24
	v_mul_f32_e32 v12, v12, v15
	v_mul_f32_e32 v13, 0x3db504f3, v13
	v_cvt_pk_bf16_f32 v12, v12, s0
	v_mul_f32_e32 v13, v17, v13
	ds_write_b16 v165, v12 offset:34816
	v_mul_f32_e32 v12, 0x3fb8aa3b, v11
	v_cvt_pk_bf16_f32 v13, v13, s0
	s_waitcnt vmcnt(6)
	v_lshlrev_b32_e32 v17, 16, v18
	v_exp_f32_e32 v18, v12
	v_add_u32_e32 v12, s44, v174
	ds_write_b16 v165, v13
	v_mad_i64_i32 v[12:13], s[6:7], v12, s48, v[2:3]
	global_load_ushort v19, v[12:13], off
	global_load_ushort v20, v[12:13], off offset:1024
	v_mul_f32_e32 v11, 0xbfb8aa3b, v11
	v_exp_f32_e32 v11, v11
	v_lshlrev_b32_e32 v15, 16, v22
	v_mul_f32_e32 v12, 0x3db504f3, v15
	v_mul_f32_e32 v12, v18, v12
	v_cvt_pk_bf16_f32 v12, v12, s0
	v_mul_f32_e32 v11, v11, v17
	ds_write_b16 v167, v12
	v_cvt_pk_bf16_f32 v11, v11, s0
	v_add_u32_e32 v12, s44, v176
	ds_write_b16 v167, v11 offset:34816
	v_mad_i64_i32 v[12:13], s[6:7], v12, s48, v[2:3]
	global_load_ushort v24, v[12:13], off
	global_load_ushort v25, v[12:13], off offset:1024
	s_waitcnt vmcnt(8)
	v_lshlrev_b32_e32 v15, 16, v16
	v_mul_f32_e32 v16, 0x3fb8aa3b, v10
	v_mul_f32_e32 v10, 0xbfb8aa3b, v10
	v_exp_f32_e32 v10, v10
	v_exp_f32_e32 v12, v16
	v_lshlrev_b32_e32 v11, 16, v23
	v_mul_f32_e32 v11, 0x3db504f3, v11
	v_mul_f32_e32 v10, v10, v15
	v_mul_f32_e32 v11, v12, v11
	v_cvt_pk_bf16_f32 v10, v10, s0
	v_cvt_pk_bf16_f32 v11, v11, s0
	ds_write_b16 v169, v10 offset:34816
	v_add_u32_e32 v10, s44, v178
	ds_write_b16 v169, v11
	v_mad_i64_i32 v[10:11], s[6:7], v10, s48, v[2:3]
	global_load_ushort v32, v[10:11], off
	global_load_ushort v33, v[10:11], off offset:1024
	s_waitcnt vmcnt(9)
	v_lshlrev_b32_e32 v10, 16, v27
	v_mul_f32_e32 v13, 0x3db504f3, v10
	v_mul_f32_e32 v10, 0x3fb8aa3b, v9
	v_exp_f32_e32 v15, v10
	v_add_u32_e32 v10, s44, v180
	v_mad_i64_i32 v[10:11], s[6:7], v10, s48, v[2:3]
	global_load_ushort v36, v[10:11], off
	global_load_ushort v37, v[10:11], off offset:1024
	v_mul_f32_e32 v9, 0xbfb8aa3b, v9
	v_exp_f32_e32 v9, v9
	s_waitcnt vmcnt(10)
	v_lshlrev_b32_e32 v12, 16, v28
	v_mul_f32_e32 v10, v15, v13
	v_cvt_pk_bf16_f32 v10, v10, s0
	v_mul_f32_e32 v9, v9, v12
	v_cvt_pk_bf16_f32 v9, v9, s0
	ds_write_b16 v171, v9 offset:34816
	ds_write_b16 v171, v10
	v_mul_f32_e32 v15, 0xbfb8aa3b, v8
	s_waitcnt vmcnt(9)
	v_lshlrev_b32_e32 v9, 16, v21
	v_mul_f32_e32 v13, 0x3db504f3, v9
	v_add_u32_e32 v9, s44, v182
	v_mad_i64_i32 v[2:3], s[6:7], v9, s48, v[2:3]
	global_load_ushort v40, v[2:3], off
	global_load_ushort v41, v[2:3], off offset:1024
	v_mul_f32_e32 v2, 0x3fb8aa3b, v8
	s_waitcnt vmcnt(10)
	v_lshlrev_b32_e32 v12, 16, v14
	v_exp_f32_e32 v14, v2
	v_add_u32_e32 v8, s44, v119
	v_mov_b64_e32 v[2:3], s[22:23]
	v_mad_i64_i32 v[2:3], s[6:7], v8, s48, v[2:3]
	v_lshl_add_u64 v[2:3], v[2:3], 0, s[8:9]
	v_lshl_add_u64 v[2:3], v[2:3], 0, v[110:111]
	global_load_dwordx4 v[8:11], v[2:3], off offset:2048
	v_exp_f32_e32 v15, v15
	v_mul_f32_e32 v13, v14, v13
	v_cvt_pk_bf16_f32 v13, v13, s0
	ds_write_b16 v173, v13
	v_mul_f32_e32 v12, v15, v12
	v_cvt_pk_bf16_f32 v12, v12, s0
	ds_write_b16 v173, v12 offset:34816
	global_load_dwordx4 v[12:15], v[2:3], off offset:2112
	s_waitcnt vmcnt(11)
	v_lshlrev_b32_e32 v16, 16, v19
	v_mul_f32_e32 v21, 0x3db504f3, v16
	v_mul_f32_e32 v16, 0x3fb8aa3b, v7
	v_exp_f32_e32 v22, v16
	global_load_dwordx4 v[16:19], v[2:3], off offset:2176
	v_mul_f32_e32 v7, 0xbfb8aa3b, v7
	v_exp_f32_e32 v7, v7
	v_mul_f32_e32 v21, v22, v21
	s_waitcnt vmcnt(11)
	v_lshlrev_b32_e32 v20, 16, v20
	v_cvt_pk_bf16_f32 v21, v21, s0
	ds_write_b16 v175, v21
	v_mul_f32_e32 v7, v7, v20
	global_load_dwordx4 v[20:23], v[2:3], off offset:2240
	v_cvt_pk_bf16_f32 v7, v7, s0
	ds_write_b16 v175, v7 offset:34816
	v_mul_f32_e32 v7, 0x3fb8aa3b, v6
	v_exp_f32_e32 v7, v7
	s_waitcnt vmcnt(11)
	v_lshlrev_b32_e32 v24, 16, v24
	v_mul_f32_e32 v24, 0x3db504f3, v24
	s_waitcnt vmcnt(10)
	v_lshlrev_b32_e32 v28, 16, v25
	v_mul_f32_e32 v7, v7, v24
	global_load_dwordx4 v[24:27], v[2:3], off offset:2304
	v_mul_f32_e32 v6, 0xbfb8aa3b, v6
	v_exp_f32_e32 v6, v6
	v_cvt_pk_bf16_f32 v7, v7, s0
	ds_write_b16 v177, v7
	v_mul_f32_e32 v6, v6, v28
	global_load_dwordx4 v[28:31], v[2:3], off offset:2368
	v_cvt_pk_bf16_f32 v6, v6, s0
	ds_write_b16 v177, v6 offset:34816
	s_waitcnt vmcnt(11)
; #define LAS __attribute__((address_space(3)))
; #define X make_ctx(lds_raw)
; __device__ __forceinline__ void gla_stage_vT(const bf16_t* proj, int tid, int t0, int h, LAS bf16_t* vT) {
;     ...
;     for (int q = 0; q < 8; ++q) { const int i = tid >> 2, c = (tid & 3) + 4 * q;
;         const u32x4 wv = *(const u32x4*)(proj + (size_t)(t0 + i) * NMAIN + C_GV + h * 256 + 8 * c);
;         LAS bf16_t* vp = vT + (8 * c) * GP + i;
;         vp[0 * GP] = (bf16_t)(wv.x & 0xffff); vp[1 * GP] = (bf16_t)(wv.x >> 16); vp[2 * GP] = (bf16_t)(wv.y & 0xffff); vp[3 * GP] = (bf16_t)(wv.y >> 16);
;         vp[4 * GP] = (bf16_t)(wv.z & 0xffff); vp[5 * GP] = (bf16_t)(wv.z >> 16); vp[6 * GP] = (bf16_t)(wv.w & 0xffff); vp[7 * GP] = (bf16_t)(wv.w >> 16); }
;     ...
;         gla_stage_vT(proj, X.tid, t0, h, vT);
;         __syncthreads();
;         bf16x8 afr[4];
; #pragma unroll
;         for (int ks = 0; ks < 4; ++ks) afr[ks] = *(const LAS bf16x8*)(qgs + (i0 + fr) * GP + 32 * ks + 8 * fq);
;         f32x4 acc[16];
; #pragma unroll
;         for (int nt = 0; nt < 16; ++nt) acc[nt] = (f32x4){0.f, 0.f, 0.f, 0.f};
;         for (int jt = 0; jt <= (w | 1); ++jt) {
	v_lshlrev_b32_e32 v7, 16, v32
	s_waitcnt vmcnt(10)
	v_lshlrev_b32_e32 v38, 16, v33
	global_load_dwordx4 v[32:35], v[2:3], off offset:2432
	v_mul_f32_e32 v6, 0x3fb8aa3b, v5
	v_mul_f32_e32 v5, 0xbfb8aa3b, v5
	v_exp_f32_e32 v6, v6
	v_exp_f32_e32 v5, v5
	v_mul_f32_e32 v7, 0x3db504f3, v7
	v_mul_f32_e32 v6, v6, v7
	v_mul_f32_e32 v5, v5, v38
	v_cvt_pk_bf16_f32 v6, v6, s0
	v_cvt_pk_bf16_f32 v5, v5, s0
	ds_write_b16 v179, v6
	ds_write_b16 v179, v5 offset:34816
	s_waitcnt vmcnt(10)
	v_lshlrev_b32_e32 v5, 16, v36
	s_waitcnt vmcnt(9)
	v_lshlrev_b32_e32 v6, 16, v37
	global_load_dwordx4 v[36:39], v[2:3], off offset:2496
	v_mul_f32_e32 v7, 0x3fb8aa3b, v4
	v_exp_f32_e32 v2, v7
	v_mul_f32_e32 v4, 0xbfb8aa3b, v4
	v_exp_f32_e32 v4, v4
	v_mul_f32_e32 v3, 0x3db504f3, v5
	v_mul_f32_e32 v2, v2, v3
	v_cvt_pk_bf16_f32 v2, v2, s0
	ds_write_b16 v181, v2
	v_mul_f32_e32 v2, v4, v6
	v_mul_f32_e32 v4, 0x3fb8aa3b, v0
	v_mul_f32_e32 v0, 0xbfb8aa3b, v0
	v_exp_f32_e32 v4, v4
	v_exp_f32_e32 v0, v0
	v_cvt_pk_bf16_f32 v2, v2, s0
	ds_write_b16 v181, v2 offset:34816
	s_waitcnt vmcnt(9)
	v_lshlrev_b32_e32 v2, 16, v40
	s_waitcnt vmcnt(8)
	v_lshlrev_b32_e32 v3, 16, v41
	v_mul_f32_e32 v2, 0x3db504f3, v2
	v_mul_f32_e32 v2, v4, v2
	v_mul_f32_e32 v0, v0, v3
	v_cvt_pk_bf16_f32 v2, v2, s0
	v_cvt_pk_bf16_f32 v0, v0, s0
	ds_write_b16 v183, v2
	ds_write_b16 v183, v0 offset:34816
	s_waitcnt vmcnt(7)
	ds_write_b16 v203, v8
	ds_write_b16_d16_hi v203, v8 offset:272
	ds_write_b16 v203, v9 offset:544
	ds_write_b16_d16_hi v203, v9 offset:816
	ds_write_b16 v203, v10 offset:1088
	ds_write_b16_d16_hi v203, v10 offset:1360
	ds_write_b16 v203, v11 offset:1632
	ds_write_b16_d16_hi v203, v11 offset:1904
	s_waitcnt vmcnt(6)
	ds_write_b16 v203, v12 offset:8704
	ds_write_b16_d16_hi v203, v12 offset:8976
	ds_write_b16 v203, v13 offset:9248
	ds_write_b16_d16_hi v203, v13 offset:9520
	ds_write_b16 v203, v14 offset:9792
	ds_write_b16_d16_hi v203, v14 offset:10064
	ds_write_b16 v203, v15 offset:10336
	ds_write_b16_d16_hi v203, v15 offset:10608
	s_waitcnt vmcnt(5)
	ds_write_b16 v203, v16 offset:17408
	ds_write_b16_d16_hi v203, v16 offset:17680
	ds_write_b16 v203, v17 offset:17952
	ds_write_b16_d16_hi v203, v17 offset:18224
	ds_write_b16 v203, v18 offset:18496
	ds_write_b16_d16_hi v203, v18 offset:18768
	ds_write_b16 v203, v19 offset:19040
	ds_write_b16_d16_hi v203, v19 offset:19312
	s_waitcnt vmcnt(4)
	ds_write_b16 v203, v20 offset:26112
	ds_write_b16_d16_hi v203, v20 offset:26384
	ds_write_b16 v203, v21 offset:26656
	ds_write_b16_d16_hi v203, v21 offset:26928
	ds_write_b16 v203, v22 offset:27200
	ds_write_b16_d16_hi v203, v22 offset:27472
	ds_write_b16 v203, v23 offset:27744
	ds_write_b16_d16_hi v203, v23 offset:28016
	s_waitcnt vmcnt(3)
	ds_write_b16 v203, v24 offset:34816
	ds_write_b16_d16_hi v203, v24 offset:35088
	ds_write_b16 v203, v25 offset:35360
	ds_write_b16_d16_hi v203, v25 offset:35632
	ds_write_b16 v203, v26 offset:35904
	ds_write_b16_d16_hi v203, v26 offset:36176
	ds_write_b16 v203, v27 offset:36448
	ds_write_b16_d16_hi v203, v27 offset:36720
	s_waitcnt vmcnt(2)
	ds_write_b16 v203, v28 offset:43520
	ds_write_b16_d16_hi v203, v28 offset:43792
	ds_write_b16 v203, v29 offset:44064
	ds_write_b16_d16_hi v203, v29 offset:44336
	ds_write_b16 v203, v30 offset:44608
	ds_write_b16_d16_hi v203, v30 offset:44880
	ds_write_b16 v203, v31 offset:45152
	ds_write_b16_d16_hi v203, v31 offset:45424
	s_waitcnt vmcnt(1)
	ds_write_b16 v203, v32 offset:52224
	ds_write_b16_d16_hi v203, v32 offset:52496
	ds_write_b16 v203, v33 offset:52768
	ds_write_b16_d16_hi v203, v33 offset:53040
	ds_write_b16 v203, v34 offset:53312
	ds_write_b16_d16_hi v203, v34 offset:53584
	ds_write_b16 v203, v35 offset:53856
	ds_write_b16_d16_hi v203, v35 offset:54128
	s_waitcnt vmcnt(0)
	ds_write_b16 v203, v36 offset:60928
	ds_write_b16_d16_hi v203, v36 offset:61200
	ds_write_b16 v203, v37 offset:61472
	ds_write_b16_d16_hi v203, v37 offset:61744
	ds_write_b16 v203, v38 offset:62016
	ds_write_b16_d16_hi v203, v38 offset:62288
	ds_write_b16 v203, v39 offset:62560
	ds_write_b16_d16_hi v203, v39 offset:62832
	s_waitcnt lgkmcnt(0)
	s_barrier
	ds_read_b128 v[80:83], v204
	ds_read_b128 v[76:79], v204 offset:64
	ds_read_b128 v[72:75], v204 offset:128
	ds_read_b128 v[68:71], v204 offset:192
	s_cbranch_vccnz .LBB0_483
	s_mov_b32 s1, 0
	v_mov_b32_e32 v0, v200
	v_mov_b32_e32 v6, v199
	v_mov_b32_e32 v7, v86
	s_branch .LBB0_481
